# mixers: LDS fragment reads of the 128x128x128 products (retention chain/output, SGU) software-pipelined into a rotating pool of dead VGPR quads with counted lgkmcnt
# speedup vs baseline: 1.0019x; 1.0014x over previous
; template <bool A_TR, bool B_TR>
; __device__ __forceinline__ void mm128(f32x4 (&acc)[8], ldsp TA, ldsp TB, int w, int lane) {
;     const ldsp ab = A_TR ? tr_base(TA, lane) + 32u * w : row_base(TA, lane) + 16u * TP * w;
;     const ldsp bb = B_TR ? tr_base(TB, lane) : row_base(TB, lane);
;     if (MM_SETPRIO) __builtin_amdgcn_s_setprio(1);
;     ...
;     bf16x8 a[4];
; #pragma unroll
;     for (int ks = 0; ks < 4; ++ks) a[ks] = A_TR ? frag_tr(ab, 0, ks) : frag_row(ab, 0, ks);
;     mm_pipe<MM_G, 0, 4, 0, 8>(acc, [&](int c, int ks) { return B_TR ? frag_tr(bb, c, ks) : frag_row(bb, c, ks); }, [&](int ks) { return a[ks]; });
;     ...
; #pragma unroll
;     for (int ks = 0; ks < 4; ++ks) {
;         const bf16x8 a = A_TR ? frag_tr(ab, 0, ks) : frag_row(ab, 0, ks);
; #pragma unroll
;         for (int c = 0; c < 8; ++c) {
;             const bf16x8 b = B_TR ? frag_tr(bb, c, ks) : frag_row(bb, c, ks);
;             acc[c] = __builtin_amdgcn_mfma_f32_16x16x32_bf16(b, a, acc[c], 0, 0, 0);
;         }
;     }
.LBB0_307:
	s_ashr_i32 s11, s10, 31
	s_lshl_b64 s[18:19], s[10:11], 15
	v_lshl_add_u64 v[146:147], v[108:109], 0, s[18:19]
	v_cvt_pk_bf16_f32 v148, v66, v67
	v_cvt_pk_bf16_f32 v149, v68, v69
	global_store_dwordx2 v[146:147], v[148:149], off
	v_cvt_pk_bf16_f32 v148, v70, v71
	v_cvt_pk_bf16_f32 v149, v72, v73
	global_store_dwordx2 v[146:147], v[148:149], off offset:512
	v_cvt_pk_bf16_f32 v148, v74, v75
	v_cvt_pk_bf16_f32 v149, v76, v77
	global_store_dwordx2 v[146:147], v[148:149], off offset:1024
	v_cvt_pk_bf16_f32 v148, v78, v79
	v_cvt_pk_bf16_f32 v149, v80, v81
	global_store_dwordx2 v[146:147], v[148:149], off offset:1536
	v_cvt_pk_bf16_f32 v148, v82, v83
	v_cvt_pk_bf16_f32 v149, v84, v85
	global_store_dwordx2 v[146:147], v[148:149], off offset:2048
	v_cvt_pk_bf16_f32 v148, v86, v87
	v_cvt_pk_bf16_f32 v149, v88, v89
	global_store_dwordx2 v[146:147], v[148:149], off offset:2560
	v_cvt_pk_bf16_f32 v148, v90, v91
	v_cvt_pk_bf16_f32 v149, v92, v93
	global_store_dwordx2 v[146:147], v[148:149], off offset:3072
	v_cvt_pk_bf16_f32 v148, v94, v95
	v_cvt_pk_bf16_f32 v149, v96, v97
	v_pk_mul_f32 v[68:69], v[122:123], v[68:69]
	v_pk_mul_f32 v[66:67], v[112:113], v[66:67]
	v_pk_mul_f32 v[72:73], v[122:123], v[72:73]
	v_pk_mul_f32 v[70:71], v[112:113], v[70:71]
	v_pk_mul_f32 v[76:77], v[122:123], v[76:77]
	v_pk_mul_f32 v[74:75], v[112:113], v[74:75]
	v_pk_mul_f32 v[80:81], v[122:123], v[80:81]
	v_pk_mul_f32 v[78:79], v[112:113], v[78:79]
	v_pk_mul_f32 v[84:85], v[122:123], v[84:85]
	v_pk_mul_f32 v[82:83], v[112:113], v[82:83]
	v_pk_mul_f32 v[88:89], v[122:123], v[88:89]
	v_pk_mul_f32 v[86:87], v[112:113], v[86:87]
	v_pk_mul_f32 v[92:93], v[122:123], v[92:93]
	v_pk_mul_f32 v[90:91], v[112:113], v[90:91]
	v_pk_mul_f32 v[96:97], v[122:123], v[96:97]
	v_pk_mul_f32 v[94:95], v[112:113], v[94:95]
	global_store_dwordx2 v[146:147], v[148:149], off offset:3584
	s_setprio 1
	v_add_u32_e32 v158, s13, v136
	ds_read_b64_tr_b16 v[178:179], v158
	ds_read_b64_tr_b16 v[180:181], v158 offset:1088
	ds_read_b64_tr_b16 v[184:185], v136 offset:35904
	ds_read_b64_tr_b16 v[182:183], v136 offset:34816
	ds_read_b64_tr_b16 v[186:187], v136 offset:34880
	ds_read_b64_tr_b16 v[188:189], v136 offset:35968
	ds_read_b64_tr_b16 v[190:191], v136 offset:34912
	ds_read_b64_tr_b16 v[192:193], v136 offset:36000
	ds_read_b64_tr_b16 v[194:195], v136 offset:34944
	ds_read_b64_tr_b16 v[196:197], v136 offset:36032
	ds_read_b64_tr_b16 v[198:199], v136 offset:34976
	ds_read_b64_tr_b16 v[200:201], v136 offset:36064
	ds_read_b64_tr_b16 v[202:203], v136 offset:35008
	ds_read_b64_tr_b16 v[204:205], v136 offset:36096
	ds_read_b64_tr_b16 v[206:207], v136 offset:34848
	ds_read_b64_tr_b16 v[208:209], v136 offset:35936
	ds_read_b64_tr_b16 v[212:213], v136 offset:35040
	ds_read_b64_tr_b16 v[214:215], v136 offset:36128
	s_waitcnt lgkmcnt(14)
	v_mfma_f32_16x16x32_bf16 v[66:69], v[182:185], v[178:181], v[66:69]
	ds_read_b64_tr_b16 v[216:217], v158 offset:8704
	ds_read_b64_tr_b16 v[218:219], v158 offset:9792
	s_waitcnt lgkmcnt(14)
	v_mfma_f32_16x16x32_bf16 v[74:77], v[186:189], v[178:181], v[74:77]
	ds_read_b64_tr_b16 v[220:221], v136 offset:43520
	ds_read_b64_tr_b16 v[222:223], v136 offset:44608
	s_waitcnt lgkmcnt(14)
	v_mfma_f32_16x16x32_bf16 v[78:81], v[190:193], v[178:181], v[78:81]
	ds_read_b64_tr_b16 v[236:237], v136 offset:43552
	ds_read_b64_tr_b16 v[238:239], v136 offset:44640
	s_waitcnt lgkmcnt(14)
	v_mfma_f32_16x16x32_bf16 v[82:85], v[194:197], v[178:181], v[82:85]
	ds_read_b64_tr_b16 v[182:183], v136 offset:43584
	ds_read_b64_tr_b16 v[184:185], v136 offset:44672
	s_waitcnt lgkmcnt(14)
	v_mfma_f32_16x16x32_bf16 v[86:89], v[198:201], v[178:181], v[86:89]
	ds_read_b64_tr_b16 v[186:187], v136 offset:43616
	ds_read_b64_tr_b16 v[188:189], v136 offset:44704
	s_waitcnt lgkmcnt(14)
	v_mfma_f32_16x16x32_bf16 v[90:93], v[202:205], v[178:181], v[90:93]
	ds_read_b64_tr_b16 v[190:191], v136 offset:43648
	ds_read_b64_tr_b16 v[192:193], v136 offset:44736
	s_waitcnt lgkmcnt(14)
	v_mfma_f32_16x16x32_bf16 v[70:73], v[206:209], v[178:181], v[70:73]
	ds_read_b64_tr_b16 v[194:195], v136 offset:43680
	ds_read_b64_tr_b16 v[196:197], v136 offset:44768
	s_waitcnt lgkmcnt(14)
	v_mfma_f32_16x16x32_bf16 v[94:97], v[212:215], v[178:181], v[94:97]
	ds_read_b64_tr_b16 v[198:199], v136 offset:43712
	ds_read_b64_tr_b16 v[200:201], v136 offset:44800
	ds_read_b64_tr_b16 v[202:203], v136 offset:43744
	ds_read_b64_tr_b16 v[204:205], v136 offset:44832
	s_waitcnt lgkmcnt(14)
	v_mfma_f32_16x16x32_bf16 v[66:69], v[220:223], v[216:219], v[66:69]
	ds_read_b64_tr_b16 v[206:207], v158 offset:17408
	ds_read_b64_tr_b16 v[208:209], v158 offset:18496
	s_waitcnt lgkmcnt(14)
	v_mfma_f32_16x16x32_bf16 v[70:73], v[236:239], v[216:219], v[70:73]
	ds_read_b64_tr_b16 v[212:213], v136 offset:52224
	ds_read_b64_tr_b16 v[214:215], v136 offset:53312
	s_waitcnt lgkmcnt(14)
	v_mfma_f32_16x16x32_bf16 v[74:77], v[182:185], v[216:219], v[74:77]
	ds_read_b64_tr_b16 v[178:179], v136 offset:52256
	ds_read_b64_tr_b16 v[180:181], v136 offset:53344
	s_waitcnt lgkmcnt(14)
	v_mfma_f32_16x16x32_bf16 v[78:81], v[186:189], v[216:219], v[78:81]
	ds_read_b64_tr_b16 v[220:221], v136 offset:52288
	ds_read_b64_tr_b16 v[222:223], v136 offset:53376
	s_waitcnt lgkmcnt(14)
	v_mfma_f32_16x16x32_bf16 v[82:85], v[190:193], v[216:219], v[82:85]
	ds_read_b64_tr_b16 v[236:237], v136 offset:52320
	ds_read_b64_tr_b16 v[238:239], v136 offset:53408
	s_waitcnt lgkmcnt(14)
	v_mfma_f32_16x16x32_bf16 v[86:89], v[194:197], v[216:219], v[86:89]
	ds_read_b64_tr_b16 v[182:183], v136 offset:52352
	ds_read_b64_tr_b16 v[184:185], v136 offset:53440
	s_waitcnt lgkmcnt(14)
; __device__ __forceinline__ unsigned cvt_pk_bf16(float lo, float hi) { const f32x2c_t v = {lo, hi}; return __builtin_bit_cast(unsigned, __builtin_convertvector(v, bf16x2c_t)); }
; #define LAS __attribute__((address_space(3)))
; __device__ __forceinline__ float bf_lo(unsigned w) { return __uint_as_float(w << 16); }
; __device__ __forceinline__ float bf_hi(unsigned w) { return __uint_as_float(w & 0xffff0000u); }
; template <bool A_TR, bool B_TR>
; __device__ __forceinline__ void mm128(f32x4 (&acc)[8], ldsp TA, ldsp TB, int w, int lane) {
;     ...
;     mm_pipe<MM_G, 0, 4, 0, 8>(acc, [&](int c, int ks) { return B_TR ? frag_tr(bb, c, ks) : frag_row(bb, c, ks); }, [&](int ks) { return a[ks]; });
;     ...
; #pragma unroll
;     for (int ks = 0; ks < 4; ++ks) {
;         const bf16x8 a = A_TR ? frag_tr(ab, 0, ks) : frag_row(ab, 0, ks);
; #pragma unroll
;         for (int c = 0; c < 8; ++c) {
;             const bf16x8 b = B_TR ? frag_tr(bb, c, ks) : frag_row(bb, c, ks);
;             acc[c] = __builtin_amdgcn_mfma_f32_16x16x32_bf16(b, a, acc[c], 0, 0, 0);
;         }
;     }
; __device__ __forceinline__ void tile_put(ldsp T, const TileRegs& t, int tid) {
; #pragma unroll
;     for (int i = 0; i < 4; ++i) { const int ck = tid + 512 * i, r = ck >> 4, ch = ck & 15; *(LAS v4u*)(T + offb(r, ch)) = t.v[i]; }
; }
; __device__ __forceinline__ void tile_put_v(ldsp T, const TileRegs& t, int tid) {
; #pragma unroll
;     for (int i = 0; i < 4; ++i) { const int ck = tid + 512 * i, r = ck >> 4, ch = ck & 15; *(LAS v4u*)(T + offb_v(r, ch)) = t.v[i]; }
; }
; __device__ __forceinline__ void tile_put_scaled(ldsp T, const TileRegs& t, float l2, float a0, float a1, int tid) {
; #pragma unroll
;     for (int i = 0; i < 4; ++i) { const int ck = tid + 512 * i, r = ck >> 4, ch = ck & 15;
;         const float sc = __builtin_amdgcn_exp2f(l2 * (a0 + a1 * (float)r));
;         v4u o;
; #pragma unroll
;         for (int k = 0; k < 4; ++k) o[k] = cvt_pk_bf16(bf_lo(t.v[i][k]) * sc, bf_hi(t.v[i][k]) * sc);
;         *(LAS v4u*)(T + offb(r, ch)) = o; }
; }
	v_mfma_f32_16x16x32_bf16 v[90:93], v[198:201], v[216:219], v[90:93]
	ds_read_b64_tr_b16 v[186:187], v136 offset:52384
	ds_read_b64_tr_b16 v[188:189], v136 offset:53472
	s_waitcnt lgkmcnt(14)
	v_mfma_f32_16x16x32_bf16 v[94:97], v[202:205], v[216:219], v[94:97]
	ds_read_b64_tr_b16 v[190:191], v136 offset:52416
	ds_read_b64_tr_b16 v[192:193], v136 offset:53504
	ds_read_b64_tr_b16 v[194:195], v136 offset:52448
	ds_read_b64_tr_b16 v[196:197], v136 offset:53536
	s_waitcnt lgkmcnt(14)
	v_mfma_f32_16x16x32_bf16 v[66:69], v[212:215], v[206:209], v[66:69]
	ds_read_b64_tr_b16 v[198:199], v158 offset:26112
	ds_read_b64_tr_b16 v[200:201], v158 offset:27200
	s_waitcnt lgkmcnt(14)
	v_mfma_f32_16x16x32_bf16 v[70:73], v[178:181], v[206:209], v[70:73]
	ds_read_b64_tr_b16 v[202:203], v136 offset:60928
	ds_read_b64_tr_b16 v[204:205], v136 offset:62016
	s_waitcnt lgkmcnt(14)
	v_mfma_f32_16x16x32_bf16 v[74:77], v[220:223], v[206:209], v[74:77]
	ds_read_b64_tr_b16 v[216:217], v136 offset:60960
	ds_read_b64_tr_b16 v[218:219], v136 offset:62048
	s_waitcnt lgkmcnt(14)
	v_mfma_f32_16x16x32_bf16 v[78:81], v[236:239], v[206:209], v[78:81]
	ds_read_b64_tr_b16 v[212:213], v136 offset:60992
	ds_read_b64_tr_b16 v[214:215], v136 offset:62080
	s_waitcnt lgkmcnt(14)
	v_mfma_f32_16x16x32_bf16 v[82:85], v[182:185], v[206:209], v[82:85]
	ds_read_b64_tr_b16 v[178:179], v136 offset:61024
	ds_read_b64_tr_b16 v[180:181], v136 offset:62112
	s_waitcnt lgkmcnt(14)
	v_mfma_f32_16x16x32_bf16 v[86:89], v[186:189], v[206:209], v[86:89]
	ds_read_b64_tr_b16 v[220:221], v136 offset:61056
	ds_read_b64_tr_b16 v[222:223], v136 offset:62144
	s_waitcnt lgkmcnt(14)
	v_mfma_f32_16x16x32_bf16 v[90:93], v[190:193], v[206:209], v[90:93]
	ds_read_b64_tr_b16 v[236:237], v136 offset:61088
	ds_read_b64_tr_b16 v[238:239], v136 offset:62176
	s_waitcnt lgkmcnt(14)
	v_mfma_f32_16x16x32_bf16 v[94:97], v[194:197], v[206:209], v[94:97]
	ds_read_b64_tr_b16 v[182:183], v136 offset:61120
	ds_read_b64_tr_b16 v[184:185], v136 offset:62208
	ds_read_b64_tr_b16 v[186:187], v136 offset:61152
	ds_read_b64_tr_b16 v[188:189], v136 offset:62240
	s_waitcnt lgkmcnt(14)
	v_mfma_f32_16x16x32_bf16 v[66:69], v[202:205], v[198:201], v[66:69]
	s_waitcnt lgkmcnt(12)
	v_mfma_f32_16x16x32_bf16 v[70:73], v[216:219], v[198:201], v[70:73]
	s_waitcnt lgkmcnt(10)
	v_mfma_f32_16x16x32_bf16 v[74:77], v[212:215], v[198:201], v[74:77]
	s_waitcnt lgkmcnt(8)
	v_mfma_f32_16x16x32_bf16 v[78:81], v[178:181], v[198:201], v[78:81]
	s_waitcnt lgkmcnt(6)
	v_mfma_f32_16x16x32_bf16 v[82:85], v[220:223], v[198:201], v[82:85]
	s_waitcnt lgkmcnt(4)
	v_mfma_f32_16x16x32_bf16 v[86:89], v[236:239], v[198:201], v[86:89]
	s_waitcnt lgkmcnt(2)
	v_mfma_f32_16x16x32_bf16 v[90:93], v[182:185], v[198:201], v[90:93]
	s_waitcnt lgkmcnt(0)
	v_mfma_f32_16x16x32_bf16 v[94:97], v[186:189], v[198:201], v[94:97]
	s_nop 7
	s_setprio 0
	v_add_u32_e32 v146, v137, v129
	s_waitcnt vmcnt(12)
	ds_write_b128 v146, v[22:25]
	v_add_u32_e32 v146, v137, v130
	ds_write_b128 v146, v[30:33]
	v_add_u32_e32 v146, v137, v131
	ds_write_b128 v146, v[38:41]
	v_add_u32_e32 v146, v137, v132
	ds_write_b128 v146, v[46:49]
	s_waitcnt vmcnt(11)
	v_lshlrev_b32_e32 v146, 16, v50
	v_and_b32_e32 v147, 0xffff0000, v50
	v_lshlrev_b32_e32 v148, 16, v51
	v_and_b32_e32 v149, 0xffff0000, v51
	v_pk_mul_f32 v[146:147], v[114:115], v[146:147]
	v_pk_mul_f32 v[148:149], v[114:115], v[148:149]
	v_cvt_pk_bf16_f32 v146, v146, v147
	v_cvt_pk_bf16_f32 v147, v148, v149
	v_lshlrev_b32_e32 v148, 16, v52
	v_and_b32_e32 v149, 0xffff0000, v52
	v_lshlrev_b32_e32 v150, 16, v53
	v_and_b32_e32 v151, 0xffff0000, v53
	v_pk_mul_f32 v[148:149], v[114:115], v[148:149]
	v_pk_mul_f32 v[150:151], v[114:115], v[150:151]
	v_cvt_pk_bf16_f32 v148, v148, v149
	v_cvt_pk_bf16_f32 v149, v150, v151
	v_add_u32_e32 v150, v138, v129
	ds_write_b128 v150, v[146:149]
	s_waitcnt vmcnt(10)
	v_lshlrev_b32_e32 v146, 16, v54
	v_and_b32_e32 v147, 0xffff0000, v54
	v_lshlrev_b32_e32 v148, 16, v55
	v_and_b32_e32 v149, 0xffff0000, v55
	v_pk_mul_f32 v[146:147], v[116:117], v[146:147]
	v_pk_mul_f32 v[148:149], v[116:117], v[148:149]
	v_cvt_pk_bf16_f32 v146, v146, v147
	v_cvt_pk_bf16_f32 v147, v148, v149
	v_lshlrev_b32_e32 v148, 16, v56
	v_and_b32_e32 v149, 0xffff0000, v56
	v_lshlrev_b32_e32 v150, 16, v57
	v_and_b32_e32 v151, 0xffff0000, v57
	v_pk_mul_f32 v[148:149], v[116:117], v[148:149]
	v_pk_mul_f32 v[150:151], v[116:117], v[150:151]
	v_cvt_pk_bf16_f32 v148, v148, v149
	v_cvt_pk_bf16_f32 v149, v150, v151
	v_add_u32_e32 v150, v138, v130
	ds_write_b128 v150, v[146:149]
	s_waitcnt vmcnt(9)
	v_lshlrev_b32_e32 v146, 16, v58
	v_and_b32_e32 v147, 0xffff0000, v58
	v_lshlrev_b32_e32 v148, 16, v59
	v_and_b32_e32 v149, 0xffff0000, v59
	v_pk_mul_f32 v[146:147], v[118:119], v[146:147]
	v_pk_mul_f32 v[148:149], v[118:119], v[148:149]
	v_cvt_pk_bf16_f32 v146, v146, v147
	v_cvt_pk_bf16_f32 v147, v148, v149
	v_lshlrev_b32_e32 v148, 16, v60
	v_and_b32_e32 v149, 0xffff0000, v60
	v_lshlrev_b32_e32 v150, 16, v61
	v_and_b32_e32 v151, 0xffff0000, v61
	v_pk_mul_f32 v[148:149], v[118:119], v[148:149]
	v_pk_mul_f32 v[150:151], v[118:119], v[150:151]
	v_cvt_pk_bf16_f32 v148, v148, v149
	v_cvt_pk_bf16_f32 v149, v150, v151
	v_add_u32_e32 v150, v138, v131
	ds_write_b128 v150, v[146:149]
	s_waitcnt vmcnt(8)
	v_lshlrev_b32_e32 v146, 16, v62
	v_and_b32_e32 v147, 0xffff0000, v62
	v_lshlrev_b32_e32 v148, 16, v63
	v_and_b32_e32 v149, 0xffff0000, v63
	v_pk_mul_f32 v[146:147], v[120:121], v[146:147]
	v_pk_mul_f32 v[148:149], v[120:121], v[148:149]
	v_cvt_pk_bf16_f32 v146, v146, v147
	v_cvt_pk_bf16_f32 v147, v148, v149
	v_lshlrev_b32_e32 v148, 16, v64
	v_and_b32_e32 v149, 0xffff0000, v64
	v_lshlrev_b32_e32 v150, 16, v65
	v_and_b32_e32 v151, 0xffff0000, v65
	v_pk_mul_f32 v[148:149], v[120:121], v[148:149]
	v_pk_mul_f32 v[150:151], v[120:121], v[150:151]
	v_cvt_pk_bf16_f32 v148, v148, v149
	v_cvt_pk_bf16_f32 v149, v150, v151
	v_add_u32_e32 v150, v138, v132
	s_cmp_gt_u32 s4, 28
	ds_write_b128 v150, v[146:149]
	s_waitcnt lgkmcnt(0)
	s_barrier
	s_cbranch_scc1 .LBB0_309
	s_mul_i32 s11, s5, 0x360000
	s_add_i32 s18, s11, s12
	s_ashr_i32 s19, s18, 31
	s_lshl_b64 s[18:19], s[18:19], 1
	s_add_u32 s18, s0, s18
	s_addc_u32 s19, s1, s19
	v_lshl_add_u64 v[50:51], s[18:19], 0, v[16:17]
	v_lshl_add_u64 v[38:39], v[50:51], 0, s[30:31]
	v_lshl_add_u64 v[58:59], v[50:51], 0, s[48:49]
	v_lshl_add_u64 v[22:23], v[38:39], 0, v[100:101]
	v_lshl_add_u64 v[30:31], v[38:39], 0, v[102:103]
	v_lshl_add_u64 v[40:41], v[38:39], 0, v[104:105]
	v_lshl_add_u64 v[46:47], v[38:39], 0, v[106:107]
	v_lshl_add_u64 v[50:51], v[58:59], 0, v[100:101]
	v_lshl_add_u64 v[54:55], v[58:59], 0, v[102:103]
	v_lshl_add_u64 v[60:61], v[58:59], 0, v[104:105]
	v_lshl_add_u64 v[62:63], v[58:59], 0, v[106:107]
	global_load_dwordx4 v[22:25], v[22:23], off
	s_nop 0
	global_load_dwordx4 v[30:33], v[30:31], off
	s_nop 0
	global_load_dwordx4 v[38:41], v[40:41], off
	s_nop 0
	global_load_dwordx4 v[46:49], v[46:47], off
	s_nop 0
	global_load_dwordx4 v[50:53], v[50:51], off
	s_nop 0
	global_load_dwordx4 v[54:57], v[54:55], off
	s_nop 0
	global_load_dwordx4 v[58:61], v[60:61], off
	s_nop 0
	global_load_dwordx4 v[62:65], v[62:63], off
.LBB0_309:
	s_add_i32 s18, s5, s10
	s_ashr_i32 s19, s18, 31
	s_lshl_b64 s[18:19], s[18:19], 15
	v_lshl_add_u64 v[146:147], v[108:109], 0, s[18:19]
	v_cvt_pk_bf16_f32 v148, v66, v67
	v_cvt_pk_bf16_f32 v149, v68, v69
	global_store_dwordx2 v[146:147], v[148:149], off
	v_cvt_pk_bf16_f32 v148, v70, v71
	v_cvt_pk_bf16_f32 v149, v72, v73
	global_store_dwordx2 v[146:147], v[148:149], off offset:512
	v_cvt_pk_bf16_f32 v148, v74, v75
	v_cvt_pk_bf16_f32 v149, v76, v77
	global_store_dwordx2 v[146:147], v[148:149], off offset:1024
	v_cvt_pk_bf16_f32 v148, v78, v79
	v_cvt_pk_bf16_f32 v149, v80, v81
	global_store_dwordx2 v[146:147], v[148:149], off offset:1536
	v_cvt_pk_bf16_f32 v148, v82, v83
	v_cvt_pk_bf16_f32 v149, v84, v85
	global_store_dwordx2 v[146:147], v[148:149], off offset:2048
	v_cvt_pk_bf16_f32 v148, v86, v87
	v_cvt_pk_bf16_f32 v149, v88, v89
	global_store_dwordx2 v[146:147], v[148:149], off offset:2560
	v_cvt_pk_bf16_f32 v148, v90, v91
	v_cvt_pk_bf16_f32 v149, v92, v93
	global_store_dwordx2 v[146:147], v[148:149], off offset:3072
	v_cvt_pk_bf16_f32 v148, v94, v95
	v_cvt_pk_bf16_f32 v149, v96, v97
	s_andn2_b64 vcc, exec, s[24:25]
	global_store_dwordx2 v[146:147], v[148:149], off offset:3584
	s_cbranch_vccnz .LBB0_304
	v_pk_mul_f32 v[68:69], v[122:123], v[68:69]
	v_pk_mul_f32 v[66:67], v[112:113], v[66:67]
	v_pk_mul_f32 v[72:73], v[122:123], v[72:73]
	v_pk_mul_f32 v[70:71], v[112:113], v[70:71]
	v_pk_mul_f32 v[76:77], v[122:123], v[76:77]
	v_pk_mul_f32 v[74:75], v[112:113], v[74:75]
	v_pk_mul_f32 v[80:81], v[122:123], v[80:81]
	v_pk_mul_f32 v[78:79], v[112:113], v[78:79]
	v_pk_mul_f32 v[84:85], v[122:123], v[84:85]
	v_pk_mul_f32 v[82:83], v[112:113], v[82:83]
	v_pk_mul_f32 v[88:89], v[122:123], v[88:89]
	v_pk_mul_f32 v[86:87], v[112:113], v[86:87]
	v_pk_mul_f32 v[92:93], v[122:123], v[92:93]
	v_pk_mul_f32 v[90:91], v[112:113], v[90:91]
	v_pk_mul_f32 v[96:97], v[122:123], v[96:97]
	v_pk_mul_f32 v[94:95], v[112:113], v[94:95]
	s_setprio 1
	ds_read_b64_tr_b16 v[178:179], v145
	ds_read_b64_tr_b16 v[180:181], v145 offset:1088
	ds_read_b64_tr_b16 v[184:185], v140 offset:1088
	ds_read_b64_tr_b16 v[182:183], v140
	ds_read_b64_tr_b16 v[186:187], v140 offset:64
	ds_read_b64_tr_b16 v[188:189], v140 offset:1152
	ds_read_b64_tr_b16 v[190:191], v140 offset:96
	ds_read_b64_tr_b16 v[192:193], v140 offset:1184
	ds_read_b64_tr_b16 v[194:195], v140 offset:128
	ds_read_b64_tr_b16 v[196:197], v140 offset:1216
	ds_read_b64_tr_b16 v[198:199], v140 offset:160
	ds_read_b64_tr_b16 v[200:201], v140 offset:1248
	ds_read_b64_tr_b16 v[202:203], v140 offset:192
	ds_read_b64_tr_b16 v[204:205], v140 offset:1280
	ds_read_b64_tr_b16 v[206:207], v140 offset:32
	ds_read_b64_tr_b16 v[208:209], v140 offset:1120
	ds_read_b64_tr_b16 v[212:213], v140 offset:224
	ds_read_b64_tr_b16 v[214:215], v140 offset:1312
	s_waitcnt lgkmcnt(14)
	v_mfma_f32_16x16x32_bf16 v[66:69], v[182:185], v[178:181], v[66:69]
	ds_read_b64_tr_b16 v[216:217], v145 offset:8704
	ds_read_b64_tr_b16 v[218:219], v145 offset:9792
	s_waitcnt lgkmcnt(14)
	v_mfma_f32_16x16x32_bf16 v[74:77], v[186:189], v[178:181], v[74:77]
	ds_read_b64_tr_b16 v[220:221], v140 offset:8704
	ds_read_b64_tr_b16 v[222:223], v140 offset:9792
	s_waitcnt lgkmcnt(14)
	v_mfma_f32_16x16x32_bf16 v[78:81], v[190:193], v[178:181], v[78:81]
	ds_read_b64_tr_b16 v[236:237], v140 offset:8736
	ds_read_b64_tr_b16 v[238:239], v140 offset:9824
	s_waitcnt lgkmcnt(14)
	v_mfma_f32_16x16x32_bf16 v[82:85], v[194:197], v[178:181], v[82:85]
	ds_read_b64_tr_b16 v[182:183], v140 offset:8768
	ds_read_b64_tr_b16 v[184:185], v140 offset:9856
	s_waitcnt lgkmcnt(14)
	v_mfma_f32_16x16x32_bf16 v[86:89], v[198:201], v[178:181], v[86:89]
	ds_read_b64_tr_b16 v[186:187], v140 offset:8800
	ds_read_b64_tr_b16 v[188:189], v140 offset:9888
	s_waitcnt lgkmcnt(14)
	v_mfma_f32_16x16x32_bf16 v[90:93], v[202:205], v[178:181], v[90:93]
	ds_read_b64_tr_b16 v[190:191], v140 offset:8832
	ds_read_b64_tr_b16 v[192:193], v140 offset:9920
	s_waitcnt lgkmcnt(14)
	v_mfma_f32_16x16x32_bf16 v[70:73], v[206:209], v[178:181], v[70:73]
	ds_read_b64_tr_b16 v[194:195], v140 offset:8864
	ds_read_b64_tr_b16 v[196:197], v140 offset:9952
	s_waitcnt lgkmcnt(14)
	v_mfma_f32_16x16x32_bf16 v[94:97], v[212:215], v[178:181], v[94:97]
	ds_read_b64_tr_b16 v[198:199], v140 offset:8896
	ds_read_b64_tr_b16 v[200:201], v140 offset:9984
	ds_read_b64_tr_b16 v[202:203], v140 offset:8928
	ds_read_b64_tr_b16 v[204:205], v140 offset:10016
	s_waitcnt lgkmcnt(14)
; __device__ __forceinline__ unsigned cvt_pk_bf16(float lo, float hi) { const f32x2c_t v = {lo, hi}; return __builtin_bit_cast(unsigned, __builtin_convertvector(v, bf16x2c_t)); }
; #define LAS __attribute__((address_space(3)))
; __device__ __forceinline__ float bf_lo(unsigned w) { return __uint_as_float(w << 16); }
; __device__ __forceinline__ float bf_hi(unsigned w) { return __uint_as_float(w & 0xffff0000u); }
; __device__ __forceinline__ void tile_put(ldsp T, const TileRegs& t, int tid) {
; #pragma unroll
;     for (int i = 0; i < 4; ++i) { const int ck = tid + 512 * i, r = ck >> 4, ch = ck & 15; *(LAS v4u*)(T + offb(r, ch)) = t.v[i]; }
; }
; __device__ __forceinline__ void tile_put_v(ldsp T, const TileRegs& t, int tid) {
; #pragma unroll
;     for (int i = 0; i < 4; ++i) { const int ck = tid + 512 * i, r = ck >> 4, ch = ck & 15; *(LAS v4u*)(T + offb_v(r, ch)) = t.v[i]; }
; }
; __device__ __forceinline__ void tile_put_scaled(ldsp T, const TileRegs& t, float l2, float a0, float a1, int tid) {
; #pragma unroll
;     for (int i = 0; i < 4; ++i) { const int ck = tid + 512 * i, r = ck >> 4, ch = ck & 15;
;         const float sc = __builtin_amdgcn_exp2f(l2 * (a0 + a1 * (float)r));
;         v4u o;
; #pragma unroll
;         for (int k = 0; k < 4; ++k) o[k] = cvt_pk_bf16(bf_lo(t.v[i][k]) * sc, bf_hi(t.v[i][k]) * sc);
;         *(LAS v4u*)(T + offb(r, ch)) = o; }
; }
	v_mfma_f32_16x16x32_bf16 v[66:69], v[220:223], v[216:219], v[66:69]
	ds_read_b64_tr_b16 v[206:207], v145 offset:17408
	ds_read_b64_tr_b16 v[208:209], v145 offset:18496
	s_waitcnt lgkmcnt(14)
	v_mfma_f32_16x16x32_bf16 v[70:73], v[236:239], v[216:219], v[70:73]
	ds_read_b64_tr_b16 v[212:213], v140 offset:17408
	ds_read_b64_tr_b16 v[214:215], v140 offset:18496
	s_waitcnt lgkmcnt(14)
	v_mfma_f32_16x16x32_bf16 v[74:77], v[182:185], v[216:219], v[74:77]
	ds_read_b64_tr_b16 v[178:179], v140 offset:17440
	ds_read_b64_tr_b16 v[180:181], v140 offset:18528
	s_waitcnt lgkmcnt(14)
	v_mfma_f32_16x16x32_bf16 v[78:81], v[186:189], v[216:219], v[78:81]
	ds_read_b64_tr_b16 v[220:221], v140 offset:17472
	ds_read_b64_tr_b16 v[222:223], v140 offset:18560
	s_waitcnt lgkmcnt(14)
	v_mfma_f32_16x16x32_bf16 v[82:85], v[190:193], v[216:219], v[82:85]
	ds_read_b64_tr_b16 v[236:237], v140 offset:17504
	ds_read_b64_tr_b16 v[238:239], v140 offset:18592
	s_waitcnt lgkmcnt(14)
	v_mfma_f32_16x16x32_bf16 v[86:89], v[194:197], v[216:219], v[86:89]
	ds_read_b64_tr_b16 v[182:183], v140 offset:17536
	ds_read_b64_tr_b16 v[184:185], v140 offset:18624
	s_waitcnt lgkmcnt(14)
	v_mfma_f32_16x16x32_bf16 v[90:93], v[198:201], v[216:219], v[90:93]
	ds_read_b64_tr_b16 v[186:187], v140 offset:17568
	ds_read_b64_tr_b16 v[188:189], v140 offset:18656
	s_waitcnt lgkmcnt(14)
	v_mfma_f32_16x16x32_bf16 v[94:97], v[202:205], v[216:219], v[94:97]
	ds_read_b64_tr_b16 v[190:191], v140 offset:17600
	ds_read_b64_tr_b16 v[192:193], v140 offset:18688
	ds_read_b64_tr_b16 v[194:195], v140 offset:17632
	ds_read_b64_tr_b16 v[196:197], v140 offset:18720
	s_waitcnt lgkmcnt(14)
	v_mfma_f32_16x16x32_bf16 v[66:69], v[212:215], v[206:209], v[66:69]
	ds_read_b64_tr_b16 v[198:199], v145 offset:26112
	ds_read_b64_tr_b16 v[200:201], v145 offset:27200
	s_waitcnt lgkmcnt(14)
	v_mfma_f32_16x16x32_bf16 v[70:73], v[178:181], v[206:209], v[70:73]
	ds_read_b64_tr_b16 v[202:203], v140 offset:26112
	ds_read_b64_tr_b16 v[204:205], v140 offset:27200
	s_waitcnt lgkmcnt(14)
	v_mfma_f32_16x16x32_bf16 v[74:77], v[220:223], v[206:209], v[74:77]
	ds_read_b64_tr_b16 v[216:217], v140 offset:26144
	ds_read_b64_tr_b16 v[218:219], v140 offset:27232
	s_waitcnt lgkmcnt(14)
	v_mfma_f32_16x16x32_bf16 v[78:81], v[236:239], v[206:209], v[78:81]
	ds_read_b64_tr_b16 v[212:213], v140 offset:26176
	ds_read_b64_tr_b16 v[214:215], v140 offset:27264
	s_waitcnt lgkmcnt(14)
	v_mfma_f32_16x16x32_bf16 v[82:85], v[182:185], v[206:209], v[82:85]
	ds_read_b64_tr_b16 v[178:179], v140 offset:26208
	ds_read_b64_tr_b16 v[180:181], v140 offset:27296
	s_waitcnt lgkmcnt(14)
	v_mfma_f32_16x16x32_bf16 v[86:89], v[186:189], v[206:209], v[86:89]
	ds_read_b64_tr_b16 v[220:221], v140 offset:26240
	ds_read_b64_tr_b16 v[222:223], v140 offset:27328
	s_waitcnt lgkmcnt(14)
	v_mfma_f32_16x16x32_bf16 v[90:93], v[190:193], v[206:209], v[90:93]
	ds_read_b64_tr_b16 v[236:237], v140 offset:26272
	ds_read_b64_tr_b16 v[238:239], v140 offset:27360
	s_waitcnt lgkmcnt(14)
	v_mfma_f32_16x16x32_bf16 v[94:97], v[194:197], v[206:209], v[94:97]
	ds_read_b64_tr_b16 v[182:183], v140 offset:26304
	ds_read_b64_tr_b16 v[184:185], v140 offset:27392
	ds_read_b64_tr_b16 v[186:187], v140 offset:26336
	ds_read_b64_tr_b16 v[188:189], v140 offset:27424
	s_waitcnt lgkmcnt(14)
	v_mfma_f32_16x16x32_bf16 v[66:69], v[202:205], v[198:201], v[66:69]
	s_waitcnt lgkmcnt(12)
	v_mfma_f32_16x16x32_bf16 v[70:73], v[216:219], v[198:201], v[70:73]
	s_waitcnt lgkmcnt(10)
	v_mfma_f32_16x16x32_bf16 v[74:77], v[212:215], v[198:201], v[74:77]
	s_waitcnt lgkmcnt(8)
	v_mfma_f32_16x16x32_bf16 v[78:81], v[178:181], v[198:201], v[78:81]
	s_waitcnt lgkmcnt(6)
	v_mfma_f32_16x16x32_bf16 v[82:85], v[220:223], v[198:201], v[82:85]
	s_waitcnt lgkmcnt(4)
	v_mfma_f32_16x16x32_bf16 v[86:89], v[236:239], v[198:201], v[86:89]
	s_waitcnt lgkmcnt(2)
	v_mfma_f32_16x16x32_bf16 v[90:93], v[182:185], v[198:201], v[90:93]
	s_waitcnt lgkmcnt(0)
	v_mfma_f32_16x16x32_bf16 v[94:97], v[186:189], v[198:201], v[94:97]
	s_nop 7
	s_setprio 0
	v_lshlrev_b32_e32 v146, 16, v18
	v_and_b32_e32 v147, 0xffff0000, v18
	v_lshlrev_b32_e32 v148, 16, v19
	v_and_b32_e32 v149, 0xffff0000, v19
	v_pk_mul_f32 v[146:147], v[114:115], v[146:147]
	v_pk_mul_f32 v[148:149], v[114:115], v[148:149]
	v_cvt_pk_bf16_f32 v146, v146, v147
	v_cvt_pk_bf16_f32 v147, v148, v149
	v_lshlrev_b32_e32 v148, 16, v20
	v_and_b32_e32 v149, 0xffff0000, v20
	v_lshlrev_b32_e32 v150, 16, v21
	v_and_b32_e32 v151, 0xffff0000, v21
	v_pk_mul_f32 v[148:149], v[114:115], v[148:149]
	v_pk_mul_f32 v[150:151], v[114:115], v[150:151]
	v_cvt_pk_bf16_f32 v148, v148, v149
	v_cvt_pk_bf16_f32 v149, v150, v151
	ds_write_b128 v99, v[0:3]
	ds_write_b128 v142, v[4:7]
	ds_write_b128 v143, v[8:11]
	ds_write_b128 v144, v[12:15]
	ds_write_b128 v99, v[146:149] offset:34816
	v_lshlrev_b32_e32 v146, 16, v26
	v_and_b32_e32 v147, 0xffff0000, v26
	v_lshlrev_b32_e32 v148, 16, v27
	v_and_b32_e32 v149, 0xffff0000, v27
	v_pk_mul_f32 v[146:147], v[116:117], v[146:147]
	v_pk_mul_f32 v[148:149], v[116:117], v[148:149]
	v_cvt_pk_bf16_f32 v146, v146, v147
	v_cvt_pk_bf16_f32 v147, v148, v149
	v_lshlrev_b32_e32 v148, 16, v28
	v_and_b32_e32 v149, 0xffff0000, v28
	v_lshlrev_b32_e32 v150, 16, v29
	v_and_b32_e32 v151, 0xffff0000, v29
	v_pk_mul_f32 v[148:149], v[116:117], v[148:149]
	v_pk_mul_f32 v[150:151], v[116:117], v[150:151]
	v_cvt_pk_bf16_f32 v148, v148, v149
	v_cvt_pk_bf16_f32 v149, v150, v151
	ds_write_b128 v142, v[146:149] offset:34816
	v_lshlrev_b32_e32 v146, 16, v34
	v_and_b32_e32 v147, 0xffff0000, v34
	v_lshlrev_b32_e32 v148, 16, v35
	v_and_b32_e32 v149, 0xffff0000, v35
	v_pk_mul_f32 v[146:147], v[118:119], v[146:147]
	v_pk_mul_f32 v[148:149], v[118:119], v[148:149]
	v_cvt_pk_bf16_f32 v146, v146, v147
	v_cvt_pk_bf16_f32 v147, v148, v149
	v_lshlrev_b32_e32 v148, 16, v36
	v_and_b32_e32 v149, 0xffff0000, v36
	v_lshlrev_b32_e32 v150, 16, v37
	v_and_b32_e32 v151, 0xffff0000, v37
	v_pk_mul_f32 v[148:149], v[118:119], v[148:149]
	v_pk_mul_f32 v[150:151], v[118:119], v[150:151]
	v_cvt_pk_bf16_f32 v148, v148, v149
	v_cvt_pk_bf16_f32 v149, v150, v151
	ds_write_b128 v143, v[146:149] offset:34816
	v_lshlrev_b32_e32 v146, 16, v42
	v_and_b32_e32 v147, 0xffff0000, v42
	v_lshlrev_b32_e32 v148, 16, v43
	v_and_b32_e32 v149, 0xffff0000, v43
	v_pk_mul_f32 v[146:147], v[120:121], v[146:147]
	v_pk_mul_f32 v[148:149], v[120:121], v[148:149]
	v_cvt_pk_bf16_f32 v146, v146, v147
	v_cvt_pk_bf16_f32 v147, v148, v149
	v_lshlrev_b32_e32 v148, 16, v44
	v_and_b32_e32 v149, 0xffff0000, v44
	v_lshlrev_b32_e32 v150, 16, v45
	v_and_b32_e32 v151, 0xffff0000, v45
	v_pk_mul_f32 v[148:149], v[120:121], v[148:149]
	v_pk_mul_f32 v[150:151], v[120:121], v[150:151]
	v_cvt_pk_bf16_f32 v148, v148, v149
	v_cvt_pk_bf16_f32 v149, v150, v151
	ds_write_b128 v144, v[146:149] offset:34816
	s_branch .LBB0_304

; __device__ __forceinline__ unsigned cvt_pk_bf16(float lo, float hi) { const f32x2c_t v = {lo, hi}; return __builtin_bit_cast(unsigned, __builtin_convertvector(v, bf16x2c_t)); }
; #define LAS __attribute__((address_space(3)))
; __device__ __forceinline__ float bf_lo(unsigned w) { return __uint_as_float(w << 16); }
; __device__ __forceinline__ float bf_hi(unsigned w) { return __uint_as_float(w & 0xffff0000u); }
; __device__ __forceinline__ void sgu_unit(ldsp lds, const bf16* proj, bf16* mix, const float* sgup, const float* ln_g, const float* ln_b, const float* w_s, const float* b_s, int unit, int tid) {
;     ...
;     const float* ws = w_s + (size_t)g * CHUNK * CHUNK;
; #pragma unroll
;     for (int i = 0; i < 4; ++i) { const int ck = tid + 512 * i, r = ck >> 4, ch = ck & 15;
;     ...
;         const f32x4 x = wx[i], y = wy[i];
;     ...
;         const f32x4 x = *(const f32x4*)(ws + r * 128 + 8 * ch), y = *(const f32x4*)(ws + r * 128 + 8 * ch + 4);
;     ...
;         v4u v; v[0] = cvt_pk_bf16(x[0], x[1]); v[1] = cvt_pk_bf16(x[2], x[3]); v[2] = cvt_pk_bf16(y[0], y[1]); v[3] = cvt_pk_bf16(y[2], y[3]);
;         *(LAS v4u*)(TA + offb(r, ch)) = v; }
;     ...
;     TileRegs rv; tile_fetch(rv, proj + row0 * INW + C_V + g * HDIM, INW, tid);
;     ...
;     __syncthreads();
; #pragma unroll
;     for (int i = 0; i < 4; ++i) { const int ck = tid + 512 * i, r = ck >> 4, ch = ck & 15;
;         const v4u v = rv.v[i];
;         const float mean = stat[2 * r], rstd = stat[2 * r + 1];
;         const f32x4 g0 = *(const f32x4*)(ln_g + g * HDIM + 8 * ch), g1 = *(const f32x4*)(ln_g + g * HDIM + 8 * ch + 4);
;         const f32x4 b0 = *(const f32x4*)(ln_b + g * HDIM + 8 * ch), b1 = *(const f32x4*)(ln_b + g * HDIM + 8 * ch + 4);
;         v4u o;
;         o[0] = cvt_pk_bf16((bf_lo(v[0]) - mean) * rstd * g0[0] + b0[0], (bf_hi(v[0]) - mean) * rstd * g0[1] + b0[1]);
;         o[1] = cvt_pk_bf16((bf_lo(v[1]) - mean) * rstd * g0[2] + b0[2], (bf_hi(v[1]) - mean) * rstd * g0[3] + b0[3]);
;         o[2] = cvt_pk_bf16((bf_lo(v[2]) - mean) * rstd * g1[0] + b1[0], (bf_hi(v[2]) - mean) * rstd * g1[1] + b1[1]);
;         o[3] = cvt_pk_bf16((bf_lo(v[3]) - mean) * rstd * g1[2] + b1[2], (bf_hi(v[3]) - mean) * rstd * g1[3] + b1[3]);
;         *(LAS v4u*)(TB + offb(r, ch)) = o; }
.LBB0_404:
	s_or_b64 exec, exec, s[0:1]
	s_and_b32 s0, s16, 7
	s_lshl_b32 s78, s0, 16
	v_lshl_add_u64 v[8:9], v[18:19], 0, s[78:79]
	v_lshl_add_u64 v[4:5], v[22:23], 2, v[8:9]
	s_waitcnt lgkmcnt(0)
	global_load_dwordx4 v[0:3], v[4:5], off offset:16
	s_nop 0
	global_load_dwordx4 v[4:7], v[4:5], off
	s_ashr_i32 s1, s4, 6
	s_mul_i32 s4, s23, 0x4800
	s_mul_hi_u32 s5, s22, 0x4800
	s_add_i32 s5, s5, s4
	s_mul_i32 s4, s22, 0x4800
	s_add_u32 s12, s58, s4
	s_addc_u32 s5, s59, s5
	s_lshl_b32 s4, s0, 8
	s_add_u32 s12, s12, s4
	s_addc_u32 s13, s5, 0
	s_lshl_b32 s78, s0, 9
	v_lshl_add_u64 v[88:89], v[38:39], 0, s[78:79]
	v_lshl_add_u64 v[96:97], v[40:41], 0, s[78:79]
	s_mul_i32 s5, s1, 0x1100
	v_add_u32_e32 v61, s5, v63
	s_waitcnt vmcnt(0)
	v_cvt_pk_bf16_f32 v4, v4, v5
	v_cvt_pk_bf16_f32 v5, v6, v7
	v_cvt_pk_bf16_f32 v6, v0, v1
	v_cvt_pk_bf16_f32 v7, v2, v3
	ds_write_b128 v70, v[4:7]
	v_lshl_add_u64 v[4:5], v[24:25], 2, v[8:9]
	global_load_dwordx4 v[0:3], v[4:5], off offset:16
	s_nop 0
	global_load_dwordx4 v[4:7], v[4:5], off
	s_waitcnt vmcnt(0)
	v_cvt_pk_bf16_f32 v4, v4, v5
	v_cvt_pk_bf16_f32 v5, v6, v7
	v_cvt_pk_bf16_f32 v6, v0, v1
	v_cvt_pk_bf16_f32 v7, v2, v3
	ds_write_b128 v71, v[4:7]
	v_lshl_add_u64 v[4:5], v[26:27], 2, v[8:9]
	global_load_dwordx4 v[0:3], v[4:5], off offset:16
	s_nop 0
	global_load_dwordx4 v[4:7], v[4:5], off
	s_waitcnt vmcnt(0)
	v_cvt_pk_bf16_f32 v4, v4, v5
	v_cvt_pk_bf16_f32 v5, v6, v7
	v_cvt_pk_bf16_f32 v6, v0, v1
	v_cvt_pk_bf16_f32 v7, v2, v3
	ds_write_b128 v72, v[4:7]
	v_lshl_add_u64 v[4:5], v[28:29], 2, v[8:9]
	global_load_dwordx4 v[0:3], v[4:5], off offset:16
	s_nop 0
	global_load_dwordx4 v[4:7], v[4:5], off
	s_waitcnt vmcnt(0)
	v_cvt_pk_bf16_f32 v4, v4, v5
	v_cvt_pk_bf16_f32 v5, v6, v7
	v_cvt_pk_bf16_f32 v6, v0, v1
	v_lshl_add_u64 v[0:1], s[12:13], 0, v[16:17]
	v_cvt_pk_bf16_f32 v7, v2, v3
	v_lshl_add_u64 v[2:3], v[0:1], 0, v[30:31]
	global_load_dwordx4 v[80:83], v[2:3], off offset:2048
	v_lshl_add_u64 v[2:3], v[0:1], 0, v[32:33]
	global_load_dwordx4 v[8:11], v[2:3], off offset:2048
	v_lshl_add_u64 v[2:3], v[0:1], 0, v[34:35]
	v_lshl_add_u64 v[0:1], v[0:1], 0, v[36:37]
	ds_write_b128 v73, v[4:7]
	global_load_dwordx4 v[4:7], v[2:3], off offset:2048
	s_waitcnt vmcnt(2)
	v_lshlrev_b32_e32 v102, 16, v80
	global_load_dwordx4 v[0:3], v[0:1], off offset:2048
	s_waitcnt lgkmcnt(0)
	s_barrier
	ds_read_b64 v[100:101], v74
	global_load_dwordx4 v[84:87], v[88:89], off offset:16
	s_nop 0
	global_load_dwordx4 v[88:91], v[88:89], off
	s_nop 0
	global_load_dwordx4 v[92:95], v[96:97], off offset:16
	s_nop 0
	global_load_dwordx4 v[96:99], v[96:97], off
	v_and_b32_e32 v103, 0xffff0000, v80
	s_waitcnt lgkmcnt(0)
	v_pk_add_f32 v[102:103], v[102:103], v[100:101] op_sel_hi:[1,0] neg_lo:[0,1] neg_hi:[0,1]
	s_nop 0
	v_pk_mul_f32 v[102:103], v[100:101], v[102:103] op_sel:[1,0]
	s_waitcnt vmcnt(0)
	v_pk_fma_f32 v[102:103], v[102:103], v[88:89], v[96:97]
	s_nop 0
	v_cvt_pk_bf16_f32 v80, v102, v103
	v_lshlrev_b32_e32 v102, 16, v81
	v_and_b32_e32 v103, 0xffff0000, v81
	v_pk_add_f32 v[102:103], v[102:103], v[100:101] op_sel_hi:[1,0] neg_lo:[0,1] neg_hi:[0,1]
	s_nop 0
	v_pk_mul_f32 v[102:103], v[100:101], v[102:103] op_sel:[1,0]
	s_nop 0
	v_pk_fma_f32 v[102:103], v[102:103], v[90:91], v[98:99]
	s_nop 0
	v_cvt_pk_bf16_f32 v81, v102, v103
	v_lshlrev_b32_e32 v102, 16, v82
	v_and_b32_e32 v103, 0xffff0000, v82
	v_pk_add_f32 v[102:103], v[102:103], v[100:101] op_sel_hi:[1,0] neg_lo:[0,1] neg_hi:[0,1]
	s_nop 0
	v_pk_mul_f32 v[102:103], v[100:101], v[102:103] op_sel:[1,0]
	s_nop 0
	v_pk_fma_f32 v[102:103], v[102:103], v[84:85], v[92:93]
	s_nop 0
	v_cvt_pk_bf16_f32 v82, v102, v103
	v_lshlrev_b32_e32 v102, 16, v83
	v_and_b32_e32 v103, 0xffff0000, v83
	v_pk_add_f32 v[102:103], v[102:103], v[100:101] op_sel_hi:[1,0] neg_lo:[0,1] neg_hi:[0,1]
	s_nop 0
	v_pk_mul_f32 v[100:101], v[100:101], v[102:103] op_sel:[1,0]
	s_nop 0
	v_pk_fma_f32 v[100:101], v[100:101], v[86:87], v[94:95]
	s_nop 0
	v_cvt_pk_bf16_f32 v83, v100, v101
	ds_write_b128 v70, v[80:83] offset:34816
	ds_read_b64 v[80:81], v75
	v_lshlrev_b32_e32 v82, 16, v8
	v_and_b32_e32 v83, 0xffff0000, v8
	s_waitcnt lgkmcnt(0)
	v_pk_add_f32 v[82:83], v[82:83], v[80:81] op_sel_hi:[1,0] neg_lo:[0,1] neg_hi:[0,1]
	s_nop 0
	v_pk_mul_f32 v[82:83], v[80:81], v[82:83] op_sel:[1,0]
	s_nop 0
	v_pk_fma_f32 v[82:83], v[88:89], v[82:83], v[96:97]
	s_nop 0
	v_cvt_pk_bf16_f32 v8, v82, v83
	v_lshlrev_b32_e32 v82, 16, v9
	v_and_b32_e32 v83, 0xffff0000, v9
	v_pk_add_f32 v[82:83], v[82:83], v[80:81] op_sel_hi:[1,0] neg_lo:[0,1] neg_hi:[0,1]
	s_nop 0
	v_pk_mul_f32 v[82:83], v[80:81], v[82:83] op_sel:[1,0]
	s_nop 0
	v_pk_fma_f32 v[82:83], v[90:91], v[82:83], v[98:99]
	s_nop 0
	v_cvt_pk_bf16_f32 v9, v82, v83
	v_lshlrev_b32_e32 v82, 16, v10
	v_and_b32_e32 v83, 0xffff0000, v10
	v_pk_add_f32 v[82:83], v[82:83], v[80:81] op_sel_hi:[1,0] neg_lo:[0,1] neg_hi:[0,1]
	s_nop 0
	v_pk_mul_f32 v[82:83], v[80:81], v[82:83] op_sel:[1,0]
	s_nop 0
	v_pk_fma_f32 v[82:83], v[84:85], v[82:83], v[92:93]
	s_nop 0
	v_cvt_pk_bf16_f32 v10, v82, v83
	v_lshlrev_b32_e32 v82, 16, v11
	v_and_b32_e32 v83, 0xffff0000, v11
	v_pk_add_f32 v[82:83], v[82:83], v[80:81] op_sel_hi:[1,0] neg_lo:[0,1] neg_hi:[0,1]
	s_nop 0
	v_pk_mul_f32 v[80:81], v[80:81], v[82:83] op_sel:[1,0]
	s_nop 0
	v_pk_fma_f32 v[80:81], v[86:87], v[80:81], v[94:95]
	s_nop 0
	v_cvt_pk_bf16_f32 v11, v80, v81
	ds_write_b128 v71, v[8:11] offset:34816
	ds_read_b64 v[8:9], v76
	v_lshlrev_b32_e32 v10, 16, v4
	v_and_b32_e32 v11, 0xffff0000, v4
	s_waitcnt lgkmcnt(0)
; #define LAS __attribute__((address_space(3)))
; template <bool A_TR, bool B_TR>
; __device__ __forceinline__ void mm128(f32x4 (&acc)[8], ldsp TA, ldsp TB, int w, int lane) {
;     const ldsp ab = A_TR ? tr_base(TA, lane) + 32u * w : row_base(TA, lane) + 16u * TP * w;
;     const ldsp bb = B_TR ? tr_base(TB, lane) : row_base(TB, lane);
;     if (MM_SETPRIO) __builtin_amdgcn_s_setprio(1);
;     ...
;     bf16x8 a[4];
; #pragma unroll
;     for (int ks = 0; ks < 4; ++ks) a[ks] = A_TR ? frag_tr(ab, 0, ks) : frag_row(ab, 0, ks);
;     mm_pipe<MM_G, 0, 4, 0, 8>(acc, [&](int c, int ks) { return B_TR ? frag_tr(bb, c, ks) : frag_row(bb, c, ks); }, [&](int ks) { return a[ks]; });
;     ...
; #pragma unroll
;     for (int ks = 0; ks < 4; ++ks) {
;         const bf16x8 a = A_TR ? frag_tr(ab, 0, ks) : frag_row(ab, 0, ks);
; #pragma unroll
;         for (int c = 0; c < 8; ++c) {
;             const bf16x8 b = B_TR ? frag_tr(bb, c, ks) : frag_row(bb, c, ks);
;             acc[c] = __builtin_amdgcn_mfma_f32_16x16x32_bf16(b, a, acc[c], 0, 0, 0);
;         }
;     }
; __device__ __forceinline__ void sgu_unit(ldsp lds, const bf16* proj, bf16* mix, const float* sgup, const float* ln_g, const float* ln_b, const float* w_s, const float* b_s, int unit, int tid) {
;     ...
; #pragma unroll
;     for (int i = 0; i < 4; ++i) { const int ck = tid + 512 * i, r = ck >> 4, ch = ck & 15;
;         const v4u v = rv.v[i];
;         const float mean = stat[2 * r], rstd = stat[2 * r + 1];
;         const f32x4 g0 = *(const f32x4*)(ln_g + g * HDIM + 8 * ch), g1 = *(const f32x4*)(ln_g + g * HDIM + 8 * ch + 4);
;         const f32x4 b0 = *(const f32x4*)(ln_b + g * HDIM + 8 * ch), b1 = *(const f32x4*)(ln_b + g * HDIM + 8 * ch + 4);
;         v4u o;
;         o[0] = cvt_pk_bf16((bf_lo(v[0]) - mean) * rstd * g0[0] + b0[0], (bf_hi(v[0]) - mean) * rstd * g0[1] + b0[1]);
;         o[1] = cvt_pk_bf16((bf_lo(v[1]) - mean) * rstd * g0[2] + b0[2], (bf_hi(v[1]) - mean) * rstd * g0[3] + b0[3]);
;         o[2] = cvt_pk_bf16((bf_lo(v[2]) - mean) * rstd * g1[0] + b1[0], (bf_hi(v[2]) - mean) * rstd * g1[1] + b1[1]);
;         o[3] = cvt_pk_bf16((bf_lo(v[3]) - mean) * rstd * g1[2] + b1[2], (bf_hi(v[3]) - mean) * rstd * g1[3] + b1[3]);
;         *(LAS v4u*)(TB + offb(r, ch)) = o; }
;     __syncthreads();
;     f32x4 acc[8]; zero8(acc);
;     mm128<false, true>(acc, TA, TB, w, lane);
	v_pk_add_f32 v[10:11], v[10:11], v[8:9] op_sel_hi:[1,0] neg_lo:[0,1] neg_hi:[0,1]
	s_nop 0
	v_pk_mul_f32 v[10:11], v[8:9], v[10:11] op_sel:[1,0]
	s_nop 0
	v_pk_fma_f32 v[10:11], v[88:89], v[10:11], v[96:97]
	s_nop 0
	v_cvt_pk_bf16_f32 v4, v10, v11
	v_lshlrev_b32_e32 v10, 16, v5
	v_and_b32_e32 v11, 0xffff0000, v5
	v_pk_add_f32 v[10:11], v[10:11], v[8:9] op_sel_hi:[1,0] neg_lo:[0,1] neg_hi:[0,1]
	s_nop 0
	v_pk_mul_f32 v[10:11], v[8:9], v[10:11] op_sel:[1,0]
	s_nop 0
	v_pk_fma_f32 v[10:11], v[90:91], v[10:11], v[98:99]
	s_nop 0
	v_cvt_pk_bf16_f32 v5, v10, v11
	v_lshlrev_b32_e32 v10, 16, v6
	v_and_b32_e32 v11, 0xffff0000, v6
	v_pk_add_f32 v[10:11], v[10:11], v[8:9] op_sel_hi:[1,0] neg_lo:[0,1] neg_hi:[0,1]
	s_nop 0
	v_pk_mul_f32 v[10:11], v[8:9], v[10:11] op_sel:[1,0]
	s_nop 0
	v_pk_fma_f32 v[10:11], v[84:85], v[10:11], v[92:93]
	s_nop 0
	v_cvt_pk_bf16_f32 v6, v10, v11
	v_lshlrev_b32_e32 v10, 16, v7
	v_and_b32_e32 v11, 0xffff0000, v7
	v_pk_add_f32 v[10:11], v[10:11], v[8:9] op_sel_hi:[1,0] neg_lo:[0,1] neg_hi:[0,1]
	s_nop 0
	v_pk_mul_f32 v[8:9], v[8:9], v[10:11] op_sel:[1,0]
	s_nop 0
	v_pk_fma_f32 v[8:9], v[86:87], v[8:9], v[94:95]
	s_nop 0
	v_cvt_pk_bf16_f32 v7, v8, v9
	ds_write_b128 v72, v[4:7] offset:34816
	ds_read_b64 v[4:5], v77
	v_lshlrev_b32_e32 v6, 16, v0
	v_and_b32_e32 v7, 0xffff0000, v0
	s_waitcnt lgkmcnt(0)
	v_pk_add_f32 v[6:7], v[6:7], v[4:5] op_sel_hi:[1,0] neg_lo:[0,1] neg_hi:[0,1]
	s_nop 0
	v_pk_mul_f32 v[6:7], v[4:5], v[6:7] op_sel:[1,0]
	s_nop 0
	v_pk_fma_f32 v[6:7], v[88:89], v[6:7], v[96:97]
	s_nop 0
	v_cvt_pk_bf16_f32 v0, v6, v7
	v_lshlrev_b32_e32 v6, 16, v1
	v_and_b32_e32 v7, 0xffff0000, v1
	v_pk_add_f32 v[6:7], v[6:7], v[4:5] op_sel_hi:[1,0] neg_lo:[0,1] neg_hi:[0,1]
	s_nop 0
	v_pk_mul_f32 v[6:7], v[4:5], v[6:7] op_sel:[1,0]
	s_nop 0
	v_pk_fma_f32 v[6:7], v[90:91], v[6:7], v[98:99]
	s_nop 0
	v_cvt_pk_bf16_f32 v1, v6, v7
	v_lshlrev_b32_e32 v6, 16, v2
	v_and_b32_e32 v7, 0xffff0000, v2
	v_pk_add_f32 v[6:7], v[6:7], v[4:5] op_sel_hi:[1,0] neg_lo:[0,1] neg_hi:[0,1]
	s_nop 0
	v_pk_mul_f32 v[6:7], v[4:5], v[6:7] op_sel:[1,0]
	s_nop 0
	v_pk_fma_f32 v[6:7], v[84:85], v[6:7], v[92:93]
	s_nop 0
	v_cvt_pk_bf16_f32 v2, v6, v7
	v_lshlrev_b32_e32 v6, 16, v3
	v_and_b32_e32 v7, 0xffff0000, v3
	v_pk_add_f32 v[6:7], v[6:7], v[4:5] op_sel_hi:[1,0] neg_lo:[0,1] neg_hi:[0,1]
	s_nop 0
	v_pk_mul_f32 v[4:5], v[4:5], v[6:7] op_sel:[1,0]
	s_nop 0
	v_pk_fma_f32 v[4:5], v[86:87], v[4:5], v[94:95]
	s_nop 0
	v_cvt_pk_bf16_f32 v3, v4, v5
	ds_write_b128 v73, v[0:3] offset:34816
	s_waitcnt lgkmcnt(0)
	s_barrier
	s_setprio 1
	ds_read_b128 v[124:127], v61
	ds_read_b64_tr_b16 v[180:181], v64 offset:35904
	ds_read_b64_tr_b16 v[178:179], v64 offset:34816
	ds_read_b64_tr_b16 v[182:183], v64 offset:34848
	ds_read_b64_tr_b16 v[184:185], v64 offset:35936
	ds_read_b64_tr_b16 v[186:187], v64 offset:34880
	ds_read_b64_tr_b16 v[188:189], v64 offset:35968
	ds_read_b64_tr_b16 v[190:191], v64 offset:34912
	ds_read_b64_tr_b16 v[192:193], v64 offset:36000
	ds_read_b64_tr_b16 v[194:195], v64 offset:34944
	ds_read_b64_tr_b16 v[196:197], v64 offset:36032
	ds_read_b64_tr_b16 v[198:199], v64 offset:34976
	ds_read_b64_tr_b16 v[200:201], v64 offset:36064
	ds_read_b64_tr_b16 v[202:203], v64 offset:35008
	ds_read_b64_tr_b16 v[204:205], v64 offset:36096
	ds_read_b64_tr_b16 v[206:207], v64 offset:35040
	ds_read_b64_tr_b16 v[208:209], v64 offset:36128
	s_waitcnt lgkmcnt(14)
	v_mfma_f32_16x16x32_bf16 v[4:7], v[178:181], v[124:127], 0
	ds_read_b128 v[212:215], v61 offset:64
	s_waitcnt lgkmcnt(13)
	v_mfma_f32_16x16x32_bf16 v[8:11], v[182:185], v[124:127], 0
	ds_read_b64_tr_b16 v[216:217], v64 offset:43520
	ds_read_b64_tr_b16 v[218:219], v64 offset:44608
	s_waitcnt lgkmcnt(13)
	v_mfma_f32_16x16x32_bf16 v[80:83], v[186:189], v[124:127], 0
	ds_read_b64_tr_b16 v[220:221], v64 offset:43552
	ds_read_b64_tr_b16 v[222:223], v64 offset:44640
	s_waitcnt lgkmcnt(13)
	v_mfma_f32_16x16x32_bf16 v[84:87], v[190:193], v[124:127], 0
	ds_read_b64_tr_b16 v[178:179], v64 offset:43584
	ds_read_b64_tr_b16 v[180:181], v64 offset:44672
	s_waitcnt lgkmcnt(13)
	v_mfma_f32_16x16x32_bf16 v[88:91], v[194:197], v[124:127], 0
	ds_read_b64_tr_b16 v[182:183], v64 offset:43616
	ds_read_b64_tr_b16 v[184:185], v64 offset:44704
	s_waitcnt lgkmcnt(13)
	v_mfma_f32_16x16x32_bf16 v[92:95], v[198:201], v[124:127], 0
	ds_read_b64_tr_b16 v[186:187], v64 offset:43648
	ds_read_b64_tr_b16 v[188:189], v64 offset:44736
	s_waitcnt lgkmcnt(13)
	v_mfma_f32_16x16x32_bf16 v[96:99], v[202:205], v[124:127], 0
	ds_read_b64_tr_b16 v[190:191], v64 offset:43680
	ds_read_b64_tr_b16 v[192:193], v64 offset:44768
	s_waitcnt lgkmcnt(13)
	v_mfma_f32_16x16x32_bf16 v[0:3], v[206:209], v[124:127], 0
	ds_read_b64_tr_b16 v[194:195], v64 offset:43712
	ds_read_b64_tr_b16 v[196:197], v64 offset:44800
	ds_read_b64_tr_b16 v[198:199], v64 offset:43744
	ds_read_b64_tr_b16 v[200:201], v64 offset:44832
	s_waitcnt lgkmcnt(14)
	v_mfma_f32_16x16x32_bf16 v[4:7], v[216:219], v[212:215], v[4:7]
	ds_read_b128 v[202:205], v61 offset:128
	s_waitcnt lgkmcnt(13)
	v_mfma_f32_16x16x32_bf16 v[8:11], v[220:223], v[212:215], v[8:11]
	ds_read_b64_tr_b16 v[206:207], v64 offset:52224
	ds_read_b64_tr_b16 v[208:209], v64 offset:53312
	s_waitcnt lgkmcnt(13)
	v_mfma_f32_16x16x32_bf16 v[80:83], v[178:181], v[212:215], v[80:83]
	ds_read_b64_tr_b16 v[124:125], v64 offset:52256
	ds_read_b64_tr_b16 v[126:127], v64 offset:53344
	s_waitcnt lgkmcnt(13)
	v_mfma_f32_16x16x32_bf16 v[84:87], v[182:185], v[212:215], v[84:87]
	ds_read_b64_tr_b16 v[216:217], v64 offset:52288
	ds_read_b64_tr_b16 v[218:219], v64 offset:53376
	s_waitcnt lgkmcnt(13)
; __device__ __forceinline__ unsigned cvt_pk_bf16(float lo, float hi) { const f32x2c_t v = {lo, hi}; return __builtin_bit_cast(unsigned, __builtin_convertvector(v, bf16x2c_t)); }
; #define LAS __attribute__((address_space(3)))
; #define LDS_WAIT() asm volatile("s_waitcnt lgkmcnt(0)" ::: "memory")
; __device__ __forceinline__ void store_acc_tile(ldsp T, const f32x4 (&a)[8], int w, int lane) {
;     const unsigned fr = lane & 15, fq = lane >> 4, row = 16u * w + fr;
; #pragma unroll
;     for (int c = 0; c < 8; ++c) { v2u v; v[0] = cvt_pk_bf16(a[c][0], a[c][1]); v[1] = cvt_pk_bf16(a[c][2], a[c][3]);
;         *(LAS v2u*)(T + offb(row, 2u * c + (fq >> 1)) + 8u * (fq & 1)) = v; }
; }
; __device__ __forceinline__ void sgu_unit(ldsp lds, const bf16* proj, bf16* mix, const float* sgup, const float* ln_g, const float* ln_b, const float* w_s, const float* b_s, int unit, int tid) {
;     ...
;     const int i = 16 * w + fr;
;     const float bs = b_s[g * CHUNK + i];
; #pragma unroll
;     for (int c = 0; c < 8; ++c) acc[c] = acc[c] + bs;
;     store_acc_tile(TA, acc, w, lane);
;     LDS_WAIT();
;     const bf16* ubase = proj + (row0 + 16 * w) * INW + C_U + g * HDIM;
;     bf16* obase = mix + (row0 + 16 * w) * DM + MIX_A + g * HDIM;
	v_mfma_f32_16x16x32_bf16 v[88:91], v[186:189], v[212:215], v[88:91]
	ds_read_b64_tr_b16 v[220:221], v64 offset:52320
	ds_read_b64_tr_b16 v[222:223], v64 offset:53408
	s_waitcnt lgkmcnt(13)
	v_mfma_f32_16x16x32_bf16 v[92:95], v[190:193], v[212:215], v[92:95]
	ds_read_b64_tr_b16 v[178:179], v64 offset:52352
	ds_read_b64_tr_b16 v[180:181], v64 offset:53440
	s_waitcnt lgkmcnt(13)
	v_mfma_f32_16x16x32_bf16 v[96:99], v[194:197], v[212:215], v[96:99]
	ds_read_b64_tr_b16 v[182:183], v64 offset:52384
	ds_read_b64_tr_b16 v[184:185], v64 offset:53472
	s_waitcnt lgkmcnt(13)
	v_mfma_f32_16x16x32_bf16 v[0:3], v[198:201], v[212:215], v[0:3]
	ds_read_b64_tr_b16 v[186:187], v64 offset:52416
	ds_read_b64_tr_b16 v[188:189], v64 offset:53504
	ds_read_b64_tr_b16 v[190:191], v64 offset:52448
	ds_read_b64_tr_b16 v[192:193], v64 offset:53536
	s_waitcnt lgkmcnt(14)
	v_mfma_f32_16x16x32_bf16 v[4:7], v[206:209], v[202:205], v[4:7]
	ds_read_b128 v[194:197], v61 offset:192
	s_waitcnt lgkmcnt(13)
	v_mfma_f32_16x16x32_bf16 v[8:11], v[124:127], v[202:205], v[8:11]
	ds_read_b64_tr_b16 v[198:199], v64 offset:60928
	ds_read_b64_tr_b16 v[200:201], v64 offset:62016
	s_waitcnt lgkmcnt(13)
	v_mfma_f32_16x16x32_bf16 v[80:83], v[216:219], v[202:205], v[80:83]
	ds_read_b64_tr_b16 v[212:213], v64 offset:60960
	ds_read_b64_tr_b16 v[214:215], v64 offset:62048
	s_waitcnt lgkmcnt(13)
	v_mfma_f32_16x16x32_bf16 v[84:87], v[220:223], v[202:205], v[84:87]
	ds_read_b64_tr_b16 v[206:207], v64 offset:60992
	ds_read_b64_tr_b16 v[208:209], v64 offset:62080
	s_waitcnt lgkmcnt(13)
	v_mfma_f32_16x16x32_bf16 v[88:91], v[178:181], v[202:205], v[88:91]
	ds_read_b64_tr_b16 v[124:125], v64 offset:61024
	ds_read_b64_tr_b16 v[126:127], v64 offset:62112
	s_waitcnt lgkmcnt(13)
	v_mfma_f32_16x16x32_bf16 v[92:95], v[182:185], v[202:205], v[92:95]
	ds_read_b64_tr_b16 v[216:217], v64 offset:61056
	ds_read_b64_tr_b16 v[218:219], v64 offset:62144
	s_waitcnt lgkmcnt(13)
	v_mfma_f32_16x16x32_bf16 v[96:99], v[186:189], v[202:205], v[96:99]
	ds_read_b64_tr_b16 v[220:221], v64 offset:61088
	ds_read_b64_tr_b16 v[222:223], v64 offset:62176
	s_waitcnt lgkmcnt(13)
	v_mfma_f32_16x16x32_bf16 v[0:3], v[190:193], v[202:205], v[0:3]
	ds_read_b64_tr_b16 v[178:179], v64 offset:61120
	ds_read_b64_tr_b16 v[180:181], v64 offset:62208
	ds_read_b64_tr_b16 v[182:183], v64 offset:61152
	ds_read_b64_tr_b16 v[184:185], v64 offset:62240
	s_waitcnt lgkmcnt(14)
	v_mfma_f32_16x16x32_bf16 v[4:7], v[198:201], v[194:197], v[4:7]
	s_waitcnt lgkmcnt(12)
	v_mfma_f32_16x16x32_bf16 v[8:11], v[212:215], v[194:197], v[8:11]
	s_waitcnt lgkmcnt(10)
	v_mfma_f32_16x16x32_bf16 v[80:83], v[206:209], v[194:197], v[80:83]
	s_waitcnt lgkmcnt(8)
	v_mfma_f32_16x16x32_bf16 v[84:87], v[124:127], v[194:197], v[84:87]
	s_waitcnt lgkmcnt(6)
	v_mfma_f32_16x16x32_bf16 v[88:91], v[216:219], v[194:197], v[88:91]
	s_waitcnt lgkmcnt(4)
	v_mfma_f32_16x16x32_bf16 v[92:95], v[220:223], v[194:197], v[92:95]
	s_waitcnt lgkmcnt(2)
	v_mfma_f32_16x16x32_bf16 v[96:99], v[178:181], v[194:197], v[96:99]
	s_waitcnt lgkmcnt(0)
	v_mfma_f32_16x16x32_bf16 v[0:3], v[182:185], v[194:197], v[0:3]
	s_nop 7
	s_setprio 0
	s_lshl_b32 s1, s1, 4
	v_lshl_or_b32 v61, s0, 7, v62
	v_add_u32_e32 v100, s1, v61
	v_ashrrev_i32_e32 v101, 31, v100
	v_lshl_add_u64 v[100:101], v[100:101], 2, s[10:11]
	global_load_dword v100, v[100:101], off
	v_or_b32_e32 v61, s1, v62
	s_ashr_i32 s0, s1, 31
	s_waitcnt vmcnt(0)
	v_pk_add_f32 v[6:7], v[6:7], v[100:101] op_sel_hi:[1,0]
	v_pk_add_f32 v[4:5], v[4:5], v[100:101] op_sel_hi:[1,0]
	v_pk_add_f32 v[10:11], v[10:11], v[100:101] op_sel_hi:[1,0]
	v_pk_add_f32 v[8:9], v[8:9], v[100:101] op_sel_hi:[1,0]
	v_pk_add_f32 v[82:83], v[82:83], v[100:101] op_sel_hi:[1,0]
	v_pk_add_f32 v[80:81], v[80:81], v[100:101] op_sel_hi:[1,0]
	v_pk_add_f32 v[86:87], v[86:87], v[100:101] op_sel_hi:[1,0]
	v_pk_add_f32 v[84:85], v[84:85], v[100:101] op_sel_hi:[1,0]
	v_pk_add_f32 v[90:91], v[90:91], v[100:101] op_sel_hi:[1,0]
	v_pk_add_f32 v[88:89], v[88:89], v[100:101] op_sel_hi:[1,0]
	v_pk_add_f32 v[94:95], v[94:95], v[100:101] op_sel_hi:[1,0]
	v_pk_add_f32 v[92:93], v[92:93], v[100:101] op_sel_hi:[1,0]
	v_pk_add_f32 v[98:99], v[98:99], v[100:101] op_sel_hi:[1,0]
	v_pk_add_f32 v[96:97], v[96:97], v[100:101] op_sel_hi:[1,0]
	v_pk_add_f32 v[2:3], v[2:3], v[100:101] op_sel_hi:[1,0]
	v_pk_add_f32 v[0:1], v[0:1], v[100:101] op_sel_hi:[1,0]
	v_mad_u64_u32 v[100:101], s[12:13], v61, s47, v[42:43]
	s_add_u32 s12, s22, s1
	s_addc_u32 s13, s23, s0
	s_mul_i32 s0, s13, 0x4800
	s_mul_hi_u32 s5, s12, 0x4800
	s_add_i32 s5, s5, s0
	s_mul_i32 s0, s12, 0x4800
	v_cvt_pk_bf16_f32 v4, v4, v5
	v_cvt_pk_bf16_f32 v5, v6, v7
	v_cvt_pk_bf16_f32 v6, v8, v9
	v_cvt_pk_bf16_f32 v7, v10, v11
	s_add_u32 s0, s58, s0
	ds_write2_b64 v100, v[4:5], v[6:7] offset1:4
	v_cvt_pk_bf16_f32 v4, v80, v81
	v_cvt_pk_bf16_f32 v5, v82, v83
	v_cvt_pk_bf16_f32 v6, v84, v85
	v_cvt_pk_bf16_f32 v7, v86, v87
	s_addc_u32 s5, s59, s5
	ds_write2_b64 v100, v[4:5], v[6:7] offset0:8 offset1:12
	v_cvt_pk_bf16_f32 v4, v88, v89
	v_cvt_pk_bf16_f32 v5, v90, v91
	v_cvt_pk_bf16_f32 v6, v92, v93
	v_cvt_pk_bf16_f32 v7, v94, v95
	s_add_u32 s22, s0, s4
	ds_write2_b64 v100, v[4:5], v[6:7] offset0:16 offset1:20
	v_cvt_pk_bf16_f32 v4, v96, v97
	v_cvt_pk_bf16_f32 v5, v98, v99
	v_cvt_pk_bf16_f32 v0, v0, v1
	v_cvt_pk_bf16_f32 v1, v2, v3
	s_addc_u32 s23, s5, 0
	v_mov_b32_e32 v61, v17
	ds_write2_b64 v100, v[4:5], v[0:1] offset0:24 offset1:28
	v_lshl_add_u64 v[6:7], s[22:23], 0, v[60:61]
	s_waitcnt lgkmcnt(0)
; __device__ __forceinline__ unsigned cvt_pk_bf16(float lo, float hi) { const f32x2c_t v = {lo, hi}; return __builtin_bit_cast(unsigned, __builtin_convertvector(v, bf16x2c_t)); }
; #define LAS __attribute__((address_space(3)))
; __device__ __forceinline__ float bf_lo(unsigned w) { return __uint_as_float(w << 16); }
; __device__ __forceinline__ float bf_hi(unsigned w) { return __uint_as_float(w & 0xffff0000u); }
; __device__ __forceinline__ void sgu_unit(ldsp lds, const bf16* proj, bf16* mix, const float* sgup, const float* ln_g, const float* ln_b, const float* w_s, const float* b_s, int unit, int tid) {
;     ...
; #pragma unroll
;     for (int k = 0; k < 4; ++k) { const int q = lane + 64 * k, r = q >> 4, ch = q & 15;
;     ...
;         const v4u s = *(const LAS v4u*)(TA + offb(16 * w + r, ch)), u = ur[k];
;     ...
;         const v4u s = *(const LAS v4u*)(TA + offb(16 * w + r, ch)), u = *(const v4u*)(ubase + (size_t)r * INW + 8 * ch);
;     ...
;         v4u o;
; #pragma unroll
;         for (int e = 0; e < 4; ++e) o[e] = cvt_pk_bf16(bf_lo(u[e]) * bf_lo(s[e]), bf_hi(u[e]) * bf_hi(s[e]));
;         *(v4u*)(obase + (size_t)r * DM + 8 * ch) = o; }
	v_lshl_add_u64 v[8:9], v[6:7], 0, v[44:45]
	global_load_dwordx4 v[8:11], v[8:9], off
	s_lshl_b64 s[12:13], s[12:13], 13
	s_add_u32 s0, s60, s12
	s_addc_u32 s5, s61, s13
	s_add_u32 s24, s0, s4
	v_or_b32_e32 v0, s1, v65
	s_addc_u32 s25, s5, 0
	v_mad_u64_u32 v[0:1], s[4:5], v0, s47, v[20:21]
	ds_read_b128 v[0:3], v0
	v_lshl_add_u64 v[4:5], s[24:25], 0, v[60:61]
	s_waitcnt lgkmcnt(0)
	v_lshlrev_b32_e32 v82, 16, v0
	v_and_b32_e32 v83, 0xffff0000, v0
	s_waitcnt vmcnt(0)
	v_lshlrev_b32_e32 v80, 16, v8
	v_and_b32_e32 v81, 0xffff0000, v8
	v_pk_mul_f32 v[80:81], v[82:83], v[80:81]
	v_lshlrev_b32_e32 v8, 16, v9
	v_cvt_pk_bf16_f32 v0, v80, v81
	v_and_b32_e32 v9, 0xffff0000, v9
	v_lshlrev_b32_e32 v80, 16, v1
	v_and_b32_e32 v81, 0xffff0000, v1
	v_pk_mul_f32 v[8:9], v[80:81], v[8:9]
	v_lshlrev_b32_e32 v80, 16, v2
	v_cvt_pk_bf16_f32 v1, v8, v9
	v_lshlrev_b32_e32 v8, 16, v10
	v_and_b32_e32 v9, 0xffff0000, v10
	v_and_b32_e32 v81, 0xffff0000, v2
	v_pk_mul_f32 v[8:9], v[80:81], v[8:9]
	v_lshlrev_b32_e32 v10, 16, v3
	v_cvt_pk_bf16_f32 v2, v8, v9
	v_lshlrev_b32_e32 v8, 16, v11
	v_and_b32_e32 v9, 0xffff0000, v11
	v_and_b32_e32 v11, 0xffff0000, v3
	v_pk_mul_f32 v[8:9], v[10:11], v[8:9]
	s_nop 0
	v_cvt_pk_bf16_f32 v3, v8, v9
	v_lshl_add_u64 v[8:9], v[4:5], 0, v[46:47]
	global_store_dwordx4 v[8:9], v[0:3], off
	v_lshl_add_u64 v[8:9], v[6:7], 0, v[48:49]
	global_load_dwordx4 v[8:11], v[8:9], off
	v_or_b32_e32 v0, s1, v66
	v_mad_u64_u32 v[0:1], s[4:5], v0, s47, v[20:21]
	ds_read_b128 v[0:3], v0
	s_waitcnt lgkmcnt(0)
	v_lshlrev_b32_e32 v82, 16, v0
	v_and_b32_e32 v83, 0xffff0000, v0
	s_waitcnt vmcnt(0)
	v_lshlrev_b32_e32 v80, 16, v8
	v_and_b32_e32 v81, 0xffff0000, v8
	v_pk_mul_f32 v[80:81], v[82:83], v[80:81]
	v_lshlrev_b32_e32 v8, 16, v9
	v_cvt_pk_bf16_f32 v0, v80, v81
	v_and_b32_e32 v9, 0xffff0000, v9
	v_lshlrev_b32_e32 v80, 16, v1
	v_and_b32_e32 v81, 0xffff0000, v1
	v_pk_mul_f32 v[8:9], v[80:81], v[8:9]
	v_lshlrev_b32_e32 v80, 16, v2
	v_cvt_pk_bf16_f32 v1, v8, v9
	v_lshlrev_b32_e32 v8, 16, v10
	v_and_b32_e32 v9, 0xffff0000, v10
	v_and_b32_e32 v81, 0xffff0000, v2
	v_pk_mul_f32 v[8:9], v[80:81], v[8:9]
	v_lshlrev_b32_e32 v10, 16, v3
	v_cvt_pk_bf16_f32 v2, v8, v9
	v_lshlrev_b32_e32 v8, 16, v11
	v_and_b32_e32 v9, 0xffff0000, v11
	v_and_b32_e32 v11, 0xffff0000, v3
	v_pk_mul_f32 v[8:9], v[10:11], v[8:9]
	s_nop 0
	v_cvt_pk_bf16_f32 v3, v8, v9
	v_lshl_add_u64 v[8:9], v[4:5], 0, v[50:51]
	global_store_dwordx4 v[8:9], v[0:3], off
	v_lshl_add_u64 v[8:9], v[6:7], 0, v[52:53]
	global_load_dwordx4 v[8:11], v[8:9], off
	v_or_b32_e32 v0, s1, v67
	v_mad_u64_u32 v[0:1], s[4:5], v0, s47, v[20:21]
	ds_read_b128 v[0:3], v0
	v_lshl_add_u64 v[6:7], v[6:7], 0, v[56:57]
	s_waitcnt lgkmcnt(0)
	v_lshlrev_b32_e32 v82, 16, v0
	v_and_b32_e32 v83, 0xffff0000, v0
	s_waitcnt vmcnt(0)
	v_lshlrev_b32_e32 v80, 16, v8
	v_and_b32_e32 v81, 0xffff0000, v8
	v_pk_mul_f32 v[80:81], v[82:83], v[80:81]
	v_lshlrev_b32_e32 v8, 16, v9
	v_cvt_pk_bf16_f32 v0, v80, v81
	v_and_b32_e32 v9, 0xffff0000, v9
	v_lshlrev_b32_e32 v80, 16, v1
	v_and_b32_e32 v81, 0xffff0000, v1
	v_pk_mul_f32 v[8:9], v[80:81], v[8:9]
	v_lshlrev_b32_e32 v80, 16, v2
	v_cvt_pk_bf16_f32 v1, v8, v9
	v_lshlrev_b32_e32 v8, 16, v10
	v_and_b32_e32 v9, 0xffff0000, v10
	v_and_b32_e32 v81, 0xffff0000, v2
	v_pk_mul_f32 v[8:9], v[80:81], v[8:9]
	v_lshlrev_b32_e32 v10, 16, v3
	v_cvt_pk_bf16_f32 v2, v8, v9
	v_lshlrev_b32_e32 v8, 16, v11
	v_and_b32_e32 v9, 0xffff0000, v11
	v_and_b32_e32 v11, 0xffff0000, v3
	v_pk_mul_f32 v[8:9], v[10:11], v[8:9]
	s_nop 0
	v_cvt_pk_bf16_f32 v3, v8, v9
	v_lshl_add_u64 v[8:9], v[4:5], 0, v[54:55]
	global_store_dwordx4 v[8:9], v[0:3], off
	global_load_dwordx4 v[6:9], v[6:7], off
	v_lshl_add_u64 v[4:5], v[4:5], 0, v[58:59]
	v_or_b32_e32 v0, s1, v68
	v_mad_u64_u32 v[0:1], s[0:1], v0, s47, v[20:21]
	ds_read_b128 v[0:3], v0
	s_waitcnt lgkmcnt(0)
	v_lshlrev_b32_e32 v80, 16, v0
	v_and_b32_e32 v81, 0xffff0000, v0
	s_waitcnt vmcnt(0)
	v_lshlrev_b32_e32 v10, 16, v6
	v_and_b32_e32 v11, 0xffff0000, v6
	v_pk_mul_f32 v[10:11], v[80:81], v[10:11]
	v_lshlrev_b32_e32 v6, 16, v7
	v_cvt_pk_bf16_f32 v0, v10, v11
	v_and_b32_e32 v7, 0xffff0000, v7
	v_lshlrev_b32_e32 v10, 16, v1
	v_and_b32_e32 v11, 0xffff0000, v1
	v_pk_mul_f32 v[6:7], v[10:11], v[6:7]
	v_lshlrev_b32_e32 v10, 16, v2
	v_cvt_pk_bf16_f32 v1, v6, v7
	v_lshlrev_b32_e32 v6, 16, v8
	v_and_b32_e32 v7, 0xffff0000, v8
	v_and_b32_e32 v11, 0xffff0000, v2
	v_pk_mul_f32 v[6:7], v[10:11], v[6:7]
	v_lshlrev_b32_e32 v8, 16, v3
	v_cvt_pk_bf16_f32 v2, v6, v7
	v_lshlrev_b32_e32 v6, 16, v9
	v_and_b32_e32 v7, 0xffff0000, v9
	v_and_b32_e32 v9, 0xffff0000, v3
	v_pk_mul_f32 v[6:7], v[8:9], v[6:7]
	s_nop 0
	v_cvt_pk_bf16_f32 v3, v6, v7
	global_store_dwordx4 v[4:5], v[0:3], off
	s_barrier
	s_and_saveexec_b64 s[0:1], s[6:7]
	s_cbranch_execz .LBB0_397
	v_mov_b32_e32 v0, s46
	ds_write_b32 v0, v78
	s_branch .LBB0_397

; template <bool A_TR, bool B_TR>
; __device__ __forceinline__ void mm128(f32x4 (&acc)[8], ldsp TA, ldsp TB, int w, int lane) {
;     const ldsp ab = A_TR ? tr_base(TA, lane) + 32u * w : row_base(TA, lane) + 16u * TP * w;
;     const ldsp bb = B_TR ? tr_base(TB, lane) : row_base(TB, lane);
;     if (MM_SETPRIO) __builtin_amdgcn_s_setprio(1);
;     ...
;     bf16x8 a[4];
; #pragma unroll
;     for (int ks = 0; ks < 4; ++ks) a[ks] = A_TR ? frag_tr(ab, 0, ks) : frag_row(ab, 0, ks);
;     mm_pipe<MM_G, 0, 4, 0, 8>(acc, [&](int c, int ks) { return B_TR ? frag_tr(bb, c, ks) : frag_row(bb, c, ks); }, [&](int ks) { return a[ks]; });
;     ...
; #pragma unroll
;     for (int ks = 0; ks < 4; ++ks) {
;         const bf16x8 a = A_TR ? frag_tr(ab, 0, ks) : frag_row(ab, 0, ks);
; #pragma unroll
;         for (int c = 0; c < 8; ++c) {
;             const bf16x8 b = B_TR ? frag_tr(bb, c, ks) : frag_row(bb, c, ks);
;             acc[c] = __builtin_amdgcn_mfma_f32_16x16x32_bf16(b, a, acc[c], 0, 0, 0);
;         }
;     }
; __device__ __forceinline__ void retout_loop(ldsp lds, const bf16* proj, const bf16* st, bf16* mix, const float* ldr, int u0, int ustep, int nunits, int tid0) {
;     ...
;         const float wf = __builtin_amdgcn_exp2f(l2f * (float)(i + 1)), wb = __builtin_amdgcn_exp2f(l2b * (float)(CHUNK - i));
; #pragma unroll
;         for (int c = 0; c < 8; ++c) acc[c] = acc[c] * wb + accF[c] * wf;
;         asm volatile("" ::: "memory");
;         if (unext < nunits) retout_fetch(R, proj, st, unext, tid);
;         mm128<false, true>(acc, TK, TV, w, lane);
.LBB0_461:
	v_sub_u32_e32 v16, 0x80, v174
	v_cvt_f32_i32_e32 v16, v16
	v_add_u32_e32 v162, 1, v174
	v_cvt_f32_i32_e32 v162, v162
	v_and_b32_e32 v165, 63, v170
	v_mul_f32_e32 v16, v177, v16
	v_exp_f32_e32 v16, v16
	v_mul_f32_e32 v162, v175, v162
	v_exp_f32_e32 v166, v162
	v_or_b32_e32 v164, 4, v178
	v_pk_mul_f32 v[152:153], v[16:17], v[152:153] op_sel_hi:[0,1]
	v_pk_mul_f32 v[150:151], v[16:17], v[150:151] op_sel_hi:[0,1]
	v_pk_mul_f32 v[132:133], v[16:17], v[132:133] op_sel_hi:[0,1]
	v_pk_mul_f32 v[130:131], v[16:17], v[130:131] op_sel_hi:[0,1]
	v_pk_fma_f32 v[116:117], v[166:167], v[116:117], v[152:153] op_sel_hi:[0,1,1]
	v_pk_fma_f32 v[114:115], v[166:167], v[114:115], v[150:151] op_sel_hi:[0,1,1]
	v_pk_mul_f32 v[150:151], v[16:17], v[156:157] op_sel_hi:[0,1]
	v_pk_mul_f32 v[152:153], v[16:17], v[154:155] op_sel_hi:[0,1]
	v_pk_mul_f32 v[148:149], v[16:17], v[148:149] op_sel_hi:[0,1]
	v_pk_mul_f32 v[146:147], v[16:17], v[146:147] op_sel_hi:[0,1]
	v_pk_mul_f32 v[144:145], v[16:17], v[144:145] op_sel_hi:[0,1]
	v_pk_mul_f32 v[142:143], v[16:17], v[142:143] op_sel_hi:[0,1]
	v_pk_mul_f32 v[140:141], v[16:17], v[140:141] op_sel_hi:[0,1]
	v_pk_mul_f32 v[138:139], v[16:17], v[138:139] op_sel_hi:[0,1]
	v_pk_mul_f32 v[136:137], v[16:17], v[136:137] op_sel_hi:[0,1]
	v_pk_mul_f32 v[134:135], v[16:17], v[134:135] op_sel_hi:[0,1]
	v_pk_fma_f32 v[100:101], v[166:167], v[100:101], v[132:133] op_sel_hi:[0,1,1]
	v_pk_fma_f32 v[98:99], v[166:167], v[98:99], v[130:131] op_sel_hi:[0,1,1]
	v_pk_mul_f32 v[130:131], v[16:17], v[160:161] op_sel_hi:[0,1]
	v_pk_mul_f32 v[132:133], v[16:17], v[158:159] op_sel_hi:[0,1]
	v_bfe_u32 v16, v170, 2, 2
	v_pk_fma_f32 v[128:129], v[166:167], v[128:129], v[130:131] op_sel_hi:[0,1,1]
	v_and_or_b32 v16, v180, 24, v16
	v_lshlrev_b32_e32 v130, 3, v165
	v_mul_u32_u24_e32 v16, 0x110, v16
	v_and_b32_e32 v130, 24, v130
	v_or_b32_e32 v163, 8, v178
	v_or_b32_e32 v162, 12, v178
	v_pk_fma_f32 v[124:125], v[166:167], v[124:125], v[150:151] op_sel_hi:[0,1,1]
	v_pk_fma_f32 v[122:123], v[166:167], v[122:123], v[152:153] op_sel_hi:[0,1,1]
	v_pk_fma_f32 v[120:121], v[166:167], v[120:121], v[148:149] op_sel_hi:[0,1,1]
	v_pk_fma_f32 v[118:119], v[166:167], v[118:119], v[146:147] op_sel_hi:[0,1,1]
	v_pk_fma_f32 v[112:113], v[166:167], v[112:113], v[144:145] op_sel_hi:[0,1,1]
	v_pk_fma_f32 v[110:111], v[166:167], v[110:111], v[142:143] op_sel_hi:[0,1,1]
	v_pk_fma_f32 v[108:109], v[166:167], v[108:109], v[140:141] op_sel_hi:[0,1,1]
	v_pk_fma_f32 v[106:107], v[166:167], v[106:107], v[138:139] op_sel_hi:[0,1,1]
	v_pk_fma_f32 v[104:105], v[166:167], v[104:105], v[136:137] op_sel_hi:[0,1,1]
	v_pk_fma_f32 v[102:103], v[166:167], v[102:103], v[134:135] op_sel_hi:[0,1,1]
	v_pk_fma_f32 v[126:127], v[166:167], v[126:127], v[132:133] op_sel_hi:[0,1,1]
	v_add3_u32 v16, s33, v16, v130
	s_setprio 1
	ds_read_b128 v[180:183], v176 offset:34816
	ds_read_b64_tr_b16 v[186:187], v16 offset:1088
	ds_read_b64_tr_b16 v[184:185], v16
	ds_read_b64_tr_b16 v[188:189], v16 offset:64
	ds_read_b64_tr_b16 v[190:191], v16 offset:1152
	ds_read_b64_tr_b16 v[192:193], v16 offset:96
	ds_read_b64_tr_b16 v[194:195], v16 offset:1184
	ds_read_b64_tr_b16 v[196:197], v16 offset:128
	ds_read_b64_tr_b16 v[198:199], v16 offset:1216
	ds_read_b64_tr_b16 v[200:201], v16 offset:160
	ds_read_b64_tr_b16 v[202:203], v16 offset:1248
	ds_read_b64_tr_b16 v[204:205], v16 offset:192
	ds_read_b64_tr_b16 v[206:207], v16 offset:1280
	ds_read_b64_tr_b16 v[212:213], v16 offset:32
	ds_read_b64_tr_b16 v[214:215], v16 offset:1120
	ds_read_b64_tr_b16 v[216:217], v16 offset:224
	ds_read_b64_tr_b16 v[218:219], v16 offset:1312
	s_waitcnt lgkmcnt(14)
	v_mfma_f32_16x16x32_bf16 v[114:117], v[184:187], v[180:183], v[114:117]
	ds_read_b128 v[220:223], v176 offset:34880
	s_waitcnt lgkmcnt(13)
	v_mfma_f32_16x16x32_bf16 v[118:121], v[188:191], v[180:183], v[118:121]
	ds_read_b64_tr_b16 v[236:237], v16 offset:8704
	ds_read_b64_tr_b16 v[238:239], v16 offset:9792
	s_waitcnt lgkmcnt(13)
	v_mfma_f32_16x16x32_bf16 v[110:113], v[192:195], v[180:183], v[110:113]
	ds_read_b64_tr_b16 v[184:185], v16 offset:8736
	ds_read_b64_tr_b16 v[186:187], v16 offset:9824
	s_waitcnt lgkmcnt(13)
	v_mfma_f32_16x16x32_bf16 v[106:109], v[196:199], v[180:183], v[106:109]
	ds_read_b64_tr_b16 v[188:189], v16 offset:8768
	ds_read_b64_tr_b16 v[190:191], v16 offset:9856
	s_waitcnt lgkmcnt(13)
	v_mfma_f32_16x16x32_bf16 v[102:105], v[200:203], v[180:183], v[102:105]
	ds_read_b64_tr_b16 v[192:193], v16 offset:8800
	ds_read_b64_tr_b16 v[194:195], v16 offset:9888
	s_waitcnt lgkmcnt(13)
	v_mfma_f32_16x16x32_bf16 v[98:101], v[204:207], v[180:183], v[98:101]
	ds_read_b64_tr_b16 v[196:197], v16 offset:8832
	ds_read_b64_tr_b16 v[198:199], v16 offset:9920
	s_waitcnt lgkmcnt(13)
	v_mfma_f32_16x16x32_bf16 v[122:125], v[212:215], v[180:183], v[122:125]
	ds_read_b64_tr_b16 v[200:201], v16 offset:8864
	ds_read_b64_tr_b16 v[202:203], v16 offset:9952
	s_waitcnt lgkmcnt(13)
	v_mfma_f32_16x16x32_bf16 v[126:129], v[216:219], v[180:183], v[126:129]
	ds_read_b64_tr_b16 v[204:205], v16 offset:8896
	ds_read_b64_tr_b16 v[206:207], v16 offset:9984
	ds_read_b64_tr_b16 v[212:213], v16 offset:8928
	ds_read_b64_tr_b16 v[214:215], v16 offset:10016
	s_waitcnt lgkmcnt(14)
	v_mfma_f32_16x16x32_bf16 v[114:117], v[236:239], v[220:223], v[114:117]
	ds_read_b128 v[216:219], v176 offset:34944
	s_waitcnt lgkmcnt(13)
	v_mfma_f32_16x16x32_bf16 v[122:125], v[184:187], v[220:223], v[122:125]
	ds_read_b64_tr_b16 v[180:181], v16 offset:17408
	ds_read_b64_tr_b16 v[182:183], v16 offset:18496
	s_waitcnt lgkmcnt(13)
; __device__ __forceinline__ void retout_loop(ldsp lds, const bf16* proj, const bf16* st, bf16* mix, const float* ldr, int u0, int ustep, int nunits, int tid0) {
;     ...
;         mm128<false, true>(acc, TK, TV, w, lane);
;         float ss = 0.f;
; #pragma unroll
;         for (int c = 0; c < 8; ++c) ss += (acc[c][0] * acc[c][0] + acc[c][1] * acc[c][1]) + (acc[c][2] * acc[c][2] + acc[c][3] * acc[c][3]);
;         ss += __shfl_xor(ss, 16); ss += __shfl_xor(ss, 32);
;         const float rn = rsqrtf(ss * (1.f / 128.f) + NORM_EPS);
	v_mfma_f32_16x16x32_bf16 v[118:121], v[188:191], v[220:223], v[118:121]
	ds_read_b64_tr_b16 v[236:237], v16 offset:17440
	ds_read_b64_tr_b16 v[238:239], v16 offset:18528
	s_waitcnt lgkmcnt(13)
	v_mfma_f32_16x16x32_bf16 v[110:113], v[192:195], v[220:223], v[110:113]
	ds_read_b64_tr_b16 v[184:185], v16 offset:17472
	ds_read_b64_tr_b16 v[186:187], v16 offset:18560
	s_waitcnt lgkmcnt(13)
	v_mfma_f32_16x16x32_bf16 v[106:109], v[196:199], v[220:223], v[106:109]
	ds_read_b64_tr_b16 v[188:189], v16 offset:17504
	ds_read_b64_tr_b16 v[190:191], v16 offset:18592
	s_waitcnt lgkmcnt(13)
	v_mfma_f32_16x16x32_bf16 v[102:105], v[200:203], v[220:223], v[102:105]
	ds_read_b64_tr_b16 v[192:193], v16 offset:17536
	ds_read_b64_tr_b16 v[194:195], v16 offset:18624
	s_waitcnt lgkmcnt(13)
	v_mfma_f32_16x16x32_bf16 v[98:101], v[204:207], v[220:223], v[98:101]
	ds_read_b64_tr_b16 v[196:197], v16 offset:17568
	ds_read_b64_tr_b16 v[198:199], v16 offset:18656
	s_waitcnt lgkmcnt(13)
	v_mfma_f32_16x16x32_bf16 v[126:129], v[212:215], v[220:223], v[126:129]
	ds_read_b64_tr_b16 v[200:201], v16 offset:17600
	ds_read_b64_tr_b16 v[202:203], v16 offset:18688
	ds_read_b64_tr_b16 v[204:205], v16 offset:17632
	ds_read_b64_tr_b16 v[206:207], v16 offset:18720
	s_waitcnt lgkmcnt(14)
	v_mfma_f32_16x16x32_bf16 v[114:117], v[180:183], v[216:219], v[114:117]
	ds_read_b128 v[212:215], v176 offset:35008
	s_waitcnt lgkmcnt(13)
	v_mfma_f32_16x16x32_bf16 v[122:125], v[236:239], v[216:219], v[122:125]
	ds_read_b64_tr_b16 v[220:221], v16 offset:26112
	ds_read_b64_tr_b16 v[222:223], v16 offset:27200
	s_waitcnt lgkmcnt(13)
	v_mfma_f32_16x16x32_bf16 v[118:121], v[184:187], v[216:219], v[118:121]
	ds_read_b64_tr_b16 v[180:181], v16 offset:26144
	ds_read_b64_tr_b16 v[182:183], v16 offset:27232
	s_waitcnt lgkmcnt(13)
	v_mfma_f32_16x16x32_bf16 v[110:113], v[188:191], v[216:219], v[110:113]
	ds_read_b64_tr_b16 v[236:237], v16 offset:26176
	ds_read_b64_tr_b16 v[238:239], v16 offset:27264
	s_waitcnt lgkmcnt(13)
	v_mfma_f32_16x16x32_bf16 v[106:109], v[192:195], v[216:219], v[106:109]
	ds_read_b64_tr_b16 v[184:185], v16 offset:26208
	ds_read_b64_tr_b16 v[186:187], v16 offset:27296
	s_waitcnt lgkmcnt(13)
	v_mfma_f32_16x16x32_bf16 v[102:105], v[196:199], v[216:219], v[102:105]
	ds_read_b64_tr_b16 v[188:189], v16 offset:26240
	ds_read_b64_tr_b16 v[190:191], v16 offset:27328
	s_waitcnt lgkmcnt(13)
	v_mfma_f32_16x16x32_bf16 v[98:101], v[200:203], v[216:219], v[98:101]
	ds_read_b64_tr_b16 v[192:193], v16 offset:26272
	ds_read_b64_tr_b16 v[194:195], v16 offset:27360
	s_waitcnt lgkmcnt(13)
	v_mfma_f32_16x16x32_bf16 v[126:129], v[204:207], v[216:219], v[126:129]
	ds_read_b64_tr_b16 v[196:197], v16 offset:26304
	ds_read_b64_tr_b16 v[198:199], v16 offset:27392
	ds_read_b64_tr_b16 v[200:201], v16 offset:26336
	ds_read_b64_tr_b16 v[202:203], v16 offset:27424
	s_waitcnt lgkmcnt(14)
	v_mfma_f32_16x16x32_bf16 v[114:117], v[220:223], v[212:215], v[114:117]
	s_waitcnt lgkmcnt(12)
	v_mfma_f32_16x16x32_bf16 v[122:125], v[180:183], v[212:215], v[122:125]
	s_waitcnt lgkmcnt(10)
	v_mfma_f32_16x16x32_bf16 v[118:121], v[236:239], v[212:215], v[118:121]
	s_waitcnt lgkmcnt(8)
	v_mfma_f32_16x16x32_bf16 v[110:113], v[184:187], v[212:215], v[110:113]
	s_waitcnt lgkmcnt(6)
	v_mfma_f32_16x16x32_bf16 v[106:109], v[188:191], v[212:215], v[106:109]
	s_waitcnt lgkmcnt(4)
	v_mfma_f32_16x16x32_bf16 v[102:105], v[192:195], v[212:215], v[102:105]
	s_waitcnt lgkmcnt(2)
	v_mfma_f32_16x16x32_bf16 v[98:101], v[196:199], v[212:215], v[98:101]
	s_waitcnt lgkmcnt(0)
	v_mfma_f32_16x16x32_bf16 v[126:129], v[200:203], v[212:215], v[126:129]
	s_nop 7
	s_setprio 0
	v_mov_b32_e32 v132, v115
	v_mov_b32_e32 v133, v123
	v_mov_b32_e32 v130, v114
	v_mov_b32_e32 v131, v122
	v_pk_mul_f32 v[132:133], v[132:133], v[132:133]
	v_mov_b32_e32 v134, v117
	v_mov_b32_e32 v135, v125
	v_pk_fma_f32 v[130:131], v[130:131], v[130:131], v[132:133]
	v_mov_b32_e32 v132, v116
	v_mov_b32_e32 v133, v124
	v_pk_mul_f32 v[134:135], v[134:135], v[134:135]
	v_mul_f32_e32 v16, v106, v106
	v_pk_fma_f32 v[132:133], v[132:133], v[132:133], v[134:135]
	v_pk_mul_f32 v[134:135], v[118:119], v[118:119]
	v_pk_add_f32 v[130:131], v[130:131], v[132:133]
	v_pk_mul_f32 v[132:133], v[120:121], v[120:121]
	v_pk_add_f32 v[130:131], v[130:131], v[130:131] op_sel:[0,1] op_sel_hi:[1,0]
	v_pk_mov_b32 v[136:137], v[134:135], v[132:133] op_sel:[1,0]
	v_mov_b32_e32 v135, v133
	v_pk_add_f32 v[132:133], v[136:137], v[134:135]
	v_mul_f32_e32 v134, v107, v107
	v_pk_add_f32 v[132:133], v[132:133], v[132:133] op_sel:[0,1] op_sel_hi:[1,0]
	v_mov_b32_e32 v131, v16
	v_mov_b32_e32 v133, v134
	v_mul_f32_e32 v16, v111, v111
	v_mul_f32_e32 v135, v108, v108
	v_pk_add_f32 v[130:131], v[130:131], v[132:133]
	v_pk_fma_f32 v[132:133], v[110:111], v[110:111], v[16:17] op_sel_hi:[1,1,0]
	v_mul_f32_e32 v16, v113, v113
	v_mul_f32_e32 v136, v109, v109
	v_mov_b32_e32 v133, v135
	v_pk_fma_f32 v[134:135], v[112:113], v[112:113], v[16:17] op_sel_hi:[1,1,0]
	v_mul_f32_e32 v16, v126, v126
	v_mov_b32_e32 v135, v136
	v_pk_add_f32 v[132:133], v[132:133], v[134:135]
	v_pk_mul_f32 v[134:135], v[102:103], v[102:103]
	v_pk_add_f32 v[130:131], v[130:131], v[132:133]
	v_pk_mul_f32 v[132:133], v[104:105], v[104:105]
	v_pk_add_f32 v[130:131], v[130:131], v[130:131] op_sel:[0,1] op_sel_hi:[1,0]
	v_pk_mov_b32 v[136:137], v[134:135], v[132:133] op_sel:[1,0]
	v_mov_b32_e32 v135, v133
	v_pk_add_f32 v[132:133], v[136:137], v[134:135]
	v_mul_f32_e32 v134, v127, v127
	v_pk_add_f32 v[132:133], v[132:133], v[132:133] op_sel:[0,1] op_sel_hi:[1,0]
	v_mov_b32_e32 v131, v16
	v_mov_b32_e32 v133, v134
	v_mul_f32_e32 v16, v99, v99
	v_mul_f32_e32 v135, v128, v128
	v_pk_add_f32 v[130:131], v[130:131], v[132:133]
	v_pk_fma_f32 v[132:133], v[98:99], v[98:99], v[16:17] op_sel_hi:[1,1,0]
	v_mul_f32_e32 v16, v101, v101
	v_mul_f32_e32 v136, v129, v129
	v_mov_b32_e32 v133, v135
	v_pk_fma_f32 v[134:135], v[100:101], v[100:101], v[16:17] op_sel_hi:[1,1,0]
	s_mov_b32 s5, 0x800000
	v_mov_b32_e32 v135, v136
	v_pk_add_f32 v[132:133], v[132:133], v[134:135]
	s_lshl_b64 s[8:9], s[8:9], 13
	v_pk_add_f32 v[130:131], v[130:131], v[132:133]
	s_nop 0
	v_add_f32_e32 v16, v130, v131
	ds_bpermute_b32 v130, v171, v16
	s_waitcnt lgkmcnt(0)
; __device__ __forceinline__ unsigned cvt_pk_bf16(float lo, float hi) { const f32x2c_t v = {lo, hi}; return __builtin_bit_cast(unsigned, __builtin_convertvector(v, bf16x2c_t)); }
; #define LAS __attribute__((address_space(3)))
; #define LDS_WAIT() asm volatile("s_waitcnt lgkmcnt(0)" ::: "memory")
; __device__ __forceinline__ float bf_lo(unsigned w) { return __uint_as_float(w << 16); }
; __device__ __forceinline__ float bf_hi(unsigned w) { return __uint_as_float(w & 0xffff0000u); }
; __device__ __forceinline__ void retout_loop(ldsp lds, const bf16* proj, const bf16* st, bf16* mix, const float* ldr, int u0, int ustep, int nunits, int tid0) {
;     ...
;         ss += __shfl_xor(ss, 16); ss += __shfl_xor(ss, 32);
;         const float rn = rsqrtf(ss * (1.f / 128.f) + NORM_EPS);
; #pragma unroll
;         for (int c = 0; c < 8; ++c) acc[c] = acc[c] * rn;
;         store_acc_tile(TK, acc, w, lane);
;         LDS_WAIT();
;         bf16* obase = mix + (row0 + 16 * w) * DM + MIX_R + h * HDIM;
; #pragma unroll
;         for (int k = 0; k < 4; ++k) { const int q = lane + 64 * k, r = q >> 4, ch = q & 15;
;             const v4u s = *(const LAS v4u*)(TK + offb(16 * w + r, ch)), gw = gr[k];
;             v4u o;
; #pragma unroll
;             for (int e = 0; e < 4; ++e) { const float g0 = bf_lo(gw[e]), g1 = bf_hi(gw[e]);
;                 o[e] = cvt_pk_bf16(g0 / (1.f + __expf(-g0)) * bf_lo(s[e]), g1 / (1.f + __expf(-g1)) * bf_hi(s[e])); }
;             *(v4u*)(obase + (size_t)r * DM + 8 * ch) = o; }
	v_add_f32_e32 v16, v16, v130
	ds_bpermute_b32 v130, v172, v16
	s_waitcnt lgkmcnt(0)
	v_add_f32_e32 v16, v16, v130
	v_fmamk_f32 v16, v16, 0x3c000000, v234
	v_mul_f32_e32 v130, 0x4b800000, v16
	v_cmp_gt_f32_e32 vcc, s5, v16
	s_add_u32 s5, s60, s8
	s_addc_u32 s9, s61, s9
	v_cndmask_b32_e32 v16, v16, v130, vcc
	v_rsq_f32_e32 v16, v16
	s_lshl_b32 s8, s10, 1
	s_add_u32 s8, s5, s8
	s_addc_u32 s9, s9, 0
	v_mul_f32_e32 v130, 0x45800000, v16
	v_cndmask_b32_e32 v16, v16, v130, vcc
	v_pk_mul_f32 v[108:109], v[108:109], v[16:17] op_sel_hi:[1,0]
	v_pk_mul_f32 v[106:107], v[106:107], v[16:17] op_sel_hi:[1,0]
	v_pk_mul_f32 v[100:101], v[100:101], v[16:17] op_sel_hi:[1,0]
	v_pk_mul_f32 v[98:99], v[98:99], v[16:17] op_sel_hi:[1,0]
	v_pk_mul_f32 v[128:129], v[128:129], v[16:17] op_sel_hi:[1,0]
	v_pk_mul_f32 v[126:127], v[126:127], v[16:17] op_sel_hi:[1,0]
	v_cvt_pk_bf16_f32 v106, v106, v107
	v_cvt_pk_bf16_f32 v107, v108, v109
	v_cvt_pk_bf16_f32 v98, v98, v99
	v_cvt_pk_bf16_f32 v99, v100, v101
	v_cvt_pk_bf16_f32 v100, v126, v127
	v_cvt_pk_bf16_f32 v101, v128, v129
	s_waitcnt vmcnt(3)
	v_lshlrev_b32_e32 v109, 16, v94
	v_and_b32_e32 v94, 0xffff0000, v94
	ds_write2_b64 v179, v[98:99], v[100:101] offset0:24 offset1:28
	v_mul_f32_e32 v98, 0xbfb8aa3b, v109
	v_mul_f32_e32 v99, 0xbfb8aa3b, v94
	v_exp_f32_e32 v98, v98
	v_exp_f32_e32 v99, v99
	v_pk_mul_f32 v[116:117], v[116:117], v[16:17] op_sel_hi:[1,0]
	v_pk_mul_f32 v[114:115], v[114:115], v[16:17] op_sel_hi:[1,0]
	v_pk_mul_f32 v[124:125], v[124:125], v[16:17] op_sel_hi:[1,0]
	v_pk_mul_f32 v[122:123], v[122:123], v[16:17] op_sel_hi:[1,0]
	v_pk_mul_f32 v[120:121], v[120:121], v[16:17] op_sel_hi:[1,0]
	v_pk_mul_f32 v[118:119], v[118:119], v[16:17] op_sel_hi:[1,0]
	v_pk_mul_f32 v[112:113], v[112:113], v[16:17] op_sel_hi:[1,0]
	v_pk_mul_f32 v[110:111], v[110:111], v[16:17] op_sel_hi:[1,0]
	v_pk_mul_f32 v[104:105], v[104:105], v[16:17] op_sel_hi:[1,0]
	v_pk_mul_f32 v[102:103], v[102:103], v[16:17] op_sel_hi:[1,0]
	v_cvt_pk_bf16_f32 v114, v114, v115
	v_cvt_pk_bf16_f32 v115, v116, v117
	v_cvt_pk_bf16_f32 v116, v122, v123
	v_cvt_pk_bf16_f32 v117, v124, v125
	ds_write2_b64 v179, v[114:115], v[116:117] offset1:4
	v_cvt_pk_bf16_f32 v114, v118, v119
	v_cvt_pk_bf16_f32 v115, v120, v121
	v_cvt_pk_bf16_f32 v110, v110, v111
	v_cvt_pk_bf16_f32 v111, v112, v113
	v_cvt_pk_bf16_f32 v102, v102, v103
	v_cvt_pk_bf16_f32 v103, v104, v105
	v_lshlrev_b32_e32 v16, 4, v173
	v_pk_add_f32 v[98:99], v[98:99], 1.0 op_sel_hi:[1,0]
	ds_write2_b64 v179, v[114:115], v[110:111] offset0:8 offset1:12
	ds_write2_b64 v179, v[106:107], v[102:103] offset0:16 offset1:20
	v_lshl_add_u64 v[106:107], s[8:9], 0, v[16:17]
	v_div_scale_f32 v110, s[8:9], v99, v99, v94
	v_rcp_f32_e32 v111, v110
	v_add_u32_e32 v108, 0, v16
	v_or_b32_e32 v16, s4, v178
	v_mad_u64_u32 v[100:101], s[8:9], v16, s47, v[108:109]
	v_fma_f32 v16, -v110, v111, 1.0
	s_waitcnt lgkmcnt(0)
	v_fmac_f32_e32 v111, v16, v111
	v_div_scale_f32 v16, vcc, v94, v99, v94
	ds_read_b128 v[102:105], v100 offset:34816
	v_mul_f32_e32 v100, v16, v111
	v_fma_f32 v101, -v110, v100, v16
	v_fmac_f32_e32 v100, v101, v111
	v_div_scale_f32 v101, s[8:9], v98, v98, v109
	v_fma_f32 v16, -v110, v100, v16
	v_rcp_f32_e32 v110, v101
	v_div_fmas_f32 v16, v16, v111, v100
	v_div_fixup_f32 v111, v16, v99, v94
	s_waitcnt lgkmcnt(0)
	v_lshlrev_b32_e32 v112, 16, v102
	v_fma_f32 v16, -v101, v110, 1.0
	v_fmac_f32_e32 v110, v16, v110
	v_div_scale_f32 v16, vcc, v109, v98, v109
	v_mul_f32_e32 v94, v16, v110
	v_fma_f32 v99, -v101, v94, v16
	v_fmac_f32_e32 v94, v99, v110
	v_fma_f32 v16, -v101, v94, v16
	v_div_fmas_f32 v16, v16, v110, v94
	v_div_fixup_f32 v110, v16, v98, v109
	v_lshlrev_b32_e32 v16, 16, v95
	v_and_b32_e32 v109, 0xffff0000, v95
	v_mul_f32_e32 v94, 0xbfb8aa3b, v16
	v_mul_f32_e32 v95, 0xbfb8aa3b, v109
	v_exp_f32_e32 v94, v94
	v_exp_f32_e32 v95, v95
	v_and_b32_e32 v113, 0xffff0000, v102
	v_or_b32_e32 v98, s4, v164
	v_mad_u64_u32 v[98:99], s[8:9], v98, s47, v[108:109]
	v_pk_add_f32 v[114:115], v[94:95], 1.0 op_sel_hi:[1,0]
	v_pk_mul_f32 v[94:95], v[110:111], v[112:113]
	v_div_scale_f32 v116, s[8:9], v115, v115, v109
	v_rcp_f32_e32 v117, v116
	v_cvt_pk_bf16_f32 v94, v94, v95
	ds_read_b128 v[98:101], v98 offset:34816
	v_fma_f32 v95, -v116, v117, 1.0
	v_fmac_f32_e32 v117, v95, v117
	v_div_scale_f32 v95, vcc, v109, v115, v109
	v_mul_f32_e32 v102, v95, v117
	v_fma_f32 v110, -v116, v102, v95
	v_fmac_f32_e32 v102, v110, v117
	v_div_scale_f32 v110, s[8:9], v114, v114, v16
	v_fma_f32 v95, -v116, v102, v95
	v_rcp_f32_e32 v116, v110
	v_div_fmas_f32 v95, v95, v117, v102
	v_div_fixup_f32 v111, v95, v115, v109
	v_and_b32_e32 v115, 0xffff0000, v97
	v_fma_f32 v95, -v110, v116, 1.0
	v_fmac_f32_e32 v116, v95, v116
	v_div_scale_f32 v95, vcc, v16, v114, v16
	v_mul_f32_e32 v102, v95, v116
	v_fma_f32 v109, -v110, v102, v95
	v_fmac_f32_e32 v102, v109, v116
	v_lshlrev_b32_e32 v109, 16, v96
	v_fma_f32 v95, -v110, v102, v95
	v_and_b32_e32 v96, 0xffff0000, v96
	v_mul_f32_e32 v110, 0xbfb8aa3b, v109
	v_exp_f32_e32 v112, v110
	v_mul_f32_e32 v110, 0xbfb8aa3b, v96
	v_exp_f32_e32 v113, v110
	v_div_fmas_f32 v95, v95, v116, v102
	v_div_fixup_f32 v110, v95, v114, v16
	v_lshlrev_b32_e32 v102, 16, v103
	v_pk_add_f32 v[112:113], v[112:113], 1.0 op_sel_hi:[1,0]
	v_and_b32_e32 v103, 0xffff0000, v103
	v_div_scale_f32 v16, s[8:9], v113, v113, v96
	v_rcp_f32_e32 v114, v16
	v_pk_mul_f32 v[102:103], v[110:111], v[102:103]
	s_nop 0
	v_cvt_pk_bf16_f32 v95, v102, v103
	v_fma_f32 v102, -v16, v114, 1.0
	v_fmac_f32_e32 v114, v102, v114
	v_div_scale_f32 v102, vcc, v96, v113, v96
	v_mul_f32_e32 v103, v102, v114
	v_fma_f32 v110, -v16, v103, v102
	v_fmac_f32_e32 v103, v110, v114
; __device__ __forceinline__ unsigned cvt_pk_bf16(float lo, float hi) { const f32x2c_t v = {lo, hi}; return __builtin_bit_cast(unsigned, __builtin_convertvector(v, bf16x2c_t)); }
; #define LAS __attribute__((address_space(3)))
; __device__ __forceinline__ float bf_lo(unsigned w) { return __uint_as_float(w << 16); }
; __device__ __forceinline__ float bf_hi(unsigned w) { return __uint_as_float(w & 0xffff0000u); }
; __device__ __forceinline__ void retout_loop(ldsp lds, const bf16* proj, const bf16* st, bf16* mix, const float* ldr, int u0, int ustep, int nunits, int tid0) {
;     ...
;         for (int k = 0; k < 4; ++k) { const int q = lane + 64 * k, r = q >> 4, ch = q & 15;
;             const v4u s = *(const LAS v4u*)(TK + offb(16 * w + r, ch)), gw = gr[k];
;             v4u o;
; #pragma unroll
;             for (int e = 0; e < 4; ++e) { const float g0 = bf_lo(gw[e]), g1 = bf_hi(gw[e]);
;                 o[e] = cvt_pk_bf16(g0 / (1.f + __expf(-g0)) * bf_lo(s[e]), g1 / (1.f + __expf(-g1)) * bf_hi(s[e])); }
;             *(v4u*)(obase + (size_t)r * DM + 8 * ch) = o; }
	v_fma_f32 v16, -v16, v103, v102
	v_div_scale_f32 v102, s[8:9], v112, v112, v109
	v_rcp_f32_e32 v110, v102
	v_div_fmas_f32 v16, v16, v114, v103
	v_div_fixup_f32 v103, v16, v113, v96
	v_lshlrev_b32_e32 v114, 16, v97
	v_fma_f32 v16, -v102, v110, 1.0
	v_fmac_f32_e32 v110, v16, v110
	v_div_scale_f32 v16, vcc, v109, v112, v109
	v_mul_f32_e32 v111, v16, v110
	v_fma_f32 v96, -v102, v111, v16
	v_fmac_f32_e32 v111, v96, v110
	v_mul_f32_e32 v96, 0xbfb8aa3b, v114
	v_mul_f32_e32 v97, 0xbfb8aa3b, v115
	v_exp_f32_e32 v96, v96
	v_exp_f32_e32 v97, v97
	v_fma_f32 v16, -v102, v111, v16
	v_div_fmas_f32 v16, v16, v110, v111
	v_div_fixup_f32 v102, v16, v112, v109
	v_pk_add_f32 v[112:113], v[96:97], 1.0 op_sel_hi:[1,0]
	v_lshlrev_b32_e32 v110, 16, v104
	v_div_scale_f32 v16, s[8:9], v113, v113, v115
	v_rcp_f32_e32 v109, v16
	v_and_b32_e32 v111, 0xffff0000, v104
	v_pk_mul_f32 v[96:97], v[102:103], v[110:111]
	s_nop 0
	v_cvt_pk_bf16_f32 v96, v96, v97
	v_fma_f32 v97, -v16, v109, 1.0
	v_fmac_f32_e32 v109, v97, v109
	v_div_scale_f32 v97, vcc, v115, v113, v115
	v_mul_f32_e32 v102, v97, v109
	v_fma_f32 v103, -v16, v102, v97
	v_fmac_f32_e32 v102, v103, v109
	v_fma_f32 v16, -v16, v102, v97
	v_div_scale_f32 v97, s[8:9], v112, v112, v114
	v_rcp_f32_e32 v104, v97
	v_div_fmas_f32 v16, v16, v109, v102
	v_div_fixup_f32 v103, v16, v113, v115
	v_fma_f32 v16, -v97, v104, 1.0
	v_fmac_f32_e32 v104, v16, v104
	v_div_scale_f32 v16, vcc, v114, v112, v114
	v_mul_f32_e32 v102, v16, v104
	v_fma_f32 v109, -v97, v102, v16
	v_fmac_f32_e32 v102, v109, v104
	v_fma_f32 v16, -v97, v102, v16
	v_div_fmas_f32 v16, v16, v104, v102
	s_waitcnt vmcnt(2)
	v_lshlrev_b32_e32 v109, 16, v90
	v_div_fixup_f32 v102, v16, v112, v114
	v_and_b32_e32 v90, 0xffff0000, v90
	v_mul_f32_e32 v16, 0xbfb8aa3b, v109
	v_exp_f32_e32 v110, v16
	v_mul_f32_e32 v16, 0xbfb8aa3b, v90
	v_exp_f32_e32 v111, v16
	v_lshlrev_b32_e32 v104, 16, v105
	v_and_b32_e32 v105, 0xffff0000, v105
	v_pk_mul_f32 v[102:103], v[102:103], v[104:105]
	v_lshlrev_b32_e32 v16, 13, v178
	v_cvt_pk_bf16_f32 v97, v102, v103
	v_pk_add_f32 v[102:103], v[110:111], 1.0 op_sel_hi:[1,0]
	v_lshl_add_u64 v[104:105], v[106:107], 0, v[16:17]
	v_div_scale_f32 v110, s[8:9], v103, v103, v90
	v_rcp_f32_e32 v111, v110
	global_store_dwordx4 v[104:105], v[94:97], off offset:2048
	v_lshlrev_b32_e32 v104, 16, v91
	v_and_b32_e32 v105, 0xffff0000, v91
	v_fma_f32 v16, -v110, v111, 1.0
	v_fmac_f32_e32 v111, v16, v111
	v_div_scale_f32 v16, vcc, v90, v103, v90
	v_mul_f32_e32 v94, v16, v111
	v_div_scale_f32 v96, s[8:9], v102, v102, v109
	v_fma_f32 v95, -v110, v94, v16
	v_rcp_f32_e32 v97, v96
	v_fmac_f32_e32 v94, v95, v111
	v_fma_f32 v16, -v110, v94, v16
	v_div_fmas_f32 v16, v16, v111, v94
	v_div_fixup_f32 v95, v16, v103, v90
	v_fma_f32 v16, -v96, v97, 1.0
	v_fmac_f32_e32 v97, v16, v97
	v_div_scale_f32 v16, vcc, v109, v102, v109
	v_mul_f32_e32 v94, v16, v97
	v_fma_f32 v90, -v96, v94, v16
	v_fmac_f32_e32 v94, v90, v97
	v_mul_f32_e32 v90, 0xbfb8aa3b, v104
	v_mul_f32_e32 v91, 0xbfb8aa3b, v105
	v_exp_f32_e32 v90, v90
	v_exp_f32_e32 v91, v91
	v_fma_f32 v16, -v96, v94, v16
	v_div_fmas_f32 v16, v16, v97, v94
	v_div_fixup_f32 v94, v16, v102, v109
	v_pk_add_f32 v[102:103], v[90:91], 1.0 op_sel_hi:[1,0]
	s_waitcnt lgkmcnt(0)
	v_lshlrev_b32_e32 v96, 16, v98
	v_div_scale_f32 v16, s[8:9], v103, v103, v105
	v_rcp_f32_e32 v109, v16
	v_and_b32_e32 v97, 0xffff0000, v98
	v_pk_mul_f32 v[90:91], v[94:95], v[96:97]
	s_nop 0
	v_cvt_pk_bf16_f32 v90, v90, v91
	v_fma_f32 v91, -v16, v109, 1.0
	v_fmac_f32_e32 v109, v91, v109
	v_div_scale_f32 v91, vcc, v105, v103, v105
	v_mul_f32_e32 v94, v91, v109
	v_fma_f32 v95, -v16, v94, v91
	v_fmac_f32_e32 v94, v95, v109
	v_fma_f32 v16, -v16, v94, v91
	v_div_scale_f32 v91, s[8:9], v102, v102, v104
	v_rcp_f32_e32 v98, v91
	v_div_fmas_f32 v16, v16, v109, v94
	v_div_fixup_f32 v95, v16, v103, v105
	v_lshlrev_b32_e32 v103, 16, v92
	v_fma_f32 v16, -v91, v98, 1.0
	v_fmac_f32_e32 v98, v16, v98
	v_div_scale_f32 v16, vcc, v104, v102, v104
	v_mul_f32_e32 v94, v16, v98
	v_fma_f32 v96, -v91, v94, v16
	v_fmac_f32_e32 v94, v96, v98
	v_fma_f32 v16, -v91, v94, v16
	v_and_b32_e32 v92, 0xffff0000, v92
	v_mul_f32_e32 v91, 0xbfb8aa3b, v103
	v_exp_f32_e32 v96, v91
	v_mul_f32_e32 v91, 0xbfb8aa3b, v92
	v_exp_f32_e32 v97, v91
	v_div_fmas_f32 v16, v16, v98, v94
	v_div_fixup_f32 v94, v16, v102, v104
	v_lshlrev_b32_e32 v98, 16, v99
	v_pk_add_f32 v[96:97], v[96:97], 1.0 op_sel_hi:[1,0]
	v_and_b32_e32 v99, 0xffff0000, v99
	v_div_scale_f32 v16, s[8:9], v97, v97, v92
	v_rcp_f32_e32 v102, v16
	v_pk_mul_f32 v[94:95], v[94:95], v[98:99]
	v_and_b32_e32 v104, 0xffff0000, v93
	v_cvt_pk_bf16_f32 v91, v94, v95
	v_fma_f32 v94, -v16, v102, 1.0
	v_fmac_f32_e32 v102, v94, v102
	v_div_scale_f32 v94, vcc, v92, v97, v92
	v_mul_f32_e32 v95, v94, v102
	v_fma_f32 v98, -v16, v95, v94
	v_fmac_f32_e32 v95, v98, v102
	v_fma_f32 v16, -v16, v95, v94
	v_div_scale_f32 v94, s[8:9], v96, v96, v103
	v_rcp_f32_e32 v98, v94
	v_div_fmas_f32 v16, v16, v102, v95
	v_div_fixup_f32 v95, v16, v97, v92
	v_lshlrev_b32_e32 v102, 16, v93
	v_fma_f32 v16, -v94, v98, 1.0
	v_fmac_f32_e32 v98, v16, v98
	v_div_scale_f32 v16, vcc, v103, v96, v103
	v_mul_f32_e32 v97, v16, v98
	v_fma_f32 v92, -v94, v97, v16
	v_fmac_f32_e32 v97, v92, v98
	v_mul_f32_e32 v92, 0xbfb8aa3b, v102
	v_mul_f32_e32 v93, 0xbfb8aa3b, v104
	v_exp_f32_e32 v92, v92
	v_exp_f32_e32 v93, v93
	v_fma_f32 v16, -v94, v97, v16
	v_div_fmas_f32 v16, v16, v98, v97
	v_div_fixup_f32 v94, v16, v96, v103
	v_pk_add_f32 v[98:99], v[92:93], 1.0 op_sel_hi:[1,0]
	v_lshlrev_b32_e32 v96, 16, v100
	v_div_scale_f32 v16, s[8:9], v99, v99, v104
	v_rcp_f32_e32 v103, v16
	v_and_b32_e32 v97, 0xffff0000, v100
	v_pk_mul_f32 v[92:93], v[94:95], v[96:97]
	s_nop 0
	v_cvt_pk_bf16_f32 v92, v92, v93
	v_fma_f32 v93, -v16, v103, 1.0
	v_fmac_f32_e32 v103, v93, v103
	v_div_scale_f32 v93, vcc, v104, v99, v104
	v_mul_f32_e32 v94, v93, v103
	v_fma_f32 v95, -v16, v94, v93
	v_fmac_f32_e32 v94, v95, v103
	v_fma_f32 v16, -v16, v94, v93
	v_div_scale_f32 v93, s[8:9], v98, v98, v102
	v_rcp_f32_e32 v96, v93
	v_div_fmas_f32 v16, v16, v103, v94
	v_div_fixup_f32 v95, v16, v99, v104
	s_waitcnt vmcnt(2)
; __device__ __forceinline__ unsigned cvt_pk_bf16(float lo, float hi) { const f32x2c_t v = {lo, hi}; return __builtin_bit_cast(unsigned, __builtin_convertvector(v, bf16x2c_t)); }
; #define LAS __attribute__((address_space(3)))
; __device__ __forceinline__ float bf_lo(unsigned w) { return __uint_as_float(w << 16); }
; __device__ __forceinline__ float bf_hi(unsigned w) { return __uint_as_float(w & 0xffff0000u); }
; __device__ __forceinline__ void retout_loop(ldsp lds, const bf16* proj, const bf16* st, bf16* mix, const float* ldr, int u0, int ustep, int nunits, int tid0) {
;     ...
;         for (int k = 0; k < 4; ++k) { const int q = lane + 64 * k, r = q >> 4, ch = q & 15;
;             const v4u s = *(const LAS v4u*)(TK + offb(16 * w + r, ch)), gw = gr[k];
;             v4u o;
; #pragma unroll
;             for (int e = 0; e < 4; ++e) { const float g0 = bf_lo(gw[e]), g1 = bf_hi(gw[e]);
;                 o[e] = cvt_pk_bf16(g0 / (1.f + __expf(-g0)) * bf_lo(s[e]), g1 / (1.f + __expf(-g1)) * bf_hi(s[e])); }
;             *(v4u*)(obase + (size_t)r * DM + 8 * ch) = o; }
	v_and_b32_e32 v104, 0xffff0000, v87
	v_fma_f32 v16, -v93, v96, 1.0
	v_fmac_f32_e32 v96, v16, v96
	v_div_scale_f32 v16, vcc, v102, v98, v102
	v_mul_f32_e32 v94, v16, v96
	v_fma_f32 v97, -v93, v94, v16
	v_fmac_f32_e32 v94, v97, v96
	v_fma_f32 v16, -v93, v94, v16
	v_div_fmas_f32 v16, v16, v96, v94
	v_div_fixup_f32 v94, v16, v98, v102
	v_lshlrev_b32_e32 v96, 16, v101
	v_and_b32_e32 v97, 0xffff0000, v101
	v_pk_mul_f32 v[94:95], v[94:95], v[96:97]
	v_lshlrev_b32_e32 v98, 16, v86
	v_and_b32_e32 v86, 0xffff0000, v86
	v_cvt_pk_bf16_f32 v93, v94, v95
	v_mul_f32_e32 v94, 0xbfb8aa3b, v98
	v_mul_f32_e32 v95, 0xbfb8aa3b, v86
	v_exp_f32_e32 v94, v94
	v_exp_f32_e32 v95, v95
	v_lshlrev_b32_e32 v16, 13, v164
	v_lshl_add_u64 v[96:97], v[106:107], 0, v[16:17]
	global_store_dwordx4 v[96:97], v[90:93], off offset:2048
	v_or_b32_e32 v16, s4, v163
	s_nop 0
	v_pk_add_f32 v[90:91], v[94:95], 1.0 op_sel_hi:[1,0]
	v_mad_u64_u32 v[92:93], s[8:9], v16, s47, v[108:109]
	v_div_scale_f32 v99, s[8:9], v91, v91, v86
	v_rcp_f32_e32 v100, v99
	ds_read_b128 v[94:97], v92 offset:34816
	v_fma_f32 v16, -v99, v100, 1.0
	v_fmac_f32_e32 v100, v16, v100
	v_div_scale_f32 v16, vcc, v86, v91, v86
	v_mul_f32_e32 v92, v16, v100
	v_fma_f32 v93, -v99, v92, v16
	v_fmac_f32_e32 v92, v93, v100
	v_div_scale_f32 v93, s[8:9], v90, v90, v98
	v_rcp_f32_e32 v101, v93
	v_fma_f32 v16, -v99, v92, v16
	v_div_fmas_f32 v16, v16, v100, v92
	v_div_fixup_f32 v99, v16, v91, v86
	v_fma_f32 v16, -v93, v101, 1.0
	v_fmac_f32_e32 v101, v16, v101
	v_div_scale_f32 v16, vcc, v98, v90, v98
	v_mul_f32_e32 v86, v16, v101
	v_fma_f32 v91, -v93, v86, v16
	v_fmac_f32_e32 v86, v91, v101
	v_fma_f32 v16, -v93, v86, v16
	v_div_fmas_f32 v16, v16, v101, v86
	v_div_fixup_f32 v98, v16, v90, v98
	v_lshlrev_b32_e32 v16, 16, v87
	v_mul_f32_e32 v86, 0xbfb8aa3b, v16
	v_mul_f32_e32 v87, 0xbfb8aa3b, v104
	v_exp_f32_e32 v86, v86
	v_exp_f32_e32 v87, v87
	v_or_b32_e32 v90, s4, v162
	v_mad_u64_u32 v[90:91], s[4:5], v90, s47, v[108:109]
	v_pk_add_f32 v[102:103], v[86:87], 1.0 op_sel_hi:[1,0]
	s_waitcnt lgkmcnt(0)
	v_lshlrev_b32_e32 v100, 16, v94
	v_div_scale_f32 v105, s[4:5], v103, v103, v104
	v_rcp_f32_e32 v108, v105
	v_and_b32_e32 v101, 0xffff0000, v94
	v_pk_mul_f32 v[86:87], v[98:99], v[100:101]
	ds_read_b128 v[90:93], v90 offset:34816
	v_cvt_pk_bf16_f32 v86, v86, v87
	v_fma_f32 v87, -v105, v108, 1.0
	v_fmac_f32_e32 v108, v87, v108
	v_div_scale_f32 v87, vcc, v104, v103, v104
	v_mul_f32_e32 v94, v87, v108
	v_fma_f32 v98, -v105, v94, v87
	v_fmac_f32_e32 v94, v98, v108
	v_div_scale_f32 v98, s[4:5], v102, v102, v16
	v_fma_f32 v87, -v105, v94, v87
	v_rcp_f32_e32 v105, v98
	v_div_fmas_f32 v87, v87, v108, v94
	v_div_fixup_f32 v99, v87, v103, v104
	v_lshlrev_b32_e32 v103, 16, v88
	v_fma_f32 v87, -v98, v105, 1.0
	v_fmac_f32_e32 v105, v87, v105
	v_div_scale_f32 v87, vcc, v16, v102, v16
	v_mul_f32_e32 v94, v87, v105
	v_fma_f32 v100, -v98, v94, v87
	v_fmac_f32_e32 v94, v100, v105
	v_fma_f32 v87, -v98, v94, v87
	v_and_b32_e32 v88, 0xffff0000, v88
	v_mul_f32_e32 v98, 0xbfb8aa3b, v103
	v_exp_f32_e32 v100, v98
	v_mul_f32_e32 v98, 0xbfb8aa3b, v88
	v_exp_f32_e32 v101, v98
	v_div_fmas_f32 v87, v87, v105, v94
	v_div_fixup_f32 v98, v87, v102, v16
	v_lshlrev_b32_e32 v94, 16, v95
	v_pk_add_f32 v[100:101], v[100:101], 1.0 op_sel_hi:[1,0]
	v_and_b32_e32 v95, 0xffff0000, v95
	v_div_scale_f32 v16, s[4:5], v101, v101, v88
	v_rcp_f32_e32 v102, v16
	v_pk_mul_f32 v[94:95], v[98:99], v[94:95]
	v_and_b32_e32 v104, 0xffff0000, v89
	v_cvt_pk_bf16_f32 v87, v94, v95
	v_fma_f32 v94, -v16, v102, 1.0
	v_fmac_f32_e32 v102, v94, v102
	v_div_scale_f32 v94, vcc, v88, v101, v88
	v_mul_f32_e32 v95, v94, v102
	v_fma_f32 v98, -v16, v95, v94
	v_fmac_f32_e32 v95, v98, v102
	v_fma_f32 v16, -v16, v95, v94
	v_div_scale_f32 v94, s[4:5], v100, v100, v103
	v_rcp_f32_e32 v98, v94
	v_div_fmas_f32 v16, v16, v102, v95
	v_div_fixup_f32 v95, v16, v101, v88
	v_lshlrev_b32_e32 v102, 16, v89
	v_fma_f32 v16, -v94, v98, 1.0
	v_fmac_f32_e32 v98, v16, v98
	v_div_scale_f32 v16, vcc, v103, v100, v103
	v_mul_f32_e32 v99, v16, v98
	v_fma_f32 v88, -v94, v99, v16
	v_fmac_f32_e32 v99, v88, v98
	v_mul_f32_e32 v88, 0xbfb8aa3b, v102
	v_mul_f32_e32 v89, 0xbfb8aa3b, v104
	v_exp_f32_e32 v88, v88
	v_exp_f32_e32 v89, v89
	v_fma_f32 v16, -v94, v99, v16
	v_div_fmas_f32 v16, v16, v98, v99
	v_div_fixup_f32 v94, v16, v100, v103
	v_pk_add_f32 v[100:101], v[88:89], 1.0 op_sel_hi:[1,0]
	v_lshlrev_b32_e32 v98, 16, v96
	v_div_scale_f32 v16, s[4:5], v101, v101, v104
	v_rcp_f32_e32 v103, v16
	v_and_b32_e32 v99, 0xffff0000, v96
	v_pk_mul_f32 v[88:89], v[94:95], v[98:99]
	s_nop 0
	v_cvt_pk_bf16_f32 v88, v88, v89
	v_fma_f32 v89, -v16, v103, 1.0
	v_fmac_f32_e32 v103, v89, v103
	v_div_scale_f32 v89, vcc, v104, v101, v104
	v_mul_f32_e32 v94, v89, v103
	v_fma_f32 v95, -v16, v94, v89
	v_fmac_f32_e32 v94, v95, v103
	v_fma_f32 v16, -v16, v94, v89
	v_div_scale_f32 v89, s[4:5], v100, v100, v102
	v_rcp_f32_e32 v96, v89
	v_div_fmas_f32 v16, v16, v103, v94
	v_div_fixup_f32 v95, v16, v101, v104
	v_fma_f32 v16, -v89, v96, 1.0
	v_fmac_f32_e32 v96, v16, v96
	v_div_scale_f32 v16, vcc, v102, v100, v102
	v_mul_f32_e32 v94, v16, v96
	v_fma_f32 v98, -v89, v94, v16
	v_fmac_f32_e32 v94, v98, v96
	v_fma_f32 v16, -v89, v94, v16
	v_div_fmas_f32 v16, v16, v96, v94
	v_div_fixup_f32 v94, v16, v100, v102
	s_waitcnt vmcnt(2)
; __device__ __forceinline__ unsigned cvt_pk_bf16(float lo, float hi) { const f32x2c_t v = {lo, hi}; return __builtin_bit_cast(unsigned, __builtin_convertvector(v, bf16x2c_t)); }
; #define LAS __attribute__((address_space(3)))
; __device__ __forceinline__ float bf_lo(unsigned w) { return __uint_as_float(w << 16); }
; __device__ __forceinline__ float bf_hi(unsigned w) { return __uint_as_float(w & 0xffff0000u); }
; __device__ __forceinline__ void retout_loop(ldsp lds, const bf16* proj, const bf16* st, bf16* mix, const float* ldr, int u0, int ustep, int nunits, int tid0) {
;     ...
;         for (int k = 0; k < 4; ++k) { const int q = lane + 64 * k, r = q >> 4, ch = q & 15;
;             const v4u s = *(const LAS v4u*)(TK + offb(16 * w + r, ch)), gw = gr[k];
;             v4u o;
; #pragma unroll
;             for (int e = 0; e < 4; ++e) { const float g0 = bf_lo(gw[e]), g1 = bf_hi(gw[e]);
;                 o[e] = cvt_pk_bf16(g0 / (1.f + __expf(-g0)) * bf_lo(s[e]), g1 / (1.f + __expf(-g1)) * bf_hi(s[e])); }
;             *(v4u*)(obase + (size_t)r * DM + 8 * ch) = o; }
;         unit = unext;
	v_lshlrev_b32_e32 v100, 16, v82
	v_and_b32_e32 v82, 0xffff0000, v82
	v_mul_f32_e32 v16, 0xbfb8aa3b, v100
	v_exp_f32_e32 v98, v16
	v_mul_f32_e32 v16, 0xbfb8aa3b, v82
	v_exp_f32_e32 v99, v16
	v_lshlrev_b32_e32 v96, 16, v97
	v_and_b32_e32 v97, 0xffff0000, v97
	v_pk_mul_f32 v[94:95], v[94:95], v[96:97]
	v_lshlrev_b32_e32 v16, 13, v163
	v_cvt_pk_bf16_f32 v89, v94, v95
	v_pk_add_f32 v[94:95], v[98:99], 1.0 op_sel_hi:[1,0]
	v_lshl_add_u64 v[96:97], v[106:107], 0, v[16:17]
	v_div_scale_f32 v98, s[4:5], v95, v95, v82
	v_rcp_f32_e32 v99, v98
	global_store_dwordx4 v[96:97], v[86:89], off offset:2048
	v_lshlrev_b32_e32 v96, 16, v83
	v_and_b32_e32 v97, 0xffff0000, v83
	v_fma_f32 v16, -v98, v99, 1.0
	v_fmac_f32_e32 v99, v16, v99
	v_div_scale_f32 v16, vcc, v82, v95, v82
	v_mul_f32_e32 v86, v16, v99
	v_div_scale_f32 v88, s[4:5], v94, v94, v100
	v_fma_f32 v87, -v98, v86, v16
	v_rcp_f32_e32 v89, v88
	v_fmac_f32_e32 v86, v87, v99
	v_fma_f32 v16, -v98, v86, v16
	v_div_fmas_f32 v16, v16, v99, v86
	v_div_fixup_f32 v87, v16, v95, v82
	v_fma_f32 v16, -v88, v89, 1.0
	v_fmac_f32_e32 v89, v16, v89
	v_div_scale_f32 v16, vcc, v100, v94, v100
	v_mul_f32_e32 v86, v16, v89
	v_fma_f32 v82, -v88, v86, v16
	v_fmac_f32_e32 v86, v82, v89
	v_mul_f32_e32 v82, 0xbfb8aa3b, v96
	v_mul_f32_e32 v83, 0xbfb8aa3b, v97
	v_exp_f32_e32 v82, v82
	v_exp_f32_e32 v83, v83
	v_fma_f32 v16, -v88, v86, v16
	v_div_fmas_f32 v16, v16, v89, v86
	v_div_fixup_f32 v86, v16, v94, v100
	v_pk_add_f32 v[94:95], v[82:83], 1.0 op_sel_hi:[1,0]
	s_waitcnt lgkmcnt(0)
	v_lshlrev_b32_e32 v88, 16, v90
	v_div_scale_f32 v16, s[4:5], v95, v95, v97
	v_rcp_f32_e32 v98, v16
	v_and_b32_e32 v89, 0xffff0000, v90
	v_pk_mul_f32 v[82:83], v[86:87], v[88:89]
	s_nop 0
	v_cvt_pk_bf16_f32 v82, v82, v83
	v_fma_f32 v83, -v16, v98, 1.0
	v_fmac_f32_e32 v98, v83, v98
	v_div_scale_f32 v83, vcc, v97, v95, v97
	v_mul_f32_e32 v86, v83, v98
	v_fma_f32 v87, -v16, v86, v83
	v_fmac_f32_e32 v86, v87, v98
	v_fma_f32 v16, -v16, v86, v83
	v_div_scale_f32 v83, s[4:5], v94, v94, v96
	v_rcp_f32_e32 v90, v83
	v_div_fmas_f32 v16, v16, v98, v86
	v_div_fixup_f32 v87, v16, v95, v97
	v_lshlrev_b32_e32 v95, 16, v84
	v_fma_f32 v16, -v83, v90, 1.0
	v_fmac_f32_e32 v90, v16, v90
	v_div_scale_f32 v16, vcc, v96, v94, v96
	v_mul_f32_e32 v86, v16, v90
	v_fma_f32 v88, -v83, v86, v16
	v_fmac_f32_e32 v86, v88, v90
	v_fma_f32 v16, -v83, v86, v16
	v_and_b32_e32 v84, 0xffff0000, v84
	v_mul_f32_e32 v83, 0xbfb8aa3b, v95
	v_exp_f32_e32 v88, v83
	v_mul_f32_e32 v83, 0xbfb8aa3b, v84
	v_exp_f32_e32 v89, v83
	v_div_fmas_f32 v16, v16, v90, v86
	v_div_fixup_f32 v86, v16, v94, v96
	v_lshlrev_b32_e32 v90, 16, v91
	v_pk_add_f32 v[88:89], v[88:89], 1.0 op_sel_hi:[1,0]
	v_and_b32_e32 v91, 0xffff0000, v91
	v_div_scale_f32 v16, s[4:5], v89, v89, v84
	v_rcp_f32_e32 v94, v16
	v_pk_mul_f32 v[86:87], v[86:87], v[90:91]
	v_and_b32_e32 v96, 0xffff0000, v85
	v_cvt_pk_bf16_f32 v83, v86, v87
	v_fma_f32 v86, -v16, v94, 1.0
	v_fmac_f32_e32 v94, v86, v94
	v_div_scale_f32 v86, vcc, v84, v89, v84
	v_mul_f32_e32 v87, v86, v94
	v_fma_f32 v90, -v16, v87, v86
	v_fmac_f32_e32 v87, v90, v94
	v_fma_f32 v16, -v16, v87, v86
	v_div_scale_f32 v86, s[4:5], v88, v88, v95
	v_rcp_f32_e32 v90, v86
	v_div_fmas_f32 v16, v16, v94, v87
	v_div_fixup_f32 v87, v16, v89, v84
	v_lshlrev_b32_e32 v94, 16, v85
	v_fma_f32 v16, -v86, v90, 1.0
	v_fmac_f32_e32 v90, v16, v90
	v_div_scale_f32 v16, vcc, v95, v88, v95
	v_mul_f32_e32 v89, v16, v90
	v_fma_f32 v84, -v86, v89, v16
	v_fmac_f32_e32 v89, v84, v90
	v_mul_f32_e32 v84, 0xbfb8aa3b, v94
	v_mul_f32_e32 v85, 0xbfb8aa3b, v96
	v_exp_f32_e32 v84, v84
	v_exp_f32_e32 v85, v85
	v_fma_f32 v16, -v86, v89, v16
	v_div_fmas_f32 v16, v16, v90, v89
	v_div_fixup_f32 v86, v16, v88, v95
	v_pk_add_f32 v[90:91], v[84:85], 1.0 op_sel_hi:[1,0]
	v_lshlrev_b32_e32 v88, 16, v92
	v_div_scale_f32 v16, s[4:5], v91, v91, v96
	v_rcp_f32_e32 v95, v16
	v_and_b32_e32 v89, 0xffff0000, v92
	v_pk_mul_f32 v[84:85], v[86:87], v[88:89]
	s_nop 0
	v_cvt_pk_bf16_f32 v84, v84, v85
	v_fma_f32 v85, -v16, v95, 1.0
	v_fmac_f32_e32 v95, v85, v95
	v_div_scale_f32 v85, vcc, v96, v91, v96
	v_mul_f32_e32 v86, v85, v95
	v_fma_f32 v87, -v16, v86, v85
	v_fmac_f32_e32 v86, v87, v95
	v_fma_f32 v16, -v16, v86, v85
	v_div_scale_f32 v85, s[4:5], v90, v90, v94
	v_rcp_f32_e32 v88, v85
	v_div_fmas_f32 v16, v16, v95, v86
	v_div_fixup_f32 v87, v16, v91, v96
	v_readlane_b32 s4, v254, 46
	v_fma_f32 v16, -v85, v88, 1.0
	v_fmac_f32_e32 v88, v16, v88
	v_div_scale_f32 v16, vcc, v94, v90, v94
	v_mul_f32_e32 v86, v16, v88
	v_fma_f32 v89, -v85, v86, v16
	v_fmac_f32_e32 v86, v89, v88
	v_fma_f32 v16, -v85, v86, v16
	v_div_fmas_f32 v16, v16, v88, v86
	v_div_fixup_f32 v86, v16, v90, v94
	v_lshlrev_b32_e32 v88, 16, v93
	v_and_b32_e32 v89, 0xffff0000, v93
	v_pk_mul_f32 v[86:87], v[86:87], v[88:89]
	v_lshlrev_b32_e32 v16, 13, v162
	v_cvt_pk_bf16_f32 v85, v86, v87
	v_lshl_add_u64 v[86:87], v[106:107], 0, v[16:17]
	s_andn2_b64 vcc, exec, s[6:7]
	s_add_i32 s0, s0, s4
	global_store_dwordx4 v[86:87], v[82:85], off offset:2048
	s_cbranch_vccz .LBB0_464
; template <bool A_TR, bool B_TR>
; __device__ __forceinline__ void mm128(f32x4 (&acc)[8], ldsp TA, ldsp TB, int w, int lane) {
;     const ldsp ab = A_TR ? tr_base(TA, lane) + 32u * w : row_base(TA, lane) + 16u * TP * w;
;     const ldsp bb = B_TR ? tr_base(TB, lane) : row_base(TB, lane);
;     if (MM_SETPRIO) __builtin_amdgcn_s_setprio(1);
;     ...
;     bf16x8 a[4];
; #pragma unroll
;     for (int ks = 0; ks < 4; ++ks) a[ks] = A_TR ? frag_tr(ab, 0, ks) : frag_row(ab, 0, ks);
;     mm_pipe<MM_G, 0, 4, 0, 8>(acc, [&](int c, int ks) { return B_TR ? frag_tr(bb, c, ks) : frag_row(bb, c, ks); }, [&](int ks) { return a[ks]; });
;     ...
; #pragma unroll
;     for (int ks = 0; ks < 4; ++ks) {
;         const bf16x8 a = A_TR ? frag_tr(ab, 0, ks) : frag_row(ab, 0, ks);
; #pragma unroll
;         for (int c = 0; c < 8; ++c) {
;             const bf16x8 b = B_TR ? frag_tr(bb, c, ks) : frag_row(bb, c, ks);
;             acc[c] = __builtin_amdgcn_mfma_f32_16x16x32_bf16(b, a, acc[c], 0, 0, 0);
;         }
;     }
; __device__ __forceinline__ void retout_loop(ldsp lds, const bf16* proj, const bf16* st, bf16* mix, const float* ldr, int u0, int ustep, int nunits, int tid0) {
;     ...
;         const int h = unit & 7, n = (unit >> 3) & 31, b = unit >> 8;
;         const size_t row0 = (size_t)b * SEQ + (size_t)n * CHUNK;
;         const float l2f = -__expf(ldr[h]) * LOG2E, l2b = -__expf(ldr[NRH + h]) * LOG2E;
;         __syncthreads();
;         tile_put(TQ, R.q, tid); tile_put(TK, R.k, tid); tile_put(TV, R.v, tid); tile_put_frag(TS, R.sf, tid);
;         __syncthreads();
;         f32x4 P[8]; zero8(P);
;         mm128<false, false>(P, TQ, TK, w, lane);
.LBB0_462:
	s_and_b32 s5, s1, 7
	s_lshl_b32 s10, s5, 2
	v_mov_b32_e32 v16, s10
	global_load_dword v82, v16, s[14:15]
	s_waitcnt vmcnt(27)
	v_add_u32_e32 v85, 0x200, v170
	global_load_dword v16, v16, s[14:15] offset:32
	s_waitcnt vmcnt(27)
	v_add_u32_e32 v87, 0x400, v170
	v_add_u32_e32 v89, 0x600, v170
	v_ashrrev_i32_e32 v162, 4, v170
	v_ashrrev_i32_e32 v164, 4, v85
	v_ashrrev_i32_e32 v166, 4, v87
	v_ashrrev_i32_e32 v168, 4, v89
	v_mul_lo_u32 v83, v162, s47
	v_mul_lo_u32 v85, v164, s47
	v_mul_lo_u32 v87, v166, s47
	v_mul_lo_u32 v89, v168, s47
	s_barrier
	v_and_b32_e32 v173, 15, v170
	s_mov_b32 s12, 0xffffff0
	v_readfirstlane_b32 s4, v170
	s_ashr_i32 s9, s4, 6
	v_and_b32_e32 v110, 48, v170
	s_lshl_b32 s4, s9, 4
	s_ashr_i32 s6, s1, 8
	s_mulk_i32 s9, 0x1100
	v_or_b32_e32 v174, s4, v173
	s_ashr_i32 s7, s6, 31
	s_and_b32 s8, s0, 0xf80
	s_waitcnt vmcnt(1)
	v_mul_f32_e32 v82, 0x3fb8aa3b, v82
	v_exp_f32_e32 v82, v82
	s_waitcnt vmcnt(0)
	v_mul_f32_e32 v16, 0x3fb8aa3b, v16
	v_exp_f32_e32 v16, v16
	v_mul_f32_e32 v175, 0xbfb8aa3b, v82
	v_mul_f32_e32 v177, 0xbfb8aa3b, v16
	v_lshlrev_b32_e32 v16, 4, v170
	v_and_b32_e32 v16, 0xf0, v16
	v_add_u32_e32 v82, 0, v16
	v_add_u32_e32 v84, v82, v83
	v_add_u32_e32 v86, v82, v85
	v_add_u32_e32 v88, v82, v87
	v_add_u32_e32 v82, v82, v89
	v_add_u32_e32 v16, s33, v16
	ds_write_b128 v84, v[0:3]
	ds_write_b128 v86, v[4:7]
	ds_write_b128 v88, v[8:11]
	ds_write_b128 v82, v[12:15]
	ds_write_b128 v84, v[18:21] offset:34816
	ds_write_b128 v86, v[22:25] offset:34816
	ds_write_b128 v88, v[26:29] offset:34816
	ds_write_b128 v82, v[30:33] offset:34816
	v_add_u32_e32 v82, v16, v83
	ds_write_b128 v82, v[34:37]
	v_add_u32_e32 v82, v16, v85
	ds_write_b128 v82, v[38:41]
	v_add_u32_e32 v82, v16, v87
	v_add_u32_e32 v16, v16, v89
	ds_write_b128 v82, v[42:45]
	ds_write_b128 v16, v[46:49]
	v_and_b32_e32 v16, 0xf0, v170
	v_add_u32_e32 v16, s96, v16
	v_and_or_b32 v82, v162, s12, v173
	v_mad_u64_u32 v[130:131], s[10:11], v82, s47, v[16:17]
	v_and_or_b32 v82, v164, s12, v173
	v_mad_u64_u32 v[132:133], s[10:11], v82, s47, v[16:17]
	v_and_or_b32 v82, v166, s12, v173
	v_mad_u64_u32 v[134:135], s[10:11], v82, s47, v[16:17]
	v_and_or_b32 v82, v168, s12, v173
	v_mad_u64_u32 v[136:137], s[10:11], v82, s47, v[16:17]
	v_mul_u32_u24_e32 v16, 0x110, v173
	v_add3_u32 v82, 0, v16, v110
	v_add_u32_e32 v176, s9, v82
	ds_write_b128 v130, v[50:53]
	ds_write_b128 v132, v[54:57]
	ds_write_b128 v134, v[58:61]
	ds_write_b128 v136, v[62:65]
	s_waitcnt lgkmcnt(0)
	s_barrier
	s_setprio 1
	ds_read_b128 v[150:153], v176
	ds_read_b128 v[154:157], v82 offset:34816
	ds_read_b128 v[158:161], v82 offset:39168
	ds_read_b128 v[178:181], v82 offset:43520
	ds_read_b128 v[182:185], v82 offset:47872
	ds_read_b128 v[186:189], v82 offset:52224
	ds_read_b128 v[190:193], v82 offset:56576
	ds_read_b128 v[194:197], v82 offset:60928
	ds_read_b128 v[198:201], v82 offset:65280
	ds_read_b128 v[202:205], v176 offset:64
	ds_read_b128 v[206:209], v82 offset:34880
	ds_read_b128 v[212:215], v82 offset:39232
	s_waitcnt lgkmcnt(10)
	v_mfma_f32_16x16x32_bf16 v[88:91], v[154:157], v[150:153], 0
	ds_read_b128 v[154:157], v82 offset:43584
	s_waitcnt lgkmcnt(10)
	v_mfma_f32_16x16x32_bf16 v[92:95], v[158:161], v[150:153], 0
	ds_read_b128 v[158:161], v82 offset:47936
	s_waitcnt lgkmcnt(10)
	v_mfma_f32_16x16x32_bf16 v[96:99], v[178:181], v[150:153], 0
	ds_read_b128 v[178:181], v82 offset:52288
	s_waitcnt lgkmcnt(10)
	v_mfma_f32_16x16x32_bf16 v[100:103], v[182:185], v[150:153], 0
	ds_read_b128 v[182:185], v82 offset:56640
	s_waitcnt lgkmcnt(10)
	v_mfma_f32_16x16x32_bf16 v[104:107], v[186:189], v[150:153], 0
	ds_read_b128 v[186:189], v82 offset:60992
	s_waitcnt lgkmcnt(10)
	v_mfma_f32_16x16x32_bf16 v[112:115], v[190:193], v[150:153], 0
	ds_read_b128 v[190:193], v82 offset:65344
	s_waitcnt lgkmcnt(10)
	v_mfma_f32_16x16x32_bf16 v[116:119], v[194:197], v[150:153], 0
	ds_read_b128 v[194:197], v176 offset:128
	s_waitcnt lgkmcnt(10)
	v_mfma_f32_16x16x32_bf16 v[84:87], v[198:201], v[150:153], 0
	ds_read_b128 v[198:201], v82 offset:34944
	ds_read_b128 v[150:153], v82 offset:39296
	s_waitcnt lgkmcnt(10)
	v_mfma_f32_16x16x32_bf16 v[88:91], v[206:209], v[202:205], v[88:91]
	ds_read_b128 v[206:209], v82 offset:43648
	s_waitcnt lgkmcnt(10)
	v_mfma_f32_16x16x32_bf16 v[92:95], v[212:215], v[202:205], v[92:95]
	ds_read_b128 v[212:215], v82 offset:48000
	s_waitcnt lgkmcnt(10)
	v_mfma_f32_16x16x32_bf16 v[96:99], v[154:157], v[202:205], v[96:99]
	ds_read_b128 v[154:157], v82 offset:52352
	s_waitcnt lgkmcnt(10)
	v_mfma_f32_16x16x32_bf16 v[100:103], v[158:161], v[202:205], v[100:103]
	ds_read_b128 v[158:161], v82 offset:56704
	s_waitcnt lgkmcnt(10)
	v_mfma_f32_16x16x32_bf16 v[104:107], v[178:181], v[202:205], v[104:107]
	ds_read_b128 v[178:181], v82 offset:61056
	s_waitcnt lgkmcnt(10)
	v_mfma_f32_16x16x32_bf16 v[112:115], v[182:185], v[202:205], v[112:115]
	ds_read_b128 v[182:185], v82 offset:65408
	s_waitcnt lgkmcnt(10)
	v_mfma_f32_16x16x32_bf16 v[116:119], v[186:189], v[202:205], v[116:119]
	ds_read_b128 v[186:189], v176 offset:192
	s_waitcnt lgkmcnt(10)
	v_mfma_f32_16x16x32_bf16 v[84:87], v[190:193], v[202:205], v[84:87]
	ds_read_b128 v[190:193], v82 offset:35008
	ds_read_b128 v[202:205], v82 offset:39360
	s_waitcnt lgkmcnt(10)
	v_mfma_f32_16x16x32_bf16 v[88:91], v[198:201], v[194:197], v[88:91]
	ds_read_b128 v[198:201], v82 offset:43712
	s_waitcnt lgkmcnt(10)
	v_mfma_f32_16x16x32_bf16 v[92:95], v[150:153], v[194:197], v[92:95]
	ds_read_b128 v[150:153], v82 offset:48064
	s_waitcnt lgkmcnt(10)
	v_mfma_f32_16x16x32_bf16 v[96:99], v[206:209], v[194:197], v[96:99]
	ds_read_b128 v[206:209], v82 offset:52416
	s_waitcnt lgkmcnt(10)
; __device__ __forceinline__ void retout_loop(ldsp lds, const bf16* proj, const bf16* st, bf16* mix, const float* ldr, int u0, int ustep, int nunits, int tid0) {
;     ...
;         mm128<false, false>(P, TQ, TK, w, lane);
; #pragma unroll
;         for (int c = 0; c < 8; ++c)
; #pragma unroll
;             for (int j = 0; j < 4; ++j) { const int dl = i - (16 * c + 4 * fq + j);
;                 P[c][j] *= __builtin_amdgcn_exp2f(dl >= 0 ? l2f * (float)dl : l2b * (float)(-dl)); }
	v_mfma_f32_16x16x32_bf16 v[124:127], v[212:215], v[194:197], v[100:103]
	ds_read_b128 v[212:215], v82 offset:56768
	s_waitcnt lgkmcnt(10)
	v_mfma_f32_16x16x32_bf16 v[138:141], v[154:157], v[194:197], v[104:107]
	ds_read_b128 v[154:157], v82 offset:61120
	s_waitcnt lgkmcnt(10)
	v_mfma_f32_16x16x32_bf16 v[112:115], v[158:161], v[194:197], v[112:115]
	ds_read_b128 v[158:161], v82 offset:65472
	s_waitcnt lgkmcnt(10)
	v_mfma_f32_16x16x32_bf16 v[116:119], v[178:181], v[194:197], v[116:119]
	s_waitcnt lgkmcnt(9)
	v_mfma_f32_16x16x32_bf16 v[120:123], v[182:185], v[194:197], v[84:87]
	s_waitcnt lgkmcnt(7)
	v_mfma_f32_16x16x32_bf16 v[146:149], v[190:193], v[186:189], v[88:91]
	s_waitcnt lgkmcnt(6)
	v_mfma_f32_16x16x32_bf16 v[106:109], v[202:205], v[186:189], v[92:95]
	s_waitcnt lgkmcnt(5)
	v_mfma_f32_16x16x32_bf16 v[102:105], v[198:201], v[186:189], v[96:99]
	s_waitcnt lgkmcnt(4)
	v_mfma_f32_16x16x32_bf16 v[98:101], v[150:153], v[186:189], v[124:127]
	s_waitcnt lgkmcnt(3)
	v_mfma_f32_16x16x32_bf16 v[94:97], v[206:209], v[186:189], v[138:141]
	s_waitcnt lgkmcnt(2)
	v_mfma_f32_16x16x32_bf16 v[90:93], v[212:215], v[186:189], v[112:115]
	s_waitcnt lgkmcnt(1)
	v_mfma_f32_16x16x32_bf16 v[86:89], v[154:157], v[186:189], v[116:119]
	s_waitcnt lgkmcnt(0)
	v_mfma_f32_16x16x32_bf16 v[82:85], v[158:161], v[186:189], v[120:123]
	s_nop 7
	s_setprio 0
	v_lshrrev_b32_e32 v111, 2, v170
	v_and_b32_e32 v111, 12, v111
	v_sub_u32_e32 v112, v174, v111
	v_sub_u32_e32 v113, 0, v112
	v_max_i32_e32 v113, v112, v113
	v_cvt_f32_u32_e32 v113, v113
	v_cmp_gt_i32_e32 vcc, 0, v112
	s_lshl_b64 s[6:7], s[6:7], 12
	s_or_b32 s6, s6, s8
	v_cndmask_b32_e32 v112, v175, v177, vcc
	v_mul_f32_e32 v112, v112, v113
	v_xad_u32 v113, v111, -1, v174
	v_sub_u32_e32 v114, 0, v113
	v_max_i32_e32 v114, v113, v114
	v_cvt_f32_u32_e32 v114, v114
	v_cmp_gt_i32_e32 vcc, 0, v113
	v_exp_f32_e32 v112, v112
	v_add3_u32 v158, s96, v16, v110
	v_cndmask_b32_e32 v113, v175, v177, vcc
	v_mul_f32_e32 v113, v113, v114
	v_exp_f32_e32 v113, v113
	s_nop 0
	v_pk_mul_f32 v[138:139], v[112:113], v[146:147]
	v_or_b32_e32 v112, 2, v111
	v_sub_u32_e32 v112, v174, v112
	v_sub_u32_e32 v113, 0, v112
	v_max_i32_e32 v113, v112, v113
	v_cvt_f32_u32_e32 v113, v113
	v_cmp_gt_i32_e32 vcc, 0, v112
	s_nop 1
	v_cndmask_b32_e32 v112, v175, v177, vcc
	v_mul_f32_e32 v112, v112, v113
	v_or_b32_e32 v113, 3, v111
	v_sub_u32_e32 v113, v174, v113
	v_sub_u32_e32 v114, 0, v113
	v_max_i32_e32 v114, v113, v114
	v_cvt_f32_u32_e32 v114, v114
	v_cmp_gt_i32_e32 vcc, 0, v113
	v_exp_f32_e32 v112, v112
	s_nop 0
	v_cndmask_b32_e32 v113, v175, v177, vcc
	v_mul_f32_e32 v113, v113, v114
	v_exp_f32_e32 v113, v113
	s_nop 0
	v_pk_mul_f32 v[140:141], v[112:113], v[148:149]
	v_or_b32_e32 v112, 16, v111
	v_sub_u32_e32 v112, v174, v112
	v_sub_u32_e32 v113, 0, v112
	v_max_i32_e32 v113, v112, v113
	v_cvt_f32_u32_e32 v113, v113
	v_cmp_gt_i32_e32 vcc, 0, v112
	s_nop 1
	v_cndmask_b32_e32 v112, v175, v177, vcc
	v_mul_f32_e32 v112, v112, v113
	v_or_b32_e32 v113, 17, v111
	v_sub_u32_e32 v113, v174, v113
	v_sub_u32_e32 v114, 0, v113
	v_max_i32_e32 v114, v113, v114
	v_cvt_f32_u32_e32 v114, v114
	v_cmp_gt_i32_e32 vcc, 0, v113
	v_exp_f32_e32 v112, v112
	s_nop 0
	v_cndmask_b32_e32 v113, v175, v177, vcc
	v_mul_f32_e32 v113, v113, v114
	v_exp_f32_e32 v113, v113
	s_nop 0
	v_pk_mul_f32 v[142:143], v[112:113], v[106:107]
	v_or_b32_e32 v106, 18, v111
	v_sub_u32_e32 v106, v174, v106
	v_sub_u32_e32 v107, 0, v106
	v_max_i32_e32 v107, v106, v107
	v_cvt_f32_u32_e32 v107, v107
	v_cmp_gt_i32_e32 vcc, 0, v106
	s_nop 1
	v_cndmask_b32_e32 v106, v175, v177, vcc
	v_mul_f32_e32 v106, v106, v107
	v_or_b32_e32 v107, 19, v111
	v_sub_u32_e32 v107, v174, v107
	v_sub_u32_e32 v112, 0, v107
	v_max_i32_e32 v112, v107, v112
	v_cvt_f32_u32_e32 v112, v112
	v_cmp_gt_i32_e32 vcc, 0, v107
	v_exp_f32_e32 v106, v106
	s_nop 0
	v_cndmask_b32_e32 v107, v175, v177, vcc
	v_mul_f32_e32 v107, v107, v112
	v_exp_f32_e32 v107, v107
	s_nop 0
	v_pk_mul_f32 v[144:145], v[106:107], v[108:109]
	v_or_b32_e32 v106, 32, v111
	v_sub_u32_e32 v106, v174, v106
	v_sub_u32_e32 v107, 0, v106
	v_max_i32_e32 v107, v106, v107
	v_cvt_f32_u32_e32 v107, v107
	v_cmp_gt_i32_e32 vcc, 0, v106
	s_nop 1
	v_cndmask_b32_e32 v106, v175, v177, vcc
	v_mul_f32_e32 v106, v106, v107
	v_or_b32_e32 v107, 33, v111
	v_sub_u32_e32 v107, v174, v107
	v_sub_u32_e32 v108, 0, v107
	v_max_i32_e32 v108, v107, v108
	v_cvt_f32_u32_e32 v108, v108
	v_cmp_gt_i32_e32 vcc, 0, v107
	v_exp_f32_e32 v106, v106
	s_nop 0
	v_cndmask_b32_e32 v107, v175, v177, vcc
	v_mul_f32_e32 v107, v107, v108
	v_exp_f32_e32 v107, v107
	s_nop 0
	v_pk_mul_f32 v[146:147], v[106:107], v[102:103]
	v_or_b32_e32 v102, 34, v111
	v_sub_u32_e32 v102, v174, v102
	v_sub_u32_e32 v103, 0, v102
	v_max_i32_e32 v103, v102, v103
	v_cvt_f32_u32_e32 v103, v103
	v_cmp_gt_i32_e32 vcc, 0, v102
	s_nop 1
	v_cndmask_b32_e32 v102, v175, v177, vcc
	v_mul_f32_e32 v102, v102, v103
	v_or_b32_e32 v103, 35, v111
	v_sub_u32_e32 v103, v174, v103
	v_sub_u32_e32 v106, 0, v103
	v_max_i32_e32 v106, v103, v106
	v_cvt_f32_u32_e32 v106, v106
	v_cmp_gt_i32_e32 vcc, 0, v103
	v_exp_f32_e32 v102, v102
	s_nop 0
	v_cndmask_b32_e32 v103, v175, v177, vcc
	v_mul_f32_e32 v103, v103, v106
	v_exp_f32_e32 v103, v103
	s_nop 0
	v_pk_mul_f32 v[148:149], v[102:103], v[104:105]
	v_or_b32_e32 v102, 48, v111
	v_sub_u32_e32 v102, v174, v102
	v_sub_u32_e32 v103, 0, v102
	v_max_i32_e32 v103, v102, v103
	v_cvt_f32_u32_e32 v103, v103
	v_cmp_gt_i32_e32 vcc, 0, v102
	s_nop 1
	v_cndmask_b32_e32 v102, v175, v177, vcc
	v_mul_f32_e32 v102, v102, v103
	v_or_b32_e32 v103, 49, v111
	v_sub_u32_e32 v103, v174, v103
	v_sub_u32_e32 v104, 0, v103
	v_max_i32_e32 v104, v103, v104
; template <bool A_TR, bool B_TR>
; __device__ __forceinline__ void mm128(f32x4 (&acc)[8], ldsp TA, ldsp TB, int w, int lane) {
;     const ldsp ab = A_TR ? tr_base(TA, lane) + 32u * w : row_base(TA, lane) + 16u * TP * w;
;     const ldsp bb = B_TR ? tr_base(TB, lane) : row_base(TB, lane);
;     if (MM_SETPRIO) __builtin_amdgcn_s_setprio(1);
;     ...
;     bf16x8 a[4];
; #pragma unroll
;     for (int ks = 0; ks < 4; ++ks) a[ks] = A_TR ? frag_tr(ab, 0, ks) : frag_row(ab, 0, ks);
;     mm_pipe<MM_G, 0, 4, 0, 8>(acc, [&](int c, int ks) { return B_TR ? frag_tr(bb, c, ks) : frag_row(bb, c, ks); }, [&](int ks) { return a[ks]; });
;     ...
; #pragma unroll
;     for (int ks = 0; ks < 4; ++ks) {
;         const bf16x8 a = A_TR ? frag_tr(ab, 0, ks) : frag_row(ab, 0, ks);
; #pragma unroll
;         for (int c = 0; c < 8; ++c) {
;             const bf16x8 b = B_TR ? frag_tr(bb, c, ks) : frag_row(bb, c, ks);
;             acc[c] = __builtin_amdgcn_mfma_f32_16x16x32_bf16(b, a, acc[c], 0, 0, 0);
;         }
;     }
; __device__ __forceinline__ void retout_loop(ldsp lds, const bf16* proj, const bf16* st, bf16* mix, const float* ldr, int u0, int ustep, int nunits, int tid0) {
;     ...
; #pragma unroll
;         for (int c = 0; c < 8; ++c)
; #pragma unroll
;             for (int j = 0; j < 4; ++j) { const int dl = i - (16 * c + 4 * fq + j);
;                 P[c][j] *= __builtin_amdgcn_exp2f(dl >= 0 ? l2f * (float)dl : l2b * (float)(-dl)); }
;         f32x4 accF[8]; zero8(accF);
;         mm128<false, false>(accF, TQ, TS, w, lane);
	v_cvt_f32_u32_e32 v104, v104
	v_cmp_gt_i32_e32 vcc, 0, v103
	v_exp_f32_e32 v102, v102
	s_nop 0
	v_cndmask_b32_e32 v103, v175, v177, vcc
	v_mul_f32_e32 v103, v103, v104
	v_exp_f32_e32 v103, v103
	s_nop 0
	v_pk_mul_f32 v[150:151], v[102:103], v[98:99]
	v_or_b32_e32 v98, 50, v111
	v_sub_u32_e32 v98, v174, v98
	v_sub_u32_e32 v99, 0, v98
	v_max_i32_e32 v99, v98, v99
	v_cvt_f32_u32_e32 v99, v99
	v_cmp_gt_i32_e32 vcc, 0, v98
	s_nop 1
	v_cndmask_b32_e32 v98, v175, v177, vcc
	v_mul_f32_e32 v98, v98, v99
	v_or_b32_e32 v99, 51, v111
	v_sub_u32_e32 v99, v174, v99
	v_sub_u32_e32 v102, 0, v99
	v_max_i32_e32 v102, v99, v102
	v_cvt_f32_u32_e32 v102, v102
	v_cmp_gt_i32_e32 vcc, 0, v99
	v_exp_f32_e32 v98, v98
	s_nop 0
	v_cndmask_b32_e32 v99, v175, v177, vcc
	v_mul_f32_e32 v99, v99, v102
	v_exp_f32_e32 v99, v99
	s_nop 0
	v_pk_mul_f32 v[152:153], v[98:99], v[100:101]
	v_or_b32_e32 v98, 64, v111
	v_sub_u32_e32 v98, v174, v98
	v_sub_u32_e32 v99, 0, v98
	v_max_i32_e32 v99, v98, v99
	v_cvt_f32_u32_e32 v99, v99
	v_cmp_gt_i32_e32 vcc, 0, v98
	s_nop 1
	v_cndmask_b32_e32 v98, v175, v177, vcc
	v_mul_f32_e32 v98, v98, v99
	v_or_b32_e32 v99, 0x41, v111
	v_sub_u32_e32 v99, v174, v99
	v_sub_u32_e32 v100, 0, v99
	v_max_i32_e32 v100, v99, v100
	v_cvt_f32_u32_e32 v100, v100
	v_cmp_gt_i32_e32 vcc, 0, v99
	v_exp_f32_e32 v98, v98
	s_nop 0
	v_cndmask_b32_e32 v99, v175, v177, vcc
	v_mul_f32_e32 v99, v99, v100
	v_exp_f32_e32 v99, v99
	s_nop 0
	v_pk_mul_f32 v[94:95], v[98:99], v[94:95]
	v_or_b32_e32 v98, 0x42, v111
	v_sub_u32_e32 v98, v174, v98
	v_sub_u32_e32 v99, 0, v98
	v_max_i32_e32 v99, v98, v99
	v_cvt_f32_u32_e32 v99, v99
	v_cmp_gt_i32_e32 vcc, 0, v98
	s_nop 1
	v_cndmask_b32_e32 v98, v175, v177, vcc
	v_mul_f32_e32 v98, v98, v99
	v_or_b32_e32 v99, 0x43, v111
	v_sub_u32_e32 v99, v174, v99
	v_sub_u32_e32 v100, 0, v99
	v_max_i32_e32 v100, v99, v100
	v_cvt_f32_u32_e32 v100, v100
	v_cmp_gt_i32_e32 vcc, 0, v99
	v_exp_f32_e32 v98, v98
	s_nop 0
	v_cndmask_b32_e32 v99, v175, v177, vcc
	v_mul_f32_e32 v99, v99, v100
	v_exp_f32_e32 v99, v99
	s_nop 0
	v_pk_mul_f32 v[96:97], v[98:99], v[96:97]
	v_or_b32_e32 v98, 0x50, v111
	v_sub_u32_e32 v98, v174, v98
	v_sub_u32_e32 v99, 0, v98
	v_max_i32_e32 v99, v98, v99
	v_cvt_f32_u32_e32 v99, v99
	v_cmp_gt_i32_e32 vcc, 0, v98
	s_nop 1
	v_cndmask_b32_e32 v98, v175, v177, vcc
	v_mul_f32_e32 v98, v98, v99
	v_or_b32_e32 v99, 0x51, v111
	v_sub_u32_e32 v99, v174, v99
	v_sub_u32_e32 v100, 0, v99
	v_max_i32_e32 v100, v99, v100
	v_cvt_f32_u32_e32 v100, v100
	v_cmp_gt_i32_e32 vcc, 0, v99
	v_exp_f32_e32 v98, v98
	s_nop 0
	v_cndmask_b32_e32 v99, v175, v177, vcc
	v_mul_f32_e32 v99, v99, v100
	v_exp_f32_e32 v99, v99
	s_nop 0
	v_pk_mul_f32 v[90:91], v[98:99], v[90:91]
	v_or_b32_e32 v98, 0x52, v111
	v_sub_u32_e32 v98, v174, v98
	v_sub_u32_e32 v99, 0, v98
	v_max_i32_e32 v99, v98, v99
	v_cvt_f32_u32_e32 v99, v99
	v_cmp_gt_i32_e32 vcc, 0, v98
	s_nop 1
	v_cndmask_b32_e32 v98, v175, v177, vcc
	v_mul_f32_e32 v98, v98, v99
	v_or_b32_e32 v99, 0x53, v111
	v_sub_u32_e32 v99, v174, v99
	v_sub_u32_e32 v100, 0, v99
	v_max_i32_e32 v100, v99, v100
	v_cvt_f32_u32_e32 v100, v100
	v_cmp_gt_i32_e32 vcc, 0, v99
	v_exp_f32_e32 v98, v98
	s_nop 0
	v_cndmask_b32_e32 v99, v175, v177, vcc
	v_mul_f32_e32 v99, v99, v100
	v_exp_f32_e32 v99, v99
	s_nop 0
	v_pk_mul_f32 v[92:93], v[98:99], v[92:93]
	v_or_b32_e32 v98, 0x60, v111
	v_sub_u32_e32 v98, v174, v98
	v_sub_u32_e32 v99, 0, v98
	v_max_i32_e32 v99, v98, v99
	v_cvt_f32_u32_e32 v99, v99
	v_cmp_gt_i32_e32 vcc, 0, v98
	s_nop 1
	v_cndmask_b32_e32 v98, v175, v177, vcc
	v_mul_f32_e32 v98, v98, v99
	v_or_b32_e32 v99, 0x61, v111
	v_sub_u32_e32 v99, v174, v99
	v_sub_u32_e32 v100, 0, v99
	v_max_i32_e32 v100, v99, v100
	v_cvt_f32_u32_e32 v100, v100
	v_cmp_gt_i32_e32 vcc, 0, v99
	v_exp_f32_e32 v98, v98
	s_nop 0
	v_cndmask_b32_e32 v99, v175, v177, vcc
	v_mul_f32_e32 v99, v99, v100
	v_exp_f32_e32 v99, v99
	s_nop 0
	v_pk_mul_f32 v[86:87], v[98:99], v[86:87]
	v_or_b32_e32 v98, 0x62, v111
	v_sub_u32_e32 v98, v174, v98
	v_sub_u32_e32 v99, 0, v98
	v_max_i32_e32 v99, v98, v99
	v_cvt_f32_u32_e32 v99, v99
	v_cmp_gt_i32_e32 vcc, 0, v98
	s_nop 1
	v_cndmask_b32_e32 v98, v175, v177, vcc
	v_mul_f32_e32 v98, v98, v99
	v_or_b32_e32 v99, 0x63, v111
	v_sub_u32_e32 v99, v174, v99
	v_sub_u32_e32 v100, 0, v99
	v_max_i32_e32 v100, v99, v100
	v_cvt_f32_u32_e32 v100, v100
	v_cmp_gt_i32_e32 vcc, 0, v99
	v_exp_f32_e32 v98, v98
	s_nop 0
	v_cndmask_b32_e32 v99, v175, v177, vcc
	v_mul_f32_e32 v99, v99, v100
	v_exp_f32_e32 v99, v99
	s_nop 0
	v_pk_mul_f32 v[88:89], v[98:99], v[88:89]
	v_or_b32_e32 v98, 0x70, v111
	v_sub_u32_e32 v98, v174, v98
	v_sub_u32_e32 v99, 0, v98
	v_max_i32_e32 v99, v98, v99
	v_cvt_f32_u32_e32 v99, v99
	v_cmp_gt_i32_e32 vcc, 0, v98
	s_nop 1
	v_cndmask_b32_e32 v98, v175, v177, vcc
	v_mul_f32_e32 v98, v98, v99
	v_or_b32_e32 v99, 0x71, v111
	v_sub_u32_e32 v99, v174, v99
	v_sub_u32_e32 v100, 0, v99
	v_max_i32_e32 v100, v99, v100
	v_cvt_f32_u32_e32 v100, v100
	v_cmp_gt_i32_e32 vcc, 0, v99
	v_exp_f32_e32 v98, v98
	s_nop 0
	v_cndmask_b32_e32 v99, v175, v177, vcc
	v_mul_f32_e32 v99, v99, v100
	v_exp_f32_e32 v99, v99
	s_nop 0
	v_pk_mul_f32 v[82:83], v[98:99], v[82:83]
	v_or_b32_e32 v98, 0x72, v111
	v_sub_u32_e32 v98, v174, v98
	v_sub_u32_e32 v99, 0, v98
	v_max_i32_e32 v99, v98, v99
	v_cvt_f32_u32_e32 v99, v99
	v_cmp_gt_i32_e32 vcc, 0, v98
	s_nop 1
	v_cndmask_b32_e32 v98, v175, v177, vcc
	v_mul_f32_e32 v98, v98, v99
	v_or_b32_e32 v99, 0x73, v111
	v_sub_u32_e32 v99, v174, v99
	v_sub_u32_e32 v100, 0, v99
	v_max_i32_e32 v100, v99, v100
	v_cvt_f32_u32_e32 v100, v100
	v_cmp_gt_i32_e32 vcc, 0, v99
	v_exp_f32_e32 v98, v98
	s_nop 0
	v_cndmask_b32_e32 v99, v175, v177, vcc
	v_mul_f32_e32 v99, v99, v100
	v_exp_f32_e32 v99, v99
	s_nop 0
	v_pk_mul_f32 v[84:85], v[98:99], v[84:85]
	s_setprio 1
	ds_read_b128 v[194:197], v176
	ds_read_b128 v[198:201], v158
	ds_read_b128 v[202:205], v158 offset:4352
	ds_read_b128 v[206:209], v158 offset:8704
	ds_read_b128 v[212:215], v158 offset:13056
	ds_read_b128 v[216:219], v158 offset:17408
	ds_read_b128 v[220:223], v158 offset:21760
	ds_read_b128 v[236:239], v158 offset:26112
	s_waitcnt lgkmcnt(6)
; template <bool A_TR, bool B_TR>
; __device__ __forceinline__ void mm128(f32x4 (&acc)[8], ldsp TA, ldsp TB, int w, int lane) {
;     ...
; #pragma unroll
;     for (int ks = 0; ks < 4; ++ks) {
;         const bf16x8 a = A_TR ? frag_tr(ab, 0, ks) : frag_row(ab, 0, ks);
; #pragma unroll
;         for (int c = 0; c < 8; ++c) {
;             const bf16x8 b = B_TR ? frag_tr(bb, c, ks) : frag_row(bb, c, ks);
;             acc[c] = __builtin_amdgcn_mfma_f32_16x16x32_bf16(b, a, acc[c], 0, 0, 0);
;         }
;     }
;     ...
;     if (MM_SETPRIO) __builtin_amdgcn_s_setprio(0);
; __device__ __forceinline__ void retout_loop(ldsp lds, const bf16* proj, const bf16* st, bf16* mix, const float* ldr, int u0, int ustep, int nunits, int tid0) {
;     ...
;         mm128<false, false>(accF, TQ, TS, w, lane);
;         __syncthreads();
;         store_acc_tile(TK, P, w, lane);
;         tile_put_frag(TS, R.sb, tid);
	v_mfma_f32_16x16x32_bf16 v[102:105], v[198:201], v[194:197], 0
	ds_read_b128 v[198:201], v158 offset:30464
	s_waitcnt lgkmcnt(6)
	v_mfma_f32_16x16x32_bf16 v[106:109], v[202:205], v[194:197], 0
	ds_read_b128 v[202:205], v176 offset:64
	s_waitcnt lgkmcnt(6)
	v_mfma_f32_16x16x32_bf16 v[110:113], v[206:209], v[194:197], 0
	ds_read_b128 v[206:209], v158 offset:64
	s_waitcnt lgkmcnt(6)
	v_mfma_f32_16x16x32_bf16 v[114:117], v[212:215], v[194:197], 0
	ds_read_b128 v[212:215], v158 offset:4416
	s_waitcnt lgkmcnt(6)
	v_mfma_f32_16x16x32_bf16 v[118:121], v[216:219], v[194:197], 0
	ds_read_b128 v[216:219], v158 offset:8768
	s_waitcnt lgkmcnt(6)
	v_mfma_f32_16x16x32_bf16 v[122:125], v[220:223], v[194:197], 0
	ds_read_b128 v[220:223], v158 offset:13120
	s_waitcnt lgkmcnt(6)
	v_mfma_f32_16x16x32_bf16 v[126:129], v[236:239], v[194:197], 0
	ds_read_b128 v[236:239], v158 offset:17472
	s_waitcnt lgkmcnt(6)
	v_mfma_f32_16x16x32_bf16 v[98:101], v[198:201], v[194:197], 0
	ds_read_b128 v[198:201], v158 offset:21824
	ds_read_b128 v[194:197], v158 offset:26176
	s_waitcnt lgkmcnt(6)
	v_mfma_f32_16x16x32_bf16 v[102:105], v[206:209], v[202:205], v[102:105]
	ds_read_b128 v[206:209], v158 offset:30528
	s_waitcnt lgkmcnt(6)
	v_mfma_f32_16x16x32_bf16 v[106:109], v[212:215], v[202:205], v[106:109]
	ds_read_b128 v[212:215], v176 offset:128
	s_waitcnt lgkmcnt(6)
	v_mfma_f32_16x16x32_bf16 v[110:113], v[216:219], v[202:205], v[110:113]
	ds_read_b128 v[216:219], v158 offset:128
	s_waitcnt lgkmcnt(6)
	v_mfma_f32_16x16x32_bf16 v[114:117], v[220:223], v[202:205], v[114:117]
	ds_read_b128 v[220:223], v158 offset:4480
	s_waitcnt lgkmcnt(6)
	v_mfma_f32_16x16x32_bf16 v[118:121], v[236:239], v[202:205], v[118:121]
	ds_read_b128 v[236:239], v158 offset:8832
	s_waitcnt lgkmcnt(6)
	v_mfma_f32_16x16x32_bf16 v[122:125], v[198:201], v[202:205], v[122:125]
	ds_read_b128 v[198:201], v158 offset:13184
	s_waitcnt lgkmcnt(6)
	v_mfma_f32_16x16x32_bf16 v[126:129], v[194:197], v[202:205], v[126:129]
	ds_read_b128 v[194:197], v158 offset:17536
	s_waitcnt lgkmcnt(6)
	v_mfma_f32_16x16x32_bf16 v[98:101], v[206:209], v[202:205], v[98:101]
	ds_read_b128 v[206:209], v158 offset:21888
	ds_read_b128 v[202:205], v158 offset:26240
	s_waitcnt lgkmcnt(6)
	v_mfma_f32_16x16x32_bf16 v[102:105], v[216:219], v[212:215], v[102:105]
	ds_read_b128 v[216:219], v158 offset:30592
	s_waitcnt lgkmcnt(6)
	v_mfma_f32_16x16x32_bf16 v[106:109], v[220:223], v[212:215], v[106:109]
	ds_read_b128 v[220:223], v176 offset:192
	s_waitcnt lgkmcnt(6)
	v_mfma_f32_16x16x32_bf16 v[110:113], v[236:239], v[212:215], v[110:113]
	ds_read_b128 v[236:239], v158 offset:192
	s_waitcnt lgkmcnt(6)
	v_mfma_f32_16x16x32_bf16 v[178:181], v[198:201], v[212:215], v[114:117]
	ds_read_b128 v[198:201], v158 offset:4544
	s_waitcnt lgkmcnt(6)
	v_mfma_f32_16x16x32_bf16 v[182:185], v[194:197], v[212:215], v[118:121]
	ds_read_b128 v[194:197], v158 offset:8896
	s_waitcnt lgkmcnt(6)
	v_mfma_f32_16x16x32_bf16 v[186:189], v[206:209], v[212:215], v[122:125]
	ds_read_b128 v[206:209], v158 offset:13248
	s_waitcnt lgkmcnt(6)
	v_mfma_f32_16x16x32_bf16 v[126:129], v[202:205], v[212:215], v[126:129]
	ds_read_b128 v[202:205], v158 offset:17600
	s_waitcnt lgkmcnt(6)
	v_mfma_f32_16x16x32_bf16 v[154:157], v[216:219], v[212:215], v[98:101]
	ds_read_b128 v[216:219], v158 offset:21952
	ds_read_b128 v[212:215], v158 offset:26304
	s_waitcnt lgkmcnt(6)
	v_mfma_f32_16x16x32_bf16 v[114:117], v[236:239], v[220:223], v[102:105]
	ds_read_b128 v[236:239], v158 offset:30656
	s_waitcnt lgkmcnt(6)
	v_mfma_f32_16x16x32_bf16 v[122:125], v[198:201], v[220:223], v[106:109]
	s_waitcnt lgkmcnt(5)
	v_mfma_f32_16x16x32_bf16 v[118:121], v[194:197], v[220:223], v[110:113]
	s_waitcnt lgkmcnt(4)
	v_mfma_f32_16x16x32_bf16 v[110:113], v[206:209], v[220:223], v[178:181]
	s_waitcnt lgkmcnt(3)
	v_mfma_f32_16x16x32_bf16 v[106:109], v[202:205], v[220:223], v[182:185]
	s_waitcnt lgkmcnt(2)
	v_mfma_f32_16x16x32_bf16 v[102:105], v[216:219], v[220:223], v[186:189]
	s_waitcnt lgkmcnt(1)
	v_mfma_f32_16x16x32_bf16 v[98:101], v[212:215], v[220:223], v[126:129]
	s_waitcnt lgkmcnt(0)
	v_mfma_f32_16x16x32_bf16 v[126:129], v[236:239], v[220:223], v[154:157]
	s_nop 7
	s_setprio 0
	s_ashr_i32 s9, s4, 31
	s_add_u32 s8, s6, s4
	v_bfe_u32 v180, v170, 1, 5
	s_addc_u32 s9, s7, s9
	v_mul_lo_u32 v16, v174, s47
	v_and_b32_e32 v131, 16, v180
	s_mul_i32 s6, s9, 0x4800
	s_mul_hi_u32 s7, s8, 0x4800
	v_add3_u32 v16, 0, v131, v16
	v_and_b32_e32 v131, 8, v180
	s_add_i32 s7, s7, s6
	s_mul_i32 s6, s8, 0x4800
	v_add_u32_e32 v16, v16, v131
	s_add_u32 s6, s58, s6
	v_add_u32_e32 v179, 0x8800, v16
	s_addc_u32 s7, s59, s7
	s_lshl_b32 s10, s5, 7
	s_lshl_b32 s5, s5, 8
	v_lshlrev_b32_e32 v16, 3, v170
	v_cvt_pk_bf16_f32 v138, v138, v139
	v_cvt_pk_bf16_f32 v139, v140, v141
	v_cvt_pk_bf16_f32 v140, v142, v143
	v_cvt_pk_bf16_f32 v141, v144, v145
	s_add_u32 s6, s6, s5
	v_and_b32_e32 v16, 0x78, v16
	v_bfe_u32 v178, v170, 4, 2
	s_barrier
; template <bool A_TR, bool B_TR>
; __device__ __forceinline__ void mm128(f32x4 (&acc)[8], ldsp TA, ldsp TB, int w, int lane) {
;     ...
; #pragma unroll
;     for (int ks = 0; ks < 4; ++ks) {
;         const bf16x8 a = A_TR ? frag_tr(ab, 0, ks) : frag_row(ab, 0, ks);
; #pragma unroll
;         for (int c = 0; c < 8; ++c) {
;             const bf16x8 b = B_TR ? frag_tr(bb, c, ks) : frag_row(bb, c, ks);
;             acc[c] = __builtin_amdgcn_mfma_f32_16x16x32_bf16(b, a, acc[c], 0, 0, 0);
;         }
;     }
;     ...
;     if (MM_SETPRIO) __builtin_amdgcn_s_setprio(0);
; __device__ __forceinline__ void retout_loop(ldsp lds, const bf16* proj, const bf16* st, bf16* mix, const float* ldr, int u0, int ustep, int nunits, int tid0) {
;     ...
;         store_acc_tile(TK, P, w, lane);
;         tile_put_frag(TS, R.sb, tid);
;         const bf16* gbase = proj + (row0 + 16 * w) * INW + C_RG + h * HDIM;
;         v4u gr[4];
; #pragma unroll
;         for (int k = 0; k < 4; ++k) { const int q = lane + 64 * k; gr[k] = *(const v4u*)(gbase + (size_t)(q >> 4) * INW + 8 * (q & 15)); }
;         const int unext = unit + ustep;
;         __syncthreads();
;         f32x4 acc[8]; zero8(acc);
;         mm128<false, false>(acc, TQ, TS, w, lane);
	ds_write2_b64 v179, v[138:139], v[140:141] offset1:4
	v_cvt_pk_bf16_f32 v138, v146, v147
	v_cvt_pk_bf16_f32 v139, v148, v149
	v_cvt_pk_bf16_f32 v140, v150, v151
	v_cvt_pk_bf16_f32 v141, v152, v153
	v_cvt_pk_bf16_f32 v94, v94, v95
	v_cvt_pk_bf16_f32 v95, v96, v97
	v_cvt_pk_bf16_f32 v90, v90, v91
	v_cvt_pk_bf16_f32 v91, v92, v93
	v_cvt_pk_bf16_f32 v86, v86, v87
	v_cvt_pk_bf16_f32 v87, v88, v89
	v_cvt_pk_bf16_f32 v82, v82, v83
	v_cvt_pk_bf16_f32 v83, v84, v85
	s_addc_u32 s7, s7, 0
	v_lshlrev_b32_e32 v16, 1, v16
	v_mul_u32_u24_e32 v84, 0x2400, v178
	ds_write2_b64 v179, v[138:139], v[140:141] offset0:8 offset1:12
	ds_write2_b64 v179, v[94:95], v[90:91] offset0:16 offset1:20
	ds_write2_b64 v179, v[86:87], v[82:83] offset0:24 offset1:28
	ds_write_b128 v130, v[66:69]
	ds_write_b128 v132, v[70:73]
	ds_write_b128 v134, v[74:77]
	ds_write_b128 v136, v[78:81]
	v_lshl_add_u64 v[82:83], s[6:7], 0, v[16:17]
	v_lshlrev_b32_e32 v84, 1, v84
	v_mov_b32_e32 v85, v17
	v_lshl_add_u64 v[82:83], v[82:83], 0, v[84:85]
	s_movk_i32 s5, 0x2000
	v_add_co_u32_e32 v84, vcc, s5, v82
	s_mov_b32 s5, 0x14000
	s_nop 0
	v_addc_co_u32_e32 v85, vcc, 0, v83, vcc
	global_load_dwordx4 v[94:97], v[84:85], off offset:2048
	v_add_co_u32_e32 v84, vcc, s5, v82
	s_mov_b32 s5, 0x26000
	s_nop 0
	v_addc_co_u32_e32 v85, vcc, 0, v83, vcc
	global_load_dwordx4 v[90:93], v[84:85], off offset:2048
	v_add_co_u32_e32 v84, vcc, s5, v82
	s_mov_b32 s5, 0x38000
	s_nop 0
	v_addc_co_u32_e32 v85, vcc, 0, v83, vcc
	v_add_co_u32_e32 v82, vcc, s5, v82
	global_load_dwordx4 v[86:89], v[84:85], off offset:2048
	s_nop 0
	v_addc_co_u32_e32 v83, vcc, 0, v83, vcc
	global_load_dwordx4 v[82:85], v[82:83], off offset:2048
	s_waitcnt lgkmcnt(0)
	s_barrier
	s_setprio 1
	ds_read_b128 v[206:209], v176
	ds_read_b128 v[212:215], v158
	ds_read_b128 v[216:219], v158 offset:4352
	ds_read_b128 v[220:223], v158 offset:8704
	ds_read_b128 v[236:239], v158 offset:13056
	s_waitcnt lgkmcnt(3)
	v_mfma_f32_16x16x32_bf16 v[134:137], v[212:215], v[206:209], 0
	ds_read_b128 v[212:215], v158 offset:17408
	s_waitcnt lgkmcnt(3)
	v_mfma_f32_16x16x32_bf16 v[138:141], v[216:219], v[206:209], 0
	ds_read_b128 v[216:219], v158 offset:21760
	s_waitcnt lgkmcnt(3)
	v_mfma_f32_16x16x32_bf16 v[142:145], v[220:223], v[206:209], 0
	ds_read_b128 v[220:223], v158 offset:26112
	s_waitcnt lgkmcnt(3)
	v_mfma_f32_16x16x32_bf16 v[146:149], v[236:239], v[206:209], 0
	ds_read_b128 v[236:239], v158 offset:30464
	s_waitcnt lgkmcnt(3)
	v_mfma_f32_16x16x32_bf16 v[150:153], v[212:215], v[206:209], 0
	ds_read_b128 v[212:215], v176 offset:64
	s_waitcnt lgkmcnt(3)
	v_mfma_f32_16x16x32_bf16 v[154:157], v[216:219], v[206:209], 0
	ds_read_b128 v[216:219], v158 offset:64
	s_waitcnt lgkmcnt(3)
	v_mfma_f32_16x16x32_bf16 v[182:185], v[220:223], v[206:209], 0
	ds_read_b128 v[220:223], v158 offset:4416
	s_waitcnt lgkmcnt(3)
	v_mfma_f32_16x16x32_bf16 v[130:133], v[236:239], v[206:209], 0
	ds_read_b128 v[236:239], v158 offset:8768
	ds_read_b128 v[206:209], v158 offset:13120
	s_waitcnt lgkmcnt(3)
	v_mfma_f32_16x16x32_bf16 v[134:137], v[216:219], v[212:215], v[134:137]
	ds_read_b128 v[216:219], v158 offset:17472
	s_waitcnt lgkmcnt(3)
	v_mfma_f32_16x16x32_bf16 v[138:141], v[220:223], v[212:215], v[138:141]
	ds_read_b128 v[220:223], v158 offset:21824
	s_waitcnt lgkmcnt(3)
	v_mfma_f32_16x16x32_bf16 v[142:145], v[236:239], v[212:215], v[142:145]
	ds_read_b128 v[236:239], v158 offset:26176
	s_waitcnt lgkmcnt(3)
	v_mfma_f32_16x16x32_bf16 v[146:149], v[206:209], v[212:215], v[146:149]
	ds_read_b128 v[206:209], v158 offset:30528
	s_waitcnt lgkmcnt(3)
	v_mfma_f32_16x16x32_bf16 v[150:153], v[216:219], v[212:215], v[150:153]
	ds_read_b128 v[216:219], v176 offset:128
	s_waitcnt lgkmcnt(3)
	v_mfma_f32_16x16x32_bf16 v[154:157], v[220:223], v[212:215], v[154:157]
	ds_read_b128 v[220:223], v158 offset:128
	s_waitcnt lgkmcnt(3)
	v_mfma_f32_16x16x32_bf16 v[182:185], v[236:239], v[212:215], v[182:185]
	ds_read_b128 v[236:239], v158 offset:4480
	s_waitcnt lgkmcnt(3)
	v_mfma_f32_16x16x32_bf16 v[130:133], v[206:209], v[212:215], v[130:133]
	ds_read_b128 v[206:209], v158 offset:8832
	ds_read_b128 v[212:215], v158 offset:13184
	s_waitcnt lgkmcnt(3)
	v_mfma_f32_16x16x32_bf16 v[134:137], v[220:223], v[216:219], v[134:137]
	ds_read_b128 v[220:223], v158 offset:17536
	s_waitcnt lgkmcnt(3)
	v_mfma_f32_16x16x32_bf16 v[138:141], v[236:239], v[216:219], v[138:141]
	ds_read_b128 v[236:239], v158 offset:21888
	s_waitcnt lgkmcnt(3)
	v_mfma_f32_16x16x32_bf16 v[142:145], v[206:209], v[216:219], v[142:145]
	ds_read_b128 v[206:209], v158 offset:26240
	s_waitcnt lgkmcnt(3)
	v_mfma_f32_16x16x32_bf16 v[190:193], v[212:215], v[216:219], v[146:149]
	ds_read_b128 v[212:215], v158 offset:30592
	s_waitcnt lgkmcnt(3)
	v_mfma_f32_16x16x32_bf16 v[194:197], v[220:223], v[216:219], v[150:153]
	ds_read_b128 v[220:223], v176 offset:192
	s_waitcnt lgkmcnt(3)
	v_mfma_f32_16x16x32_bf16 v[198:201], v[236:239], v[216:219], v[154:157]
	ds_read_b128 v[236:239], v158 offset:192
	s_waitcnt lgkmcnt(3)
	v_mfma_f32_16x16x32_bf16 v[182:185], v[206:209], v[216:219], v[182:185]
	ds_read_b128 v[206:209], v158 offset:4544
	s_waitcnt lgkmcnt(3)
	v_mfma_f32_16x16x32_bf16 v[186:189], v[212:215], v[216:219], v[130:133]
	ds_read_b128 v[212:215], v158 offset:8896
	ds_read_b128 v[216:219], v158 offset:13248
	s_waitcnt lgkmcnt(3)
	v_mfma_f32_16x16x32_bf16 v[150:153], v[236:239], v[220:223], v[134:137]
	ds_read_b128 v[236:239], v158 offset:17600
	s_waitcnt lgkmcnt(3)
	v_mfma_f32_16x16x32_bf16 v[154:157], v[206:209], v[220:223], v[138:141]
	ds_read_b128 v[206:209], v158 offset:21952
	s_waitcnt lgkmcnt(3)
	v_mfma_f32_16x16x32_bf16 v[146:149], v[212:215], v[220:223], v[142:145]
	ds_read_b128 v[212:215], v158 offset:26304
	s_waitcnt lgkmcnt(3)
	v_mfma_f32_16x16x32_bf16 v[142:145], v[216:219], v[220:223], v[190:193]
	ds_read_b128 v[216:219], v158 offset:30656
	s_waitcnt lgkmcnt(3)
	v_mfma_f32_16x16x32_bf16 v[138:141], v[236:239], v[220:223], v[194:197]
	s_waitcnt lgkmcnt(2)
	v_mfma_f32_16x16x32_bf16 v[134:137], v[206:209], v[220:223], v[198:201]
	s_waitcnt lgkmcnt(1)
	v_mfma_f32_16x16x32_bf16 v[130:133], v[212:215], v[220:223], v[182:185]
	s_waitcnt lgkmcnt(0)
	v_mfma_f32_16x16x32_bf16 v[158:161], v[216:219], v[220:223], v[186:189]
	s_nop 7
	s_setprio 0
	s_add_i32 s1, s1, s95
	s_cmpk_gt_i32 s1, 0x3ff
	s_cselect_b64 s[6:7], -1, 0
	s_and_b64 vcc, exec, s[6:7]
	s_cbranch_vccnz .LBB0_461
; __device__ __forceinline__ void tile_fetch(TileRegs& t, const bf16* src, size_t ld, int tid) {
; #pragma unroll
;     for (int i = 0; i < 4; ++i) { const int ck = tid + 512 * i, r = ck >> 4, ch = ck & 15; t.v[i] = *(const v4u*)(src + (size_t)r * ld + 8 * ch); }
; }
; __device__ __forceinline__ void retout_fetch(RetoutRegs& R, const bf16* proj, const bf16* st, int unit, int tid) {
;     const int h = unit & 7, n = (unit >> 3) & 31, b = unit >> 8;
;     const bf16* base = proj + ((size_t)b * SEQ + (size_t)n * CHUNK) * INW + h * HDIM;
;     tile_fetch(R.q, base + C_RQ, INW, tid); tile_fetch(R.k, base + C_RK, INW, tid); tile_fetch(R.v, base + C_RV, INW, tid);
;     tile_fetch(R.sf, st + ((((size_t)0 * BATCH + b) * NRH + h) * NCH + n) * (size_t)(HDIM * HDIM), HDIM, tid);
;     tile_fetch(R.sb, st + ((((size_t)1 * BATCH + b) * NRH + h) * NCH + n) * (size_t)(HDIM * HDIM), HDIM, tid);
; }
	s_ashr_i32 s12, s1, 8
	s_bfe_u32 s11, s1, 0x50003
	s_ashr_i32 s13, s12, 31
	s_lshl_b64 s[16:17], s[12:13], 12
	s_lshl_b32 s18, s11, 7
	s_or_b32 s16, s18, s16
	s_mulk_i32 s17, 0x4800
	s_mul_hi_u32 s18, s16, 0x4800
	s_and_b32 s5, s1, 7
	s_add_i32 s18, s18, s17
	s_mulk_i32 s16, 0x4800
	s_add_u32 s16, s58, s16
	s_addc_u32 s17, s59, s18
	s_lshl_b32 s18, s5, 8
	s_add_u32 s16, s16, s18
	s_addc_u32 s17, s17, 0
	v_lshl_add_u64 v[34:35], s[16:17], 0, v[16:17]
	s_mov_b64 s[16:17], 0x1000
	v_lshl_add_u64 v[8:9], v[34:35], 0, s[16:17]
	v_lshl_add_u64 v[26:27], v[34:35], 0, s[48:49]
	v_lshl_add_u64 v[42:43], v[34:35], 0, s[30:31]
	v_mad_i64_i32 v[0:1], s[16:17], v162, s85, v[8:9]
	v_mad_i64_i32 v[4:5], s[16:17], v164, s85, v[8:9]
	v_mad_i64_i32 v[10:11], s[16:17], v166, s85, v[8:9]
	v_mad_i64_i32 v[12:13], s[16:17], v168, s85, v[8:9]
	v_mad_i64_i32 v[18:19], s[16:17], v162, s85, v[26:27]
	v_mad_i64_i32 v[22:23], s[16:17], v164, s85, v[26:27]
	v_mad_i64_i32 v[28:29], s[16:17], v166, s85, v[26:27]
	v_mad_i64_i32 v[30:31], s[16:17], v168, s85, v[26:27]
	v_mad_i64_i32 v[34:35], s[16:17], v162, s85, v[42:43]
	v_mad_i64_i32 v[38:39], s[16:17], v164, s85, v[42:43]
	v_mad_i64_i32 v[44:45], s[16:17], v166, s85, v[42:43]
	v_mad_i64_i32 v[46:47], s[16:17], v168, s85, v[42:43]
	s_lshl_b64 s[16:17], s[12:13], 8
	s_lshl_b32 s18, s5, 5
	s_or_b32 s16, s16, s18
	s_or_b32 s16, s16, s11
	s_lshl_b64 s[16:17], s[16:17], 15
	s_add_u32 s16, s62, s16
	s_addc_u32 s17, s63, s17
	s_lshl_b64 s[12:13], s[12:13], 23
	s_lshl_b32 s5, s5, 20
	s_or_b32 s5, s12, s5
	s_add_u32 s5, s62, s5
	s_addc_u32 s13, s63, s13
	s_lshl_b32 s11, s11, 15
	s_add_u32 s12, s5, s11
	s_addc_u32 s13, s13, 0
	v_ashrrev_i32_e32 v163, 31, v162
	v_ashrrev_i32_e32 v165, 31, v164
	v_ashrrev_i32_e32 v167, 31, v166
	v_ashrrev_i32_e32 v169, 31, v168
	v_lshl_add_u64 v[70:71], s[12:13], 0, v[16:17]
	s_mov_b64 s[12:13], 0x2000000
	v_lshl_add_u64 v[58:59], s[16:17], 0, v[16:17]
	v_lshlrev_b64 v[66:67], 8, v[162:163]
	v_lshlrev_b64 v[68:69], 8, v[164:165]
	v_lshlrev_b64 v[74:75], 8, v[166:167]
	v_lshlrev_b64 v[76:77], 8, v[168:169]
	v_lshl_add_u64 v[78:79], v[70:71], 0, s[12:13]
	v_lshl_add_u64 v[50:51], v[58:59], 0, v[66:67]
	v_lshl_add_u64 v[54:55], v[58:59], 0, v[68:69]
	v_lshl_add_u64 v[60:61], v[58:59], 0, v[74:75]
	v_lshl_add_u64 v[62:63], v[58:59], 0, v[76:77]
	v_lshl_add_u64 v[66:67], v[78:79], 0, v[66:67]
	v_lshl_add_u64 v[70:71], v[78:79], 0, v[68:69]
	v_lshl_add_u64 v[74:75], v[78:79], 0, v[74:75]
	v_lshl_add_u64 v[78:79], v[78:79], 0, v[76:77]
	global_load_dwordx4 v[0:3], v[0:1], off
	s_nop 0
	global_load_dwordx4 v[4:7], v[4:5], off
	s_nop 0
	global_load_dwordx4 v[8:11], v[10:11], off
	s_nop 0
	global_load_dwordx4 v[12:15], v[12:13], off
	s_nop 0
	global_load_dwordx4 v[18:21], v[18:19], off
	s_nop 0
	global_load_dwordx4 v[22:25], v[22:23], off
	s_nop 0
	global_load_dwordx4 v[26:29], v[28:29], off
	s_nop 0
	global_load_dwordx4 v[30:33], v[30:31], off
	s_nop 0
	global_load_dwordx4 v[34:37], v[34:35], off
	s_nop 0
	global_load_dwordx4 v[38:41], v[38:39], off
	s_nop 0
	global_load_dwordx4 v[42:45], v[44:45], off
	s_nop 0
	global_load_dwordx4 v[46:49], v[46:47], off
	s_nop 0
	global_load_dwordx4 v[50:53], v[50:51], off
	s_nop 0
	global_load_dwordx4 v[54:57], v[54:55], off
	s_nop 0
	global_load_dwordx4 v[58:61], v[60:61], off
	s_nop 0
	global_load_dwordx4 v[62:65], v[62:63], off
	s_nop 0
	global_load_dwordx4 v[66:69], v[66:67], off
	s_nop 0
	global_load_dwordx4 v[70:73], v[70:71], off
	s_nop 0
	global_load_dwordx4 v[74:77], v[74:75], off
	s_nop 0
	global_load_dwordx4 v[78:81], v[78:79], off
	s_branch .LBB0_461
